# removed the 28 redundant back-to-back s_setprio 0 / s_setprio 1 pairs in the middle of the 32-MFMA blocks (on top of v29)
# baseline (speedup 1.0000x reference)
; #define PG8_STAGE(bufoff, gbase, voff) do { _Pragma("unroll") for (int _i = 0; _i < 2; ++_i) \
;         __builtin_amdgcn_global_load_lds((const unsigned*)((const char*)(gbase) + (voff)[_i]), (LAS unsigned*)(lds + (bufoff) + ldsw + _i * 8192), 16, 0, 0); } while (0)
; #define PG8_LDA(dst, b, h) do { _Pragma("unroll") for (int m = 0; m < 4; ++m) _Pragma("unroll") for (int k = 0; k < 2; ++k) dst[m][k] = *(const LAS bf16x8*)(lds + PG8_SA(b, h) + aoff + m * 2048 + k * 1024); } while (0)
; #define PG8_LDB(dst, b, h) do { _Pragma("unroll") for (int n = 0; n < 2; ++n) _Pragma("unroll") for (int k = 0; k < 2; ++k) dst[n][k] = *(const LAS bf16x8*)(lds + PG8_SB(b, h) + boff + n * 2048 + k * 1024); } while (0)
; #define PG8_MMA(ai, bj, At, Bt) do { __builtin_amdgcn_s_setprio(1); _Pragma("unroll") for (int m = 0; m < 4; ++m) _Pragma("unroll") for (int n = 0; n < 2; ++n) _Pragma("unroll") for (int k = 0; k < 2; ++k) \
;         acc[ai][bj][m][n] = __builtin_amdgcn_mfma_f32_16x16x32_bf16(Bt[n][k], At[m][k], acc[ai][bj][m][n], 0, 0, 0); __builtin_amdgcn_s_setprio(0); } while (0)
; #define PG8_WAIT_V(n) asm volatile("s_waitcnt vmcnt(" #n ")" ::: "memory")
; #define PG8_WAIT_L(n) asm volatile("s_waitcnt lgkmcnt(" #n ")" ::: "memory")
; #define PG8_BAR __builtin_amdgcn_s_barrier()
; #define PG8_SCHED __builtin_amdgcn_sched_barrier(0)
; template <class Epi, class Sched>
; __device__ __forceinline__ void gemm_phase(LAS unsigned char* lds, const Gemm g, const Sched& S, const Epi& E) {
;     ...
;             const bool last = (t == nt - 2);
;             const char* a1 = cA + (size_t)(t + 1) * kstep;
;             const char* a2 = last ? nA : cA + (size_t)(t + 2) * kstep; const char* b2 = last ? nB : cB + (size_t)(t + 2) * kstep;
;             const char* a3 = a2 + kstep; const char* b3 = b2 + kstep;
;             PG8_LDB(B0, 0, 0); PG8_LDB(B1, 0, 1); PG8_SCHED; PG8_LDA(At, 0, 0); PG8_STAGE(PG8_SA(1, 1), a1 + hstepA, voffA);
;             PG8_WAIT_V(8); PG8_WAIT_L(0); PG8_BAR; PG8_MMA(0, 0, At, B0); PG8_MMA(0, 1, At, B1); PG8_BAR; PG8_SCHED;
;             PG8_LDA(At, 0, 1); PG8_STAGE(PG8_SB(0, 0), b2, voffB); PG8_STAGE(PG8_SB(0, 1), b2 + hstepB, voffB); PG8_STAGE(PG8_SA(0, 0), a2, voffA);
.LBB0_122:
	ds_read_b128 v[128:131], v209
	ds_read_b128 v[132:135], v209 offset:1024
	ds_read_b128 v[136:139], v209 offset:2048
	ds_read_b128 v[140:143], v209 offset:3072
	ds_read_b128 v[144:147], v210
	ds_read_b128 v[148:151], v210 offset:1024
	ds_read_b128 v[152:155], v210 offset:2048
	ds_read_b128 v[156:159], v210 offset:3072
	s_add_u32 s4, s0, 0xfff80080
	s_addc_u32 s5, s1, -1
	s_cmp_eq_u32 s87, 28
	s_cselect_b32 s7, s8, s5
	s_cselect_b32 s6, s9, s4
	s_cselect_b32 s5, s10, s35
	s_cselect_b32 s4, s11, s34
	v_lshl_add_u64 v[216:217], s[0:1], 0, v[178:179]
	s_add_i32 m0, s15, 0xc000
	ds_read_b128 v[160:163], v211
	ds_read_b128 v[164:167], v211 offset:1024
	ds_read_b128 v[182:185], v211 offset:2048
	ds_read_b128 v[186:189], v211 offset:3072
	ds_read_b128 v[190:193], v211 offset:4096
	ds_read_b128 v[194:197], v211 offset:5120
	ds_read_b128 v[198:201], v211 offset:6144
	ds_read_b128 v[202:205], v211 offset:7168
	global_load_lds_dwordx4 v[216:217], off
	v_lshl_add_u64 v[216:217], s[0:1], 0, v[180:181]
	s_add_i32 m0, s15, 0xe000
	s_nop 0
	global_load_lds_dwordx4 v[216:217], off
	s_waitcnt vmcnt(8) lgkmcnt(0)
	s_barrier
	s_setprio 1
	v_mfma_f32_16x16x32_bf16 v[124:127], v[128:131], v[160:163], v[124:127]
	v_mfma_f32_16x16x32_bf16 v[120:123], v[136:139], v[160:163], v[120:123]
	v_mfma_f32_16x16x32_bf16 v[116:119], v[128:131], v[182:185], v[116:119]
	v_mfma_f32_16x16x32_bf16 v[112:115], v[136:139], v[182:185], v[112:115]
	v_mfma_f32_16x16x32_bf16 v[108:111], v[128:131], v[190:193], v[108:111]
	v_mfma_f32_16x16x32_bf16 v[104:107], v[136:139], v[190:193], v[104:107]
	v_mfma_f32_16x16x32_bf16 v[96:99], v[128:131], v[198:201], v[96:99]
	v_mfma_f32_16x16x32_bf16 v[100:103], v[136:139], v[198:201], v[100:103]
	v_mfma_f32_16x16x32_bf16 v[124:127], v[132:135], v[164:167], v[124:127]
	v_mfma_f32_16x16x32_bf16 v[120:123], v[140:143], v[164:167], v[120:123]
	v_mfma_f32_16x16x32_bf16 v[116:119], v[132:135], v[186:189], v[116:119]
	v_mfma_f32_16x16x32_bf16 v[112:115], v[140:143], v[186:189], v[112:115]
	v_mfma_f32_16x16x32_bf16 v[108:111], v[132:135], v[194:197], v[108:111]
	v_mfma_f32_16x16x32_bf16 v[104:107], v[140:143], v[194:197], v[104:107]
	v_mfma_f32_16x16x32_bf16 v[96:99], v[132:135], v[202:205], v[96:99]
	v_mfma_f32_16x16x32_bf16 v[100:103], v[140:143], v[202:205], v[100:103]
	v_mfma_f32_16x16x32_bf16 v[60:63], v[144:147], v[160:163], v[60:63]
	v_mfma_f32_16x16x32_bf16 v[56:59], v[152:155], v[160:163], v[56:59]
	v_mfma_f32_16x16x32_bf16 v[52:55], v[144:147], v[182:185], v[52:55]
	v_mfma_f32_16x16x32_bf16 v[48:51], v[152:155], v[182:185], v[48:51]
	v_mfma_f32_16x16x32_bf16 v[44:47], v[144:147], v[190:193], v[44:47]
	v_mfma_f32_16x16x32_bf16 v[40:43], v[152:155], v[190:193], v[40:43]
	v_mfma_f32_16x16x32_bf16 v[32:35], v[144:147], v[198:201], v[32:35]
	v_mfma_f32_16x16x32_bf16 v[36:39], v[152:155], v[198:201], v[36:39]
	v_mfma_f32_16x16x32_bf16 v[60:63], v[148:151], v[164:167], v[60:63]
	v_mfma_f32_16x16x32_bf16 v[56:59], v[156:159], v[164:167], v[56:59]
	v_mfma_f32_16x16x32_bf16 v[52:55], v[148:151], v[186:189], v[52:55]
	v_mfma_f32_16x16x32_bf16 v[48:51], v[156:159], v[186:189], v[48:51]
	v_mfma_f32_16x16x32_bf16 v[44:47], v[148:151], v[194:197], v[44:47]
	v_mfma_f32_16x16x32_bf16 v[40:43], v[156:159], v[194:197], v[40:43]
	v_mfma_f32_16x16x32_bf16 v[32:35], v[148:151], v[202:205], v[32:35]
	v_mfma_f32_16x16x32_bf16 v[36:39], v[156:159], v[202:205], v[36:39]
	s_setprio 0
	s_barrier
	s_add_i32 s26, s33, s14
	v_lshl_add_u64 v[216:217], s[4:5], 0, v[170:171]
	s_mov_b32 m0, s26
	ds_read_b128 v[160:163], v211 offset:16384
	ds_read_b128 v[164:167], v211 offset:17408
	ds_read_b128 v[182:185], v211 offset:18432
	ds_read_b128 v[186:189], v211 offset:19456
	ds_read_b128 v[190:193], v211 offset:20480
	ds_read_b128 v[194:197], v211 offset:21504
	ds_read_b128 v[198:201], v211 offset:22528
	ds_read_b128 v[202:205], v211 offset:23552
	global_load_lds_dwordx4 v[216:217], off
	s_add_i32 m0, s26, 0x2000
	s_add_u32 s96, s4, 0x80000
	v_lshl_add_u64 v[218:219], s[4:5], 0, v[174:175]
	s_addc_u32 s97, s5, 0
	s_add_i32 s26, s36, s14
	global_load_lds_dwordx4 v[218:219], off
	v_lshl_add_u64 v[220:221], s[96:97], 0, v[170:171]
	s_mov_b32 m0, s26
	v_lshl_add_u64 v[222:223], s[6:7], 0, v[172:173]
	global_load_lds_dwordx4 v[220:221], off
	v_lshl_add_u64 v[220:221], s[96:97], 0, v[174:175]
	s_add_i32 m0, s26, 0x2000
	s_nop 0
	global_load_lds_dwordx4 v[220:221], off
	v_lshl_add_u64 v[220:221], s[6:7], 0, v[168:169]
	s_mov_b32 m0, s15
	s_nop 0
	global_load_lds_dwordx4 v[220:221], off
	s_mov_b32 m0, s28
	s_nop 0
	global_load_lds_dwordx4 v[222:223], off
	s_waitcnt vmcnt(8) lgkmcnt(0)
	s_barrier
; #define PG8_STAGE(bufoff, gbase, voff) do { _Pragma("unroll") for (int _i = 0; _i < 2; ++_i) \
;         __builtin_amdgcn_global_load_lds((const unsigned*)((const char*)(gbase) + (voff)[_i]), (LAS unsigned*)(lds + (bufoff) + ldsw + _i * 8192), 16, 0, 0); } while (0)
; #define PG8_LDA(dst, b, h) do { _Pragma("unroll") for (int m = 0; m < 4; ++m) _Pragma("unroll") for (int k = 0; k < 2; ++k) dst[m][k] = *(const LAS bf16x8*)(lds + PG8_SA(b, h) + aoff + m * 2048 + k * 1024); } while (0)
; #define PG8_LDB(dst, b, h) do { _Pragma("unroll") for (int n = 0; n < 2; ++n) _Pragma("unroll") for (int k = 0; k < 2; ++k) dst[n][k] = *(const LAS bf16x8*)(lds + PG8_SB(b, h) + boff + n * 2048 + k * 1024); } while (0)
; #define PG8_MMA(ai, bj, At, Bt) do { __builtin_amdgcn_s_setprio(1); _Pragma("unroll") for (int m = 0; m < 4; ++m) _Pragma("unroll") for (int n = 0; n < 2; ++n) _Pragma("unroll") for (int k = 0; k < 2; ++k) \
;         acc[ai][bj][m][n] = __builtin_amdgcn_mfma_f32_16x16x32_bf16(Bt[n][k], At[m][k], acc[ai][bj][m][n], 0, 0, 0); __builtin_amdgcn_s_setprio(0); } while (0)
; #define PG8_WAIT_V(n) asm volatile("s_waitcnt vmcnt(" #n ")" ::: "memory")
; #define PG8_WAIT_L(n) asm volatile("s_waitcnt lgkmcnt(" #n ")" ::: "memory")
; #define PG8_BAR __builtin_amdgcn_s_barrier()
; #define PG8_SCHED __builtin_amdgcn_sched_barrier(0)
; template <class Epi, class Sched>
; __device__ __forceinline__ void gemm_phase(LAS unsigned char* lds, const Gemm g, const Sched& S, const Epi& E) {
;     ...
;             PG8_WAIT_V(8); PG8_WAIT_L(0); PG8_BAR; PG8_MMA(1, 0, At, B0); PG8_MMA(1, 1, At, B1); PG8_BAR; PG8_SCHED;
;             PG8_LDB(B0, 1, 0); PG8_LDB(B1, 1, 1); PG8_SCHED; PG8_LDA(At, 1, 0); PG8_STAGE(PG8_SA(0, 1), a2 + hstepA, voffA);
;             PG8_WAIT_V(8); PG8_WAIT_L(0); PG8_BAR; PG8_MMA(0, 0, At, B0); PG8_MMA(0, 1, At, B1); PG8_BAR; PG8_SCHED;
	s_setprio 1
	v_mfma_f32_16x16x32_bf16 v[92:95], v[128:131], v[160:163], v[92:95]
	v_mfma_f32_16x16x32_bf16 v[88:91], v[136:139], v[160:163], v[88:91]
	v_mfma_f32_16x16x32_bf16 v[84:87], v[128:131], v[182:185], v[84:87]
	v_mfma_f32_16x16x32_bf16 v[80:83], v[136:139], v[182:185], v[80:83]
	v_mfma_f32_16x16x32_bf16 v[76:79], v[128:131], v[190:193], v[76:79]
	v_mfma_f32_16x16x32_bf16 v[72:75], v[136:139], v[190:193], v[72:75]
	v_mfma_f32_16x16x32_bf16 v[64:67], v[128:131], v[198:201], v[64:67]
	v_mfma_f32_16x16x32_bf16 v[68:71], v[136:139], v[198:201], v[68:71]
	v_mfma_f32_16x16x32_bf16 v[92:95], v[132:135], v[164:167], v[92:95]
	v_mfma_f32_16x16x32_bf16 v[88:91], v[140:143], v[164:167], v[88:91]
	v_mfma_f32_16x16x32_bf16 v[84:87], v[132:135], v[186:189], v[84:87]
	v_mfma_f32_16x16x32_bf16 v[80:83], v[140:143], v[186:189], v[80:83]
	v_mfma_f32_16x16x32_bf16 v[76:79], v[132:135], v[194:197], v[76:79]
	v_mfma_f32_16x16x32_bf16 v[72:75], v[140:143], v[194:197], v[72:75]
	v_mfma_f32_16x16x32_bf16 v[64:67], v[132:135], v[202:205], v[64:67]
	v_mfma_f32_16x16x32_bf16 v[68:71], v[140:143], v[202:205], v[68:71]
	v_mfma_f32_16x16x32_bf16 v[28:31], v[144:147], v[160:163], v[28:31]
	v_mfma_f32_16x16x32_bf16 v[24:27], v[152:155], v[160:163], v[24:27]
	v_mfma_f32_16x16x32_bf16 v[20:23], v[144:147], v[182:185], v[20:23]
	v_mfma_f32_16x16x32_bf16 v[16:19], v[152:155], v[182:185], v[16:19]
	v_mfma_f32_16x16x32_bf16 v[12:15], v[144:147], v[190:193], v[12:15]
	v_mfma_f32_16x16x32_bf16 v[8:11], v[152:155], v[190:193], v[8:11]
	v_mfma_f32_16x16x32_bf16 v[0:3], v[144:147], v[198:201], v[0:3]
	v_mfma_f32_16x16x32_bf16 v[4:7], v[152:155], v[198:201], v[4:7]
	v_mfma_f32_16x16x32_bf16 v[28:31], v[148:151], v[164:167], v[28:31]
	v_mfma_f32_16x16x32_bf16 v[24:27], v[156:159], v[164:167], v[24:27]
	v_mfma_f32_16x16x32_bf16 v[20:23], v[148:151], v[186:189], v[20:23]
	v_mfma_f32_16x16x32_bf16 v[16:19], v[156:159], v[186:189], v[16:19]
	v_mfma_f32_16x16x32_bf16 v[12:15], v[148:151], v[194:197], v[12:15]
	v_mfma_f32_16x16x32_bf16 v[8:11], v[156:159], v[194:197], v[8:11]
	v_mfma_f32_16x16x32_bf16 v[0:3], v[148:151], v[202:205], v[0:3]
	v_mfma_f32_16x16x32_bf16 v[4:7], v[156:159], v[202:205], v[4:7]
	s_setprio 0
	s_barrier
	s_add_i32 s37, 0, 0x18000
	s_add_i32 s26, 0, 0x1c000
	v_add_u32_e32 v140, s37, v208
	v_add_u32_e32 v156, s26, v208
	ds_read_b128 v[128:131], v140
	ds_read_b128 v[132:135], v140 offset:1024
	ds_read_b128 v[136:139], v140 offset:2048
	ds_read_b128 v[140:143], v140 offset:3072
	ds_read_b128 v[144:147], v156
	ds_read_b128 v[148:151], v156 offset:1024
	ds_read_b128 v[152:155], v156 offset:2048
	ds_read_b128 v[156:159], v156 offset:3072
	s_add_u32 s6, s6, 0x80000
	s_addc_u32 s7, s7, 0
	s_mov_b32 m0, s29
	v_lshl_add_u64 v[224:225], s[6:7], 0, v[168:169]
	ds_read_b128 v[160:163], v211 offset:32768
	ds_read_b128 v[164:167], v211 offset:33792
	ds_read_b128 v[182:185], v211 offset:34816
	ds_read_b128 v[186:189], v211 offset:35840
	ds_read_b128 v[190:193], v211 offset:36864
	ds_read_b128 v[194:197], v211 offset:37888
	ds_read_b128 v[198:201], v211 offset:38912
	ds_read_b128 v[202:205], v211 offset:39936
	global_load_lds_dwordx4 v[224:225], off
	v_lshl_add_u64 v[224:225], s[6:7], 0, v[172:173]
	s_mov_b32 m0, s30
	s_nop 0
	global_load_lds_dwordx4 v[224:225], off
	s_waitcnt vmcnt(8) lgkmcnt(0)
	s_barrier
	s_setprio 1
	v_mfma_f32_16x16x32_bf16 v[124:127], v[128:131], v[160:163], v[124:127]
	v_mfma_f32_16x16x32_bf16 v[120:123], v[136:139], v[160:163], v[120:123]
	v_mfma_f32_16x16x32_bf16 v[116:119], v[128:131], v[182:185], v[116:119]
	v_mfma_f32_16x16x32_bf16 v[112:115], v[136:139], v[182:185], v[112:115]
	v_mfma_f32_16x16x32_bf16 v[108:111], v[128:131], v[190:193], v[108:111]
	v_mfma_f32_16x16x32_bf16 v[104:107], v[136:139], v[190:193], v[104:107]
	v_mfma_f32_16x16x32_bf16 v[96:99], v[128:131], v[198:201], v[96:99]
	v_mfma_f32_16x16x32_bf16 v[100:103], v[136:139], v[198:201], v[100:103]
	v_mfma_f32_16x16x32_bf16 v[124:127], v[132:135], v[164:167], v[124:127]
	v_mfma_f32_16x16x32_bf16 v[120:123], v[140:143], v[164:167], v[120:123]
	v_mfma_f32_16x16x32_bf16 v[116:119], v[132:135], v[186:189], v[116:119]
	v_mfma_f32_16x16x32_bf16 v[112:115], v[140:143], v[186:189], v[112:115]
	v_mfma_f32_16x16x32_bf16 v[108:111], v[132:135], v[194:197], v[108:111]
	v_mfma_f32_16x16x32_bf16 v[104:107], v[140:143], v[194:197], v[104:107]
	v_mfma_f32_16x16x32_bf16 v[96:99], v[132:135], v[202:205], v[96:99]
	v_mfma_f32_16x16x32_bf16 v[100:103], v[140:143], v[202:205], v[100:103]
	v_mfma_f32_16x16x32_bf16 v[60:63], v[144:147], v[160:163], v[60:63]
	v_mfma_f32_16x16x32_bf16 v[56:59], v[152:155], v[160:163], v[56:59]
	v_mfma_f32_16x16x32_bf16 v[52:55], v[144:147], v[182:185], v[52:55]
	v_mfma_f32_16x16x32_bf16 v[48:51], v[152:155], v[182:185], v[48:51]
	v_mfma_f32_16x16x32_bf16 v[44:47], v[144:147], v[190:193], v[44:47]
	v_mfma_f32_16x16x32_bf16 v[40:43], v[152:155], v[190:193], v[40:43]
	v_mfma_f32_16x16x32_bf16 v[32:35], v[144:147], v[198:201], v[32:35]
	v_mfma_f32_16x16x32_bf16 v[36:39], v[152:155], v[198:201], v[36:39]
	v_mfma_f32_16x16x32_bf16 v[60:63], v[148:151], v[164:167], v[60:63]
	v_mfma_f32_16x16x32_bf16 v[56:59], v[156:159], v[164:167], v[56:59]
	v_mfma_f32_16x16x32_bf16 v[52:55], v[148:151], v[186:189], v[52:55]
	v_mfma_f32_16x16x32_bf16 v[48:51], v[156:159], v[186:189], v[48:51]
	v_mfma_f32_16x16x32_bf16 v[44:47], v[148:151], v[194:197], v[44:47]
	v_mfma_f32_16x16x32_bf16 v[40:43], v[156:159], v[194:197], v[40:43]
	v_mfma_f32_16x16x32_bf16 v[32:35], v[148:151], v[202:205], v[32:35]
	v_mfma_f32_16x16x32_bf16 v[36:39], v[156:159], v[202:205], v[36:39]
	s_setprio 0
	s_barrier
; #define PG8_STAGE(bufoff, gbase, voff) do { _Pragma("unroll") for (int _i = 0; _i < 2; ++_i) \
;         __builtin_amdgcn_global_load_lds((const unsigned*)((const char*)(gbase) + (voff)[_i]), (LAS unsigned*)(lds + (bufoff) + ldsw + _i * 8192), 16, 0, 0); } while (0)
; #define PG8_LDA(dst, b, h) do { _Pragma("unroll") for (int m = 0; m < 4; ++m) _Pragma("unroll") for (int k = 0; k < 2; ++k) dst[m][k] = *(const LAS bf16x8*)(lds + PG8_SA(b, h) + aoff + m * 2048 + k * 1024); } while (0)
; #define PG8_MMA(ai, bj, At, Bt) do { __builtin_amdgcn_s_setprio(1); _Pragma("unroll") for (int m = 0; m < 4; ++m) _Pragma("unroll") for (int n = 0; n < 2; ++n) _Pragma("unroll") for (int k = 0; k < 2; ++k) \
;         acc[ai][bj][m][n] = __builtin_amdgcn_mfma_f32_16x16x32_bf16(Bt[n][k], At[m][k], acc[ai][bj][m][n], 0, 0, 0); __builtin_amdgcn_s_setprio(0); } while (0)
; #define PG8_WAIT_V(n) asm volatile("s_waitcnt vmcnt(" #n ")" ::: "memory")
; #define PG8_WAIT_L(n) asm volatile("s_waitcnt lgkmcnt(" #n ")" ::: "memory")
; #define PG8_BAR __builtin_amdgcn_s_barrier()
; #define PG8_SCHED __builtin_amdgcn_sched_barrier(0)
; template <class Epi, class Sched>
; __device__ __forceinline__ void gemm_phase(LAS unsigned char* lds, const Gemm g, const Sched& S, const Epi& E) {
;     ...
;             PG8_LDA(At, 1, 1); PG8_STAGE(PG8_SB(1, 0), b3, voffB); PG8_STAGE(PG8_SB(1, 1), b3 + hstepB, voffB); PG8_STAGE(PG8_SA(1, 0), a3, voffA);
;             PG8_WAIT_V(8); PG8_WAIT_L(0); PG8_BAR; PG8_MMA(1, 0, At, B0); PG8_MMA(1, 1, At, B1); PG8_BAR; PG8_SCHED;
;         }
;         if (wr == 0) PG8_BAR;
	s_add_i32 s6, s37, s14
	v_lshl_add_u64 v[216:217], v[216:217], 0, s[80:81]
	s_mov_b32 m0, s6
	ds_read_b128 v[160:163], v211 offset:49152
	ds_read_b128 v[164:167], v211 offset:50176
	ds_read_b128 v[182:185], v211 offset:51200
	ds_read_b128 v[186:189], v211 offset:52224
	ds_read_b128 v[190:193], v211 offset:53248
	ds_read_b128 v[194:197], v211 offset:54272
	ds_read_b128 v[198:201], v211 offset:55296
	ds_read_b128 v[202:205], v211 offset:56320
	global_load_lds_dwordx4 v[216:217], off
	s_add_i32 m0, s6, 0x2000
	s_add_u32 s4, s4, 0x80080
	v_lshl_add_u64 v[216:217], v[218:219], 0, s[80:81]
	s_addc_u32 s5, s5, 0
	s_add_i32 s6, s26, s14
	global_load_lds_dwordx4 v[216:217], off
	v_lshl_add_u64 v[216:217], s[4:5], 0, v[170:171]
	s_mov_b32 m0, s6
	s_nop 0
	global_load_lds_dwordx4 v[216:217], off
	v_lshl_add_u64 v[216:217], s[4:5], 0, v[174:175]
	s_add_i32 m0, s6, 0x2000
	s_nop 0
	global_load_lds_dwordx4 v[216:217], off
	v_lshl_add_u64 v[216:217], v[220:221], 0, s[80:81]
	s_mov_b32 m0, s21
	s_nop 0
	global_load_lds_dwordx4 v[216:217], off
	v_lshl_add_u64 v[216:217], v[222:223], 0, s[80:81]
	s_mov_b32 m0, s18
	s_nop 0
	global_load_lds_dwordx4 v[216:217], off
	s_waitcnt vmcnt(8) lgkmcnt(0)
	s_barrier
	s_setprio 1
	v_mfma_f32_16x16x32_bf16 v[92:95], v[128:131], v[160:163], v[92:95]
	v_mfma_f32_16x16x32_bf16 v[88:91], v[136:139], v[160:163], v[88:91]
	v_mfma_f32_16x16x32_bf16 v[84:87], v[128:131], v[182:185], v[84:87]
	v_mfma_f32_16x16x32_bf16 v[80:83], v[136:139], v[182:185], v[80:83]
	v_mfma_f32_16x16x32_bf16 v[76:79], v[128:131], v[190:193], v[76:79]
	v_mfma_f32_16x16x32_bf16 v[72:75], v[136:139], v[190:193], v[72:75]
	v_mfma_f32_16x16x32_bf16 v[64:67], v[128:131], v[198:201], v[64:67]
	v_mfma_f32_16x16x32_bf16 v[68:71], v[136:139], v[198:201], v[68:71]
	v_mfma_f32_16x16x32_bf16 v[92:95], v[132:135], v[164:167], v[92:95]
	v_mfma_f32_16x16x32_bf16 v[88:91], v[140:143], v[164:167], v[88:91]
	v_mfma_f32_16x16x32_bf16 v[84:87], v[132:135], v[186:189], v[84:87]
	v_mfma_f32_16x16x32_bf16 v[80:83], v[140:143], v[186:189], v[80:83]
	v_mfma_f32_16x16x32_bf16 v[76:79], v[132:135], v[194:197], v[76:79]
	v_mfma_f32_16x16x32_bf16 v[72:75], v[140:143], v[194:197], v[72:75]
	v_mfma_f32_16x16x32_bf16 v[64:67], v[132:135], v[202:205], v[64:67]
	v_mfma_f32_16x16x32_bf16 v[68:71], v[140:143], v[202:205], v[68:71]
	v_mfma_f32_16x16x32_bf16 v[28:31], v[144:147], v[160:163], v[28:31]
	v_mfma_f32_16x16x32_bf16 v[24:27], v[152:155], v[160:163], v[24:27]
	v_mfma_f32_16x16x32_bf16 v[20:23], v[144:147], v[182:185], v[20:23]
	v_mfma_f32_16x16x32_bf16 v[16:19], v[152:155], v[182:185], v[16:19]
	v_mfma_f32_16x16x32_bf16 v[12:15], v[144:147], v[190:193], v[12:15]
	v_mfma_f32_16x16x32_bf16 v[8:11], v[152:155], v[190:193], v[8:11]
	v_mfma_f32_16x16x32_bf16 v[0:3], v[144:147], v[198:201], v[0:3]
	v_mfma_f32_16x16x32_bf16 v[4:7], v[152:155], v[198:201], v[4:7]
	v_mfma_f32_16x16x32_bf16 v[28:31], v[148:151], v[164:167], v[28:31]
	v_mfma_f32_16x16x32_bf16 v[24:27], v[156:159], v[164:167], v[24:27]
	v_mfma_f32_16x16x32_bf16 v[20:23], v[148:151], v[186:189], v[20:23]
	v_mfma_f32_16x16x32_bf16 v[16:19], v[156:159], v[186:189], v[16:19]
	v_mfma_f32_16x16x32_bf16 v[12:15], v[148:151], v[194:197], v[12:15]
	v_mfma_f32_16x16x32_bf16 v[8:11], v[156:159], v[194:197], v[8:11]
	v_mfma_f32_16x16x32_bf16 v[0:3], v[148:151], v[202:205], v[0:3]
	v_mfma_f32_16x16x32_bf16 v[4:7], v[156:159], v[202:205], v[4:7]
	s_setprio 0
	s_barrier
	s_add_i32 s87, s87, 2
	s_add_u32 s0, s0, 0x100
	s_addc_u32 s1, s1, 0
	s_add_u32 s34, s34, 0x100
	s_addc_u32 s35, s35, 0
	s_cmp_gt_u32 s87, 29
	s_cbranch_scc0 .LBB0_122
	s_and_b64 vcc, exec, s[82:83]
	s_cbranch_vccz .LBB0_125
	s_barrier

; #define PG8_STAGE(bufoff, gbase, voff) do { _Pragma("unroll") for (int _i = 0; _i < 2; ++_i) \
;         __builtin_amdgcn_global_load_lds((const unsigned*)((const char*)(gbase) + (voff)[_i]), (LAS unsigned*)(lds + (bufoff) + ldsw + _i * 8192), 16, 0, 0); } while (0)
; #define PG8_LDA(dst, b, h) do { _Pragma("unroll") for (int m = 0; m < 4; ++m) _Pragma("unroll") for (int k = 0; k < 2; ++k) dst[m][k] = *(const LAS bf16x8*)(lds + PG8_SA(b, h) + aoff + m * 2048 + k * 1024); } while (0)
; #define PG8_LDB(dst, b, h) do { _Pragma("unroll") for (int n = 0; n < 2; ++n) _Pragma("unroll") for (int k = 0; k < 2; ++k) dst[n][k] = *(const LAS bf16x8*)(lds + PG8_SB(b, h) + boff + n * 2048 + k * 1024); } while (0)
; #define PG8_MMA(ai, bj, At, Bt) do { __builtin_amdgcn_s_setprio(1); _Pragma("unroll") for (int m = 0; m < 4; ++m) _Pragma("unroll") for (int n = 0; n < 2; ++n) _Pragma("unroll") for (int k = 0; k < 2; ++k) \
;         acc[ai][bj][m][n] = __builtin_amdgcn_mfma_f32_16x16x32_bf16(Bt[n][k], At[m][k], acc[ai][bj][m][n], 0, 0, 0); __builtin_amdgcn_s_setprio(0); } while (0)
; #define PG8_WAIT_V(n) asm volatile("s_waitcnt vmcnt(" #n ")" ::: "memory")
; #define PG8_WAIT_L(n) asm volatile("s_waitcnt lgkmcnt(" #n ")" ::: "memory")
; #define PG8_BAR __builtin_amdgcn_s_barrier()
; #define PG8_SCHED __builtin_amdgcn_sched_barrier(0)
; template <class Epi, class Sched>
; __device__ __forceinline__ void gemm_phase(LAS unsigned char* lds, const Gemm g, const Sched& S, const Epi& E) {
;     ...
;             const bool last = (t == nt - 2);
;             const char* a1 = cA + (size_t)(t + 1) * kstep;
;             const char* a2 = last ? nA : cA + (size_t)(t + 2) * kstep; const char* b2 = last ? nB : cB + (size_t)(t + 2) * kstep;
;             const char* a3 = a2 + kstep; const char* b3 = b2 + kstep;
;             PG8_LDB(B0, 0, 0); PG8_LDB(B1, 0, 1); PG8_SCHED; PG8_LDA(At, 0, 0); PG8_STAGE(PG8_SA(1, 1), a1 + hstepA, voffA);
;             PG8_WAIT_V(8); PG8_WAIT_L(0); PG8_BAR; PG8_MMA(0, 0, At, B0); PG8_MMA(0, 1, At, B1); PG8_BAR; PG8_SCHED;
;             PG8_LDA(At, 0, 1); PG8_STAGE(PG8_SB(0, 0), b2, voffB); PG8_STAGE(PG8_SB(0, 1), b2 + hstepB, voffB); PG8_STAGE(PG8_SA(0, 0), a2, voffA);
.LBB0_531:
	s_add_u32 s61, s76, s82
	s_addc_u32 s73, s77, s83
	s_add_u32 s86, s61, 0x100
	s_addc_u32 s87, s73, 0
	s_and_b64 s[84:85], s[80:81], exec
	s_cselect_b32 s85, s12, s87
	s_cselect_b32 s84, s13, s86
	s_add_u32 s82, s74, s82
	s_addc_u32 s83, s75, s83
	s_add_u32 s82, s82, 0x100
	s_addc_u32 s83, s83, 0
	s_and_b64 s[80:81], s[80:81], exec
	s_cselect_b32 s87, s49, s83
	s_cselect_b32 s86, s59, s82
	s_add_u32 s90, s61, 0x40080
	ds_read_b128 v[128:131], v163
	ds_read_b128 v[132:135], v163 offset:1024
	ds_read_b128 v[136:139], v163 offset:2048
	ds_read_b128 v[140:143], v163 offset:3072
	ds_read_b128 v[156:159], v164
	ds_read_b128 v[166:169], v164 offset:1024
	ds_read_b128 v[170:173], v164 offset:2048
	ds_read_b128 v[174:177], v164 offset:3072
	s_addc_u32 s91, s73, 0
	s_add_i32 s97, s33, s14
	s_add_i32 m0, s15, 0xc000
	s_add_i32 vcc_lo, s15, 0xe000
	s_add_i32 s94, s97, 0x2000
	s_add_u32 s88, s86, 0x10000
	s_addc_u32 s89, s87, 0
	s_add_i32 s96, s36, s14
	s_add_i32 s95, s96, 0x2000
	s_add_u32 s82, s84, 0x40000
	s_addc_u32 s83, s85, 0
	s_add_i32 s93, s37, s14
	s_add_i32 s73, s93, 0x2000
	s_add_u32 s80, s86, 0x10080
	s_addc_u32 s81, s87, 0
	s_add_i32 s92, s26, s14
	s_add_i32 s61, s92, 0x2000
	v_lshl_add_u64 v[210:211], s[90:91], 0, v[150:151]
	ds_read_b128 v[178:181], v165
	ds_read_b128 v[182:185], v165 offset:1024
	ds_read_b128 v[186:189], v165 offset:2048
	ds_read_b128 v[190:193], v165 offset:3072
	ds_read_b128 v[194:197], v165 offset:4096
	ds_read_b128 v[198:201], v165 offset:5120
	ds_read_b128 v[202:205], v165 offset:6144
	ds_read_b128 v[206:209], v165 offset:7168
	global_load_lds_dwordx4 v[210:211], off
	v_lshl_add_u64 v[210:211], s[90:91], 0, v[146:147]
	s_mov_b32 m0, vcc_lo
	s_nop 0
	global_load_lds_dwordx4 v[210:211], off
	s_waitcnt vmcnt(8) lgkmcnt(0)
	s_barrier
	s_setprio 1
	v_mfma_f32_16x16x32_bf16 v[124:127], v[128:131], v[178:181], v[124:127]
	v_mfma_f32_16x16x32_bf16 v[120:123], v[136:139], v[178:181], v[120:123]
	v_mfma_f32_16x16x32_bf16 v[116:119], v[128:131], v[186:189], v[116:119]
	v_mfma_f32_16x16x32_bf16 v[112:115], v[136:139], v[186:189], v[112:115]
	v_mfma_f32_16x16x32_bf16 v[108:111], v[128:131], v[194:197], v[108:111]
	v_mfma_f32_16x16x32_bf16 v[100:103], v[136:139], v[194:197], v[100:103]
	v_mfma_f32_16x16x32_bf16 v[92:95], v[128:131], v[202:205], v[92:95]
	v_mfma_f32_16x16x32_bf16 v[84:87], v[136:139], v[202:205], v[84:87]
	v_mfma_f32_16x16x32_bf16 v[124:127], v[132:135], v[182:185], v[124:127]
	v_mfma_f32_16x16x32_bf16 v[120:123], v[140:143], v[182:185], v[120:123]
	v_mfma_f32_16x16x32_bf16 v[116:119], v[132:135], v[190:193], v[116:119]
	v_mfma_f32_16x16x32_bf16 v[112:115], v[140:143], v[190:193], v[112:115]
	v_mfma_f32_16x16x32_bf16 v[108:111], v[132:135], v[198:201], v[108:111]
	v_mfma_f32_16x16x32_bf16 v[100:103], v[140:143], v[198:201], v[100:103]
	v_mfma_f32_16x16x32_bf16 v[92:95], v[132:135], v[206:209], v[92:95]
	v_mfma_f32_16x16x32_bf16 v[84:87], v[140:143], v[206:209], v[84:87]
	v_mfma_f32_16x16x32_bf16 v[104:107], v[156:159], v[178:181], v[104:107]
	v_mfma_f32_16x16x32_bf16 v[96:99], v[170:173], v[178:181], v[96:99]
	v_mfma_f32_16x16x32_bf16 v[88:91], v[156:159], v[186:189], v[88:91]
	v_mfma_f32_16x16x32_bf16 v[80:83], v[170:173], v[186:189], v[80:83]
	v_mfma_f32_16x16x32_bf16 v[76:79], v[156:159], v[194:197], v[76:79]
	v_mfma_f32_16x16x32_bf16 v[72:75], v[170:173], v[194:197], v[72:75]
	v_mfma_f32_16x16x32_bf16 v[68:71], v[156:159], v[202:205], v[68:71]
	v_mfma_f32_16x16x32_bf16 v[64:67], v[170:173], v[202:205], v[64:67]
	v_mfma_f32_16x16x32_bf16 v[104:107], v[166:169], v[182:185], v[104:107]
	v_mfma_f32_16x16x32_bf16 v[96:99], v[174:177], v[182:185], v[96:99]
	v_mfma_f32_16x16x32_bf16 v[88:91], v[166:169], v[190:193], v[88:91]
	v_mfma_f32_16x16x32_bf16 v[80:83], v[174:177], v[190:193], v[80:83]
	v_mfma_f32_16x16x32_bf16 v[76:79], v[166:169], v[198:201], v[76:79]
	v_mfma_f32_16x16x32_bf16 v[72:75], v[174:177], v[198:201], v[72:75]
	v_mfma_f32_16x16x32_bf16 v[68:71], v[166:169], v[206:209], v[68:71]
	v_mfma_f32_16x16x32_bf16 v[64:67], v[174:177], v[206:209], v[64:67]
	s_setprio 0
	s_barrier
	s_mov_b32 m0, s97
	v_lshl_add_u64 v[210:211], s[86:87], 0, v[148:149]
	ds_read_b128 v[178:181], v165 offset:16384
	ds_read_b128 v[182:185], v165 offset:17408
	ds_read_b128 v[186:189], v165 offset:18432
	ds_read_b128 v[190:193], v165 offset:19456
	ds_read_b128 v[194:197], v165 offset:20480
	ds_read_b128 v[198:201], v165 offset:21504
	ds_read_b128 v[202:205], v165 offset:22528
	ds_read_b128 v[206:209], v165 offset:23552
	global_load_lds_dwordx4 v[210:211], off
	v_lshl_add_u64 v[216:217], s[86:87], 0, v[144:145]
	s_mov_b32 m0, s94
	v_lshl_add_u64 v[218:219], s[88:89], 0, v[148:149]
	global_load_lds_dwordx4 v[216:217], off
	s_mov_b32 m0, s96
	v_lshl_add_u64 v[220:221], s[84:85], 0, v[146:147]
	global_load_lds_dwordx4 v[218:219], off
	v_lshl_add_u64 v[218:219], s[88:89], 0, v[144:145]
	s_mov_b32 m0, s95
	s_nop 0
	global_load_lds_dwordx4 v[218:219], off
	v_lshl_add_u64 v[218:219], s[84:85], 0, v[150:151]
	s_mov_b32 m0, s15
	s_nop 0
	global_load_lds_dwordx4 v[218:219], off
	s_mov_b32 m0, s18
	s_nop 0
	global_load_lds_dwordx4 v[220:221], off
	s_waitcnt vmcnt(8) lgkmcnt(0)
	s_barrier
; #define PG8_STAGE(bufoff, gbase, voff) do { _Pragma("unroll") for (int _i = 0; _i < 2; ++_i) \
;         __builtin_amdgcn_global_load_lds((const unsigned*)((const char*)(gbase) + (voff)[_i]), (LAS unsigned*)(lds + (bufoff) + ldsw + _i * 8192), 16, 0, 0); } while (0)
; #define PG8_LDA(dst, b, h) do { _Pragma("unroll") for (int m = 0; m < 4; ++m) _Pragma("unroll") for (int k = 0; k < 2; ++k) dst[m][k] = *(const LAS bf16x8*)(lds + PG8_SA(b, h) + aoff + m * 2048 + k * 1024); } while (0)
; #define PG8_LDB(dst, b, h) do { _Pragma("unroll") for (int n = 0; n < 2; ++n) _Pragma("unroll") for (int k = 0; k < 2; ++k) dst[n][k] = *(const LAS bf16x8*)(lds + PG8_SB(b, h) + boff + n * 2048 + k * 1024); } while (0)
; #define PG8_MMA(ai, bj, At, Bt) do { __builtin_amdgcn_s_setprio(1); _Pragma("unroll") for (int m = 0; m < 4; ++m) _Pragma("unroll") for (int n = 0; n < 2; ++n) _Pragma("unroll") for (int k = 0; k < 2; ++k) \
;         acc[ai][bj][m][n] = __builtin_amdgcn_mfma_f32_16x16x32_bf16(Bt[n][k], At[m][k], acc[ai][bj][m][n], 0, 0, 0); __builtin_amdgcn_s_setprio(0); } while (0)
; #define PG8_WAIT_V(n) asm volatile("s_waitcnt vmcnt(" #n ")" ::: "memory")
; #define PG8_WAIT_L(n) asm volatile("s_waitcnt lgkmcnt(" #n ")" ::: "memory")
; #define PG8_BAR __builtin_amdgcn_s_barrier()
; #define PG8_SCHED __builtin_amdgcn_sched_barrier(0)
; template <class Epi, class Sched>
; __device__ __forceinline__ void gemm_phase(LAS unsigned char* lds, const Gemm g, const Sched& S, const Epi& E) {
;     ...
;             PG8_WAIT_V(8); PG8_WAIT_L(0); PG8_BAR; PG8_MMA(1, 0, At, B0); PG8_MMA(1, 1, At, B1); PG8_BAR; PG8_SCHED;
;             PG8_LDB(B0, 1, 0); PG8_LDB(B1, 1, 1); PG8_SCHED; PG8_LDA(At, 1, 0); PG8_STAGE(PG8_SA(0, 1), a2 + hstepA, voffA);
;             PG8_WAIT_V(8); PG8_WAIT_L(0); PG8_BAR; PG8_MMA(0, 0, At, B0); PG8_MMA(0, 1, At, B1); PG8_BAR; PG8_SCHED;
	s_setprio 1
	v_mfma_f32_16x16x32_bf16 v[60:63], v[128:131], v[178:181], v[60:63]
	v_mfma_f32_16x16x32_bf16 v[56:59], v[136:139], v[178:181], v[56:59]
	v_mfma_f32_16x16x32_bf16 v[48:51], v[128:131], v[186:189], v[48:51]
	v_mfma_f32_16x16x32_bf16 v[40:43], v[136:139], v[186:189], v[40:43]
	v_mfma_f32_16x16x32_bf16 v[32:35], v[128:131], v[194:197], v[32:35]
	v_mfma_f32_16x16x32_bf16 v[24:27], v[136:139], v[194:197], v[24:27]
	v_mfma_f32_16x16x32_bf16 v[16:19], v[128:131], v[202:205], v[16:19]
	v_mfma_f32_16x16x32_bf16 v[8:11], v[136:139], v[202:205], v[8:11]
	v_mfma_f32_16x16x32_bf16 v[60:63], v[132:135], v[182:185], v[60:63]
	v_mfma_f32_16x16x32_bf16 v[56:59], v[140:143], v[182:185], v[56:59]
	v_mfma_f32_16x16x32_bf16 v[48:51], v[132:135], v[190:193], v[48:51]
	v_mfma_f32_16x16x32_bf16 v[40:43], v[140:143], v[190:193], v[40:43]
	v_mfma_f32_16x16x32_bf16 v[32:35], v[132:135], v[198:201], v[32:35]
	v_mfma_f32_16x16x32_bf16 v[24:27], v[140:143], v[198:201], v[24:27]
	v_mfma_f32_16x16x32_bf16 v[16:19], v[132:135], v[206:209], v[16:19]
	v_mfma_f32_16x16x32_bf16 v[8:11], v[140:143], v[206:209], v[8:11]
	v_mfma_f32_16x16x32_bf16 v[52:55], v[156:159], v[178:181], v[52:55]
	v_mfma_f32_16x16x32_bf16 v[44:47], v[170:173], v[178:181], v[44:47]
	v_mfma_f32_16x16x32_bf16 v[36:39], v[156:159], v[186:189], v[36:39]
	v_mfma_f32_16x16x32_bf16 v[28:31], v[170:173], v[186:189], v[28:31]
	v_mfma_f32_16x16x32_bf16 v[20:23], v[156:159], v[194:197], v[20:23]
	v_mfma_f32_16x16x32_bf16 v[12:15], v[170:173], v[194:197], v[12:15]
	v_mfma_f32_16x16x32_bf16 v[4:7], v[156:159], v[202:205], v[4:7]
	v_mfma_f32_16x16x32_bf16 v[0:3], v[170:173], v[202:205], v[0:3]
	v_mfma_f32_16x16x32_bf16 v[52:55], v[166:169], v[182:185], v[52:55]
	v_mfma_f32_16x16x32_bf16 v[44:47], v[174:177], v[182:185], v[44:47]
	v_mfma_f32_16x16x32_bf16 v[36:39], v[166:169], v[190:193], v[36:39]
	v_mfma_f32_16x16x32_bf16 v[28:31], v[174:177], v[190:193], v[28:31]
	v_mfma_f32_16x16x32_bf16 v[20:23], v[166:169], v[198:201], v[20:23]
	v_mfma_f32_16x16x32_bf16 v[12:15], v[174:177], v[198:201], v[12:15]
	v_mfma_f32_16x16x32_bf16 v[4:7], v[166:169], v[206:209], v[4:7]
	v_mfma_f32_16x16x32_bf16 v[0:3], v[174:177], v[206:209], v[0:3]
	s_setprio 0
	s_barrier
	v_add_u32_e32 v140, s37, v162
	v_add_u32_e32 v174, s26, v162
	ds_read_b128 v[128:131], v140
	ds_read_b128 v[132:135], v140 offset:1024
	ds_read_b128 v[136:139], v140 offset:2048
	ds_read_b128 v[140:143], v140 offset:3072
	ds_read_b128 v[156:159], v174
	ds_read_b128 v[166:169], v174 offset:1024
	ds_read_b128 v[170:173], v174 offset:2048
	ds_read_b128 v[174:177], v174 offset:3072
	s_mov_b32 m0, s19
	v_lshl_add_u64 v[222:223], s[82:83], 0, v[150:151]
	ds_read_b128 v[178:181], v165 offset:32768
	ds_read_b128 v[182:185], v165 offset:33792
	ds_read_b128 v[186:189], v165 offset:34816
	ds_read_b128 v[190:193], v165 offset:35840
	ds_read_b128 v[194:197], v165 offset:36864
	ds_read_b128 v[198:201], v165 offset:37888
	ds_read_b128 v[202:205], v165 offset:38912
	ds_read_b128 v[206:209], v165 offset:39936
	global_load_lds_dwordx4 v[222:223], off
	v_lshl_add_u64 v[222:223], s[82:83], 0, v[146:147]
	s_mov_b32 m0, s21
	s_nop 0
	global_load_lds_dwordx4 v[222:223], off
	s_waitcnt vmcnt(8) lgkmcnt(0)
	s_barrier
	s_setprio 1
	v_mfma_f32_16x16x32_bf16 v[124:127], v[128:131], v[178:181], v[124:127]
	v_mfma_f32_16x16x32_bf16 v[120:123], v[136:139], v[178:181], v[120:123]
	v_mfma_f32_16x16x32_bf16 v[116:119], v[128:131], v[186:189], v[116:119]
	v_mfma_f32_16x16x32_bf16 v[112:115], v[136:139], v[186:189], v[112:115]
	v_mfma_f32_16x16x32_bf16 v[108:111], v[128:131], v[194:197], v[108:111]
	v_mfma_f32_16x16x32_bf16 v[100:103], v[136:139], v[194:197], v[100:103]
	v_mfma_f32_16x16x32_bf16 v[92:95], v[128:131], v[202:205], v[92:95]
	v_mfma_f32_16x16x32_bf16 v[84:87], v[136:139], v[202:205], v[84:87]
	v_mfma_f32_16x16x32_bf16 v[124:127], v[132:135], v[182:185], v[124:127]
	v_mfma_f32_16x16x32_bf16 v[120:123], v[140:143], v[182:185], v[120:123]
	v_mfma_f32_16x16x32_bf16 v[116:119], v[132:135], v[190:193], v[116:119]
	v_mfma_f32_16x16x32_bf16 v[112:115], v[140:143], v[190:193], v[112:115]
	v_mfma_f32_16x16x32_bf16 v[108:111], v[132:135], v[198:201], v[108:111]
	v_mfma_f32_16x16x32_bf16 v[100:103], v[140:143], v[198:201], v[100:103]
	v_mfma_f32_16x16x32_bf16 v[92:95], v[132:135], v[206:209], v[92:95]
	v_mfma_f32_16x16x32_bf16 v[84:87], v[140:143], v[206:209], v[84:87]
	v_mfma_f32_16x16x32_bf16 v[104:107], v[156:159], v[178:181], v[104:107]
	v_mfma_f32_16x16x32_bf16 v[96:99], v[170:173], v[178:181], v[96:99]
	v_mfma_f32_16x16x32_bf16 v[88:91], v[156:159], v[186:189], v[88:91]
	v_mfma_f32_16x16x32_bf16 v[80:83], v[170:173], v[186:189], v[80:83]
	v_mfma_f32_16x16x32_bf16 v[76:79], v[156:159], v[194:197], v[76:79]
	v_mfma_f32_16x16x32_bf16 v[72:75], v[170:173], v[194:197], v[72:75]
	v_mfma_f32_16x16x32_bf16 v[68:71], v[156:159], v[202:205], v[68:71]
	v_mfma_f32_16x16x32_bf16 v[64:67], v[170:173], v[202:205], v[64:67]
	v_mfma_f32_16x16x32_bf16 v[104:107], v[166:169], v[182:185], v[104:107]
	v_mfma_f32_16x16x32_bf16 v[96:99], v[174:177], v[182:185], v[96:99]
	v_mfma_f32_16x16x32_bf16 v[88:91], v[166:169], v[190:193], v[88:91]
	v_mfma_f32_16x16x32_bf16 v[80:83], v[174:177], v[190:193], v[80:83]
	v_mfma_f32_16x16x32_bf16 v[76:79], v[166:169], v[198:201], v[76:79]
	v_mfma_f32_16x16x32_bf16 v[72:75], v[174:177], v[198:201], v[72:75]
	v_mfma_f32_16x16x32_bf16 v[68:71], v[166:169], v[206:209], v[68:71]
	v_mfma_f32_16x16x32_bf16 v[64:67], v[174:177], v[206:209], v[64:67]
	s_setprio 0
	s_barrier
; #define PG8_STAGE(bufoff, gbase, voff) do { _Pragma("unroll") for (int _i = 0; _i < 2; ++_i) \
;         __builtin_amdgcn_global_load_lds((const unsigned*)((const char*)(gbase) + (voff)[_i]), (LAS unsigned*)(lds + (bufoff) + ldsw + _i * 8192), 16, 0, 0); } while (0)
; #define PG8_LDA(dst, b, h) do { _Pragma("unroll") for (int m = 0; m < 4; ++m) _Pragma("unroll") for (int k = 0; k < 2; ++k) dst[m][k] = *(const LAS bf16x8*)(lds + PG8_SA(b, h) + aoff + m * 2048 + k * 1024); } while (0)
; #define PG8_MMA(ai, bj, At, Bt) do { __builtin_amdgcn_s_setprio(1); _Pragma("unroll") for (int m = 0; m < 4; ++m) _Pragma("unroll") for (int n = 0; n < 2; ++n) _Pragma("unroll") for (int k = 0; k < 2; ++k) \
;         acc[ai][bj][m][n] = __builtin_amdgcn_mfma_f32_16x16x32_bf16(Bt[n][k], At[m][k], acc[ai][bj][m][n], 0, 0, 0); __builtin_amdgcn_s_setprio(0); } while (0)
; #define PG8_WAIT_V(n) asm volatile("s_waitcnt vmcnt(" #n ")" ::: "memory")
; #define PG8_WAIT_L(n) asm volatile("s_waitcnt lgkmcnt(" #n ")" ::: "memory")
; #define PG8_BAR __builtin_amdgcn_s_barrier()
; #define PG8_SCHED __builtin_amdgcn_sched_barrier(0)
; template <class Epi, class Sched>
; __device__ __forceinline__ void gemm_phase(LAS unsigned char* lds, const Gemm g, const Sched& S, const Epi& E) {
;     ...
;             PG8_LDA(At, 1, 1); PG8_STAGE(PG8_SB(1, 0), b3, voffB); PG8_STAGE(PG8_SB(1, 1), b3 + hstepB, voffB); PG8_STAGE(PG8_SA(1, 0), a3, voffA);
;             PG8_WAIT_V(8); PG8_WAIT_L(0); PG8_BAR; PG8_MMA(1, 0, At, B0); PG8_MMA(1, 1, At, B1); PG8_BAR; PG8_SCHED;
;         }
;         if (wr == 0) PG8_BAR;
	s_mov_b32 m0, s93
	v_lshl_add_u64 v[210:211], v[210:211], 0, s[8:9]
	ds_read_b128 v[178:181], v165 offset:49152
	ds_read_b128 v[182:185], v165 offset:50176
	ds_read_b128 v[186:189], v165 offset:51200
	ds_read_b128 v[190:193], v165 offset:52224
	ds_read_b128 v[194:197], v165 offset:53248
	ds_read_b128 v[198:201], v165 offset:54272
	ds_read_b128 v[202:205], v165 offset:55296
	ds_read_b128 v[206:209], v165 offset:56320
	global_load_lds_dwordx4 v[210:211], off
	v_lshl_add_u64 v[210:211], v[216:217], 0, s[8:9]
	s_mov_b32 m0, s73
	s_nop 0
	global_load_lds_dwordx4 v[210:211], off
	v_lshl_add_u64 v[210:211], s[80:81], 0, v[148:149]
	s_mov_b32 m0, s92
	s_nop 0
	global_load_lds_dwordx4 v[210:211], off
	v_lshl_add_u64 v[210:211], s[80:81], 0, v[144:145]
	s_mov_b32 m0, s61
	s_nop 0
	global_load_lds_dwordx4 v[210:211], off
	v_lshl_add_u64 v[210:211], v[218:219], 0, s[8:9]
	s_mov_b32 m0, s34
	s_nop 0
	global_load_lds_dwordx4 v[210:211], off
	v_lshl_add_u64 v[210:211], v[220:221], 0, s[8:9]
	s_mov_b32 m0, s35
	s_nop 0
	global_load_lds_dwordx4 v[210:211], off
	s_waitcnt vmcnt(8) lgkmcnt(0)
	s_barrier
	s_setprio 1
	v_mfma_f32_16x16x32_bf16 v[60:63], v[128:131], v[178:181], v[60:63]
	v_mfma_f32_16x16x32_bf16 v[56:59], v[136:139], v[178:181], v[56:59]
	v_mfma_f32_16x16x32_bf16 v[48:51], v[128:131], v[186:189], v[48:51]
	v_mfma_f32_16x16x32_bf16 v[40:43], v[136:139], v[186:189], v[40:43]
	v_mfma_f32_16x16x32_bf16 v[32:35], v[128:131], v[194:197], v[32:35]
	v_mfma_f32_16x16x32_bf16 v[24:27], v[136:139], v[194:197], v[24:27]
	v_mfma_f32_16x16x32_bf16 v[16:19], v[128:131], v[202:205], v[16:19]
	v_mfma_f32_16x16x32_bf16 v[8:11], v[136:139], v[202:205], v[8:11]
	v_mfma_f32_16x16x32_bf16 v[60:63], v[132:135], v[182:185], v[60:63]
	v_mfma_f32_16x16x32_bf16 v[56:59], v[140:143], v[182:185], v[56:59]
	v_mfma_f32_16x16x32_bf16 v[48:51], v[132:135], v[190:193], v[48:51]
	v_mfma_f32_16x16x32_bf16 v[40:43], v[140:143], v[190:193], v[40:43]
	v_mfma_f32_16x16x32_bf16 v[32:35], v[132:135], v[198:201], v[32:35]
	v_mfma_f32_16x16x32_bf16 v[24:27], v[140:143], v[198:201], v[24:27]
	v_mfma_f32_16x16x32_bf16 v[16:19], v[132:135], v[206:209], v[16:19]
	v_mfma_f32_16x16x32_bf16 v[8:11], v[140:143], v[206:209], v[8:11]
	v_mfma_f32_16x16x32_bf16 v[52:55], v[156:159], v[178:181], v[52:55]
	v_mfma_f32_16x16x32_bf16 v[44:47], v[170:173], v[178:181], v[44:47]
	v_mfma_f32_16x16x32_bf16 v[36:39], v[156:159], v[186:189], v[36:39]
	v_mfma_f32_16x16x32_bf16 v[28:31], v[170:173], v[186:189], v[28:31]
	v_mfma_f32_16x16x32_bf16 v[20:23], v[156:159], v[194:197], v[20:23]
	v_mfma_f32_16x16x32_bf16 v[12:15], v[170:173], v[194:197], v[12:15]
	v_mfma_f32_16x16x32_bf16 v[4:7], v[156:159], v[202:205], v[4:7]
	v_mfma_f32_16x16x32_bf16 v[0:3], v[170:173], v[202:205], v[0:3]
	v_mfma_f32_16x16x32_bf16 v[52:55], v[166:169], v[182:185], v[52:55]
	v_mfma_f32_16x16x32_bf16 v[44:47], v[174:177], v[182:185], v[44:47]
	v_mfma_f32_16x16x32_bf16 v[36:39], v[166:169], v[190:193], v[36:39]
	v_mfma_f32_16x16x32_bf16 v[28:31], v[174:177], v[190:193], v[28:31]
	v_mfma_f32_16x16x32_bf16 v[20:23], v[166:169], v[198:201], v[20:23]
	v_mfma_f32_16x16x32_bf16 v[12:15], v[174:177], v[198:201], v[12:15]
	v_mfma_f32_16x16x32_bf16 v[4:7], v[166:169], v[206:209], v[4:7]
	v_mfma_f32_16x16x32_bf16 v[0:3], v[174:177], v[206:209], v[0:3]
	s_setprio 0
	s_barrier
	s_andn2_b64 vcc, exec, s[78:79]
	s_mov_b64 s[80:81], -1
	s_mov_b64 s[78:79], 0
	s_mov_b64 s[82:83], 0x100
	s_cbranch_vccz .LBB0_531
	v_readlane_b32 s80, v248, 11
	s_and_b64 vcc, exec, s[56:57]
	v_readlane_b32 s81, v248, 12
	v_readlane_b32 s82, v248, 13
	v_readlane_b32 s83, v248, 14
	v_readlane_b32 s84, v248, 15
	v_readlane_b32 s85, v248, 16
	v_readlane_b32 s86, v248, 17
	v_readlane_b32 s87, v248, 18
	v_readlane_b32 s88, v248, 19
	v_readlane_b32 s89, v248, 20
	v_readlane_b32 s90, v248, 21
	v_readlane_b32 s91, v248, 22
	v_readlane_b32 s92, v248, 23
	v_readlane_b32 s93, v248, 24
	v_readlane_b32 s94, v248, 25
	v_readlane_b32 s95, v248, 26
	s_cbranch_vccz .LBB0_534
	s_barrier

; #define PG8_STAGE(bufoff, gbase, voff) do { _Pragma("unroll") for (int _i = 0; _i < 2; ++_i) \
;         __builtin_amdgcn_global_load_lds((const unsigned*)((const char*)(gbase) + (voff)[_i]), (LAS unsigned*)(lds + (bufoff) + ldsw + _i * 8192), 16, 0, 0); } while (0)
; #define PG8_LDA(dst, b, h) do { _Pragma("unroll") for (int m = 0; m < 4; ++m) _Pragma("unroll") for (int k = 0; k < 2; ++k) dst[m][k] = *(const LAS bf16x8*)(lds + PG8_SA(b, h) + aoff + m * 2048 + k * 1024); } while (0)
; #define PG8_LDB(dst, b, h) do { _Pragma("unroll") for (int n = 0; n < 2; ++n) _Pragma("unroll") for (int k = 0; k < 2; ++k) dst[n][k] = *(const LAS bf16x8*)(lds + PG8_SB(b, h) + boff + n * 2048 + k * 1024); } while (0)
; #define PG8_MMA(ai, bj, At, Bt) do { __builtin_amdgcn_s_setprio(1); _Pragma("unroll") for (int m = 0; m < 4; ++m) _Pragma("unroll") for (int n = 0; n < 2; ++n) _Pragma("unroll") for (int k = 0; k < 2; ++k) \
;         acc[ai][bj][m][n] = __builtin_amdgcn_mfma_f32_16x16x32_bf16(Bt[n][k], At[m][k], acc[ai][bj][m][n], 0, 0, 0); __builtin_amdgcn_s_setprio(0); } while (0)
; #define PG8_WAIT_V(n) asm volatile("s_waitcnt vmcnt(" #n ")" ::: "memory")
; #define PG8_WAIT_L(n) asm volatile("s_waitcnt lgkmcnt(" #n ")" ::: "memory")
; #define PG8_BAR __builtin_amdgcn_s_barrier()
; #define PG8_SCHED __builtin_amdgcn_sched_barrier(0)
; template <class Epi, class Sched>
; __device__ __forceinline__ void gemm_phase(LAS unsigned char* lds, const Gemm g, const Sched& S, const Epi& E) {
;     ...
;             const bool last = (t == nt - 2);
;             const char* a1 = cA + (size_t)(t + 1) * kstep;
;             const char* a2 = last ? nA : cA + (size_t)(t + 2) * kstep; const char* b2 = last ? nB : cB + (size_t)(t + 2) * kstep;
;             const char* a3 = a2 + kstep; const char* b3 = b2 + kstep;
;             PG8_LDB(B0, 0, 0); PG8_LDB(B1, 0, 1); PG8_SCHED; PG8_LDA(At, 0, 0); PG8_STAGE(PG8_SA(1, 1), a1 + hstepA, voffA);
;             PG8_WAIT_V(8); PG8_WAIT_L(0); PG8_BAR; PG8_MMA(0, 0, At, B0); PG8_MMA(0, 1, At, B1); PG8_BAR; PG8_SCHED;
;             PG8_LDA(At, 0, 1); PG8_STAGE(PG8_SB(0, 0), b2, voffB); PG8_STAGE(PG8_SB(0, 1), b2 + hstepB, voffB); PG8_STAGE(PG8_SA(0, 0), a2, voffA);
.LBB0_553:
	s_add_u32 s35, s78, s82
	s_addc_u32 s45, s79, s83
	s_add_u32 s63, s35, 0x100
	s_addc_u32 s65, s45, 0
	s_and_b64 s[48:49], s[80:81], exec
	s_cselect_b32 s85, s71, s65
	s_cselect_b32 s84, s70, s63
	s_add_u32 s48, s76, s82
	s_addc_u32 s49, s77, s83
	s_add_u32 s63, s48, 0x100
	s_addc_u32 s65, s49, 0
	s_and_b64 s[48:49], s[80:81], exec
	s_cselect_b32 s87, s31, s65
	s_cselect_b32 s86, s34, s63
	s_add_u32 s90, s35, 0x80080
	ds_read_b128 v[64:67], v218
	ds_read_b128 v[68:71], v218 offset:1024
	ds_read_b128 v[72:75], v218 offset:2048
	ds_read_b128 v[80:83], v218 offset:3072
	ds_read_b128 v[88:91], v219
	ds_read_b128 v[92:95], v219 offset:1024
	ds_read_b128 v[100:103], v219 offset:2048
	ds_read_b128 v[108:111], v219 offset:3072
	s_addc_u32 s91, s45, 0
	s_add_i32 s75, s33, s12
	s_add_i32 m0, s13, 0xc000
	s_add_i32 s92, s13, 0xe000
	s_add_i32 s63, s75, 0x2000
	s_add_u32 s88, s86, 0x10000
	s_addc_u32 s89, s87, 0
	s_add_i32 s67, s36, s12
	s_add_i32 s65, s67, 0x2000
	s_add_u32 s82, s84, 0x80000
	s_addc_u32 s83, s85, 0
	s_add_i32 s49, s37, s12
	s_add_i32 s45, s49, 0x2000
	s_add_u32 s80, s86, 0x10080
	s_addc_u32 s81, s87, 0
	s_add_i32 s48, s26, s12
	s_add_i32 s35, s48, 0x2000
	v_lshl_add_u64 v[204:205], s[90:91], 0, v[190:191]
	ds_read_b128 v[128:131], v220
	ds_read_b128 v[148:151], v220 offset:1024
	ds_read_b128 v[164:167], v220 offset:2048
	ds_read_b128 v[172:175], v220 offset:3072
	ds_read_b128 v[176:179], v220 offset:4096
	ds_read_b128 v[180:183], v220 offset:5120
	ds_read_b128 v[196:199], v220 offset:6144
	ds_read_b128 v[200:203], v220 offset:7168
	global_load_lds_dwordx4 v[204:205], off
	v_lshl_add_u64 v[204:205], s[90:91], 0, v[186:187]
	s_mov_b32 m0, s92
	s_nop 0
	global_load_lds_dwordx4 v[204:205], off
	s_waitcnt vmcnt(8) lgkmcnt(0)
	s_barrier
	s_setprio 1
	v_mfma_f32_16x16x32_bf16 v[168:171], v[64:67], v[128:131], v[168:171]
	v_mfma_f32_16x16x32_bf16 v[156:159], v[72:75], v[128:131], v[156:159]
	v_mfma_f32_16x16x32_bf16 v[144:147], v[64:67], v[164:167], v[144:147]
	v_mfma_f32_16x16x32_bf16 v[136:139], v[72:75], v[164:167], v[136:139]
	v_mfma_f32_16x16x32_bf16 v[124:127], v[64:67], v[176:179], v[124:127]
	v_mfma_f32_16x16x32_bf16 v[116:119], v[72:75], v[176:179], v[116:119]
	v_mfma_f32_16x16x32_bf16 v[104:107], v[64:67], v[196:199], v[104:107]
	v_mfma_f32_16x16x32_bf16 v[84:87], v[72:75], v[196:199], v[84:87]
	v_mfma_f32_16x16x32_bf16 v[168:171], v[68:71], v[148:151], v[168:171]
	v_mfma_f32_16x16x32_bf16 v[156:159], v[80:83], v[148:151], v[156:159]
	v_mfma_f32_16x16x32_bf16 v[144:147], v[68:71], v[172:175], v[144:147]
	v_mfma_f32_16x16x32_bf16 v[136:139], v[80:83], v[172:175], v[136:139]
	v_mfma_f32_16x16x32_bf16 v[124:127], v[68:71], v[180:183], v[124:127]
	v_mfma_f32_16x16x32_bf16 v[116:119], v[80:83], v[180:183], v[116:119]
	v_mfma_f32_16x16x32_bf16 v[104:107], v[68:71], v[200:203], v[104:107]
	v_mfma_f32_16x16x32_bf16 v[84:87], v[80:83], v[200:203], v[84:87]
	v_mfma_f32_16x16x32_bf16 v[160:163], v[88:91], v[128:131], v[160:163]
	v_mfma_f32_16x16x32_bf16 v[140:143], v[88:91], v[164:167], v[140:143]
	v_mfma_f32_16x16x32_bf16 v[132:135], v[100:103], v[164:167], v[132:135]
	v_mfma_f32_16x16x32_bf16 v[120:123], v[88:91], v[176:179], v[120:123]
	v_mfma_f32_16x16x32_bf16 v[112:115], v[100:103], v[176:179], v[112:115]
	v_mfma_f32_16x16x32_bf16 v[96:99], v[88:91], v[196:199], v[96:99]
	v_mfma_f32_16x16x32_bf16 v[76:79], v[100:103], v[196:199], v[76:79]
	v_mfma_f32_16x16x32_bf16 v[160:163], v[92:95], v[148:151], v[160:163]
	v_mfma_f32_16x16x32_bf16 v[128:131], v[100:103], v[128:131], v[152:155]
	v_mfma_f32_16x16x32_bf16 v[140:143], v[92:95], v[172:175], v[140:143]
	v_mfma_f32_16x16x32_bf16 v[132:135], v[108:111], v[172:175], v[132:135]
	v_mfma_f32_16x16x32_bf16 v[120:123], v[92:95], v[180:183], v[120:123]
	v_mfma_f32_16x16x32_bf16 v[112:115], v[108:111], v[180:183], v[112:115]
	v_mfma_f32_16x16x32_bf16 v[96:99], v[92:95], v[200:203], v[96:99]
	v_mfma_f32_16x16x32_bf16 v[76:79], v[108:111], v[200:203], v[76:79]
	v_mfma_f32_16x16x32_bf16 v[128:131], v[108:111], v[148:151], v[128:131]
	s_setprio 0
	s_barrier
	s_mov_b32 m0, s75
	v_lshl_add_u64 v[204:205], s[86:87], 0, v[188:189]
	ds_read_b128 v[148:151], v220 offset:16384
	ds_read_b128 v[152:155], v220 offset:17408
	ds_read_b128 v[164:167], v220 offset:18432
	ds_read_b128 v[172:175], v220 offset:19456
	ds_read_b128 v[176:179], v220 offset:20480
	ds_read_b128 v[180:183], v220 offset:21504
	ds_read_b128 v[196:199], v220 offset:22528
	ds_read_b128 v[200:203], v220 offset:23552
	global_load_lds_dwordx4 v[204:205], off
	v_lshl_add_u64 v[206:207], s[86:87], 0, v[184:185]
	s_mov_b32 m0, s63
	v_lshl_add_u64 v[208:209], s[88:89], 0, v[188:189]
	global_load_lds_dwordx4 v[206:207], off
	s_mov_b32 m0, s67
	v_lshl_add_u64 v[210:211], s[84:85], 0, v[186:187]
	global_load_lds_dwordx4 v[208:209], off
	v_lshl_add_u64 v[208:209], s[88:89], 0, v[184:185]
	s_mov_b32 m0, s65
	s_nop 0
	global_load_lds_dwordx4 v[208:209], off
	v_lshl_add_u64 v[208:209], s[84:85], 0, v[190:191]
	s_mov_b32 m0, s13
	s_nop 0
	global_load_lds_dwordx4 v[208:209], off
	s_mov_b32 m0, s14
	s_nop 0
	global_load_lds_dwordx4 v[210:211], off
	s_waitcnt vmcnt(8) lgkmcnt(0)
	s_barrier
; #define PG8_STAGE(bufoff, gbase, voff) do { _Pragma("unroll") for (int _i = 0; _i < 2; ++_i) \
;         __builtin_amdgcn_global_load_lds((const unsigned*)((const char*)(gbase) + (voff)[_i]), (LAS unsigned*)(lds + (bufoff) + ldsw + _i * 8192), 16, 0, 0); } while (0)
; #define PG8_LDA(dst, b, h) do { _Pragma("unroll") for (int m = 0; m < 4; ++m) _Pragma("unroll") for (int k = 0; k < 2; ++k) dst[m][k] = *(const LAS bf16x8*)(lds + PG8_SA(b, h) + aoff + m * 2048 + k * 1024); } while (0)
; #define PG8_LDB(dst, b, h) do { _Pragma("unroll") for (int n = 0; n < 2; ++n) _Pragma("unroll") for (int k = 0; k < 2; ++k) dst[n][k] = *(const LAS bf16x8*)(lds + PG8_SB(b, h) + boff + n * 2048 + k * 1024); } while (0)
; #define PG8_MMA(ai, bj, At, Bt) do { __builtin_amdgcn_s_setprio(1); _Pragma("unroll") for (int m = 0; m < 4; ++m) _Pragma("unroll") for (int n = 0; n < 2; ++n) _Pragma("unroll") for (int k = 0; k < 2; ++k) \
;         acc[ai][bj][m][n] = __builtin_amdgcn_mfma_f32_16x16x32_bf16(Bt[n][k], At[m][k], acc[ai][bj][m][n], 0, 0, 0); __builtin_amdgcn_s_setprio(0); } while (0)
; #define PG8_WAIT_V(n) asm volatile("s_waitcnt vmcnt(" #n ")" ::: "memory")
; #define PG8_WAIT_L(n) asm volatile("s_waitcnt lgkmcnt(" #n ")" ::: "memory")
; #define PG8_BAR __builtin_amdgcn_s_barrier()
; #define PG8_SCHED __builtin_amdgcn_sched_barrier(0)
; template <class Epi, class Sched>
; __device__ __forceinline__ void gemm_phase(LAS unsigned char* lds, const Gemm g, const Sched& S, const Epi& E) {
;     ...
;             PG8_WAIT_V(8); PG8_WAIT_L(0); PG8_BAR; PG8_MMA(1, 0, At, B0); PG8_MMA(1, 1, At, B1); PG8_BAR; PG8_SCHED;
;             PG8_LDB(B0, 1, 0); PG8_LDB(B1, 1, 1); PG8_SCHED; PG8_LDA(At, 1, 0); PG8_STAGE(PG8_SA(0, 1), a2 + hstepA, voffA);
;             PG8_WAIT_V(8); PG8_WAIT_L(0); PG8_BAR; PG8_MMA(0, 0, At, B0); PG8_MMA(0, 1, At, B1); PG8_BAR; PG8_SCHED;
	s_setprio 1
	v_mfma_f32_16x16x32_bf16 v[60:63], v[64:67], v[148:151], v[60:63]
	v_mfma_f32_16x16x32_bf16 v[52:55], v[72:75], v[148:151], v[52:55]
	v_mfma_f32_16x16x32_bf16 v[44:47], v[64:67], v[164:167], v[44:47]
	v_mfma_f32_16x16x32_bf16 v[36:39], v[72:75], v[164:167], v[36:39]
	v_mfma_f32_16x16x32_bf16 v[28:31], v[64:67], v[176:179], v[28:31]
	v_mfma_f32_16x16x32_bf16 v[20:23], v[72:75], v[176:179], v[20:23]
	v_mfma_f32_16x16x32_bf16 v[12:15], v[64:67], v[196:199], v[12:15]
	v_mfma_f32_16x16x32_bf16 v[4:7], v[72:75], v[196:199], v[4:7]
	v_mfma_f32_16x16x32_bf16 v[60:63], v[68:71], v[152:155], v[60:63]
	v_mfma_f32_16x16x32_bf16 v[52:55], v[80:83], v[152:155], v[52:55]
	v_mfma_f32_16x16x32_bf16 v[44:47], v[68:71], v[172:175], v[44:47]
	v_mfma_f32_16x16x32_bf16 v[36:39], v[80:83], v[172:175], v[36:39]
	v_mfma_f32_16x16x32_bf16 v[28:31], v[68:71], v[180:183], v[28:31]
	v_mfma_f32_16x16x32_bf16 v[20:23], v[80:83], v[180:183], v[20:23]
	v_mfma_f32_16x16x32_bf16 v[12:15], v[68:71], v[200:203], v[12:15]
	v_mfma_f32_16x16x32_bf16 v[4:7], v[80:83], v[200:203], v[4:7]
	v_mfma_f32_16x16x32_bf16 v[56:59], v[88:91], v[148:151], v[56:59]
	v_mfma_f32_16x16x32_bf16 v[48:51], v[100:103], v[148:151], v[48:51]
	v_mfma_f32_16x16x32_bf16 v[40:43], v[88:91], v[164:167], v[40:43]
	v_mfma_f32_16x16x32_bf16 v[32:35], v[100:103], v[164:167], v[32:35]
	v_mfma_f32_16x16x32_bf16 v[24:27], v[88:91], v[176:179], v[24:27]
	v_mfma_f32_16x16x32_bf16 v[16:19], v[100:103], v[176:179], v[16:19]
	v_mfma_f32_16x16x32_bf16 v[8:11], v[88:91], v[196:199], v[8:11]
	v_mfma_f32_16x16x32_bf16 v[0:3], v[100:103], v[196:199], v[0:3]
	v_mfma_f32_16x16x32_bf16 v[56:59], v[92:95], v[152:155], v[56:59]
	v_mfma_f32_16x16x32_bf16 v[48:51], v[108:111], v[152:155], v[48:51]
	v_mfma_f32_16x16x32_bf16 v[40:43], v[92:95], v[172:175], v[40:43]
	v_mfma_f32_16x16x32_bf16 v[32:35], v[108:111], v[172:175], v[32:35]
	v_mfma_f32_16x16x32_bf16 v[24:27], v[92:95], v[180:183], v[24:27]
	v_mfma_f32_16x16x32_bf16 v[16:19], v[108:111], v[180:183], v[16:19]
	v_mfma_f32_16x16x32_bf16 v[8:11], v[92:95], v[200:203], v[8:11]
	v_mfma_f32_16x16x32_bf16 v[0:3], v[108:111], v[200:203], v[0:3]
	s_setprio 0
	s_barrier
	v_add_u32_e32 v80, s37, v217
	v_add_u32_e32 v108, s26, v217
	ds_read_b128 v[64:67], v80
	ds_read_b128 v[68:71], v80 offset:1024
	ds_read_b128 v[72:75], v80 offset:2048
	ds_read_b128 v[80:83], v80 offset:3072
	ds_read_b128 v[88:91], v108
	ds_read_b128 v[92:95], v108 offset:1024
	ds_read_b128 v[100:103], v108 offset:2048
	ds_read_b128 v[108:111], v108 offset:3072
	s_mov_b32 m0, s15
	v_lshl_add_u64 v[222:223], s[82:83], 0, v[190:191]
	ds_read_b128 v[148:151], v220 offset:32768
	ds_read_b128 v[152:155], v220 offset:33792
	ds_read_b128 v[164:167], v220 offset:34816
	ds_read_b128 v[172:175], v220 offset:35840
	ds_read_b128 v[176:179], v220 offset:36864
	ds_read_b128 v[180:183], v220 offset:37888
	ds_read_b128 v[196:199], v220 offset:38912
	ds_read_b128 v[200:203], v220 offset:39936
	global_load_lds_dwordx4 v[222:223], off
	v_lshl_add_u64 v[222:223], s[82:83], 0, v[186:187]
	s_mov_b32 m0, s18
	s_nop 0
	global_load_lds_dwordx4 v[222:223], off
	s_waitcnt vmcnt(8) lgkmcnt(0)
	s_barrier
	s_setprio 1
	v_mfma_f32_16x16x32_bf16 v[168:171], v[64:67], v[148:151], v[168:171]
	v_mfma_f32_16x16x32_bf16 v[156:159], v[72:75], v[148:151], v[156:159]
	v_mfma_f32_16x16x32_bf16 v[144:147], v[64:67], v[164:167], v[144:147]
	v_mfma_f32_16x16x32_bf16 v[136:139], v[72:75], v[164:167], v[136:139]
	v_mfma_f32_16x16x32_bf16 v[124:127], v[64:67], v[176:179], v[124:127]
	v_mfma_f32_16x16x32_bf16 v[116:119], v[72:75], v[176:179], v[116:119]
	v_mfma_f32_16x16x32_bf16 v[104:107], v[64:67], v[196:199], v[104:107]
	v_mfma_f32_16x16x32_bf16 v[84:87], v[72:75], v[196:199], v[84:87]
	v_mfma_f32_16x16x32_bf16 v[168:171], v[68:71], v[152:155], v[168:171]
	v_mfma_f32_16x16x32_bf16 v[156:159], v[80:83], v[152:155], v[156:159]
	v_mfma_f32_16x16x32_bf16 v[144:147], v[68:71], v[172:175], v[144:147]
	v_mfma_f32_16x16x32_bf16 v[136:139], v[80:83], v[172:175], v[136:139]
	v_mfma_f32_16x16x32_bf16 v[124:127], v[68:71], v[180:183], v[124:127]
	v_mfma_f32_16x16x32_bf16 v[116:119], v[80:83], v[180:183], v[116:119]
	v_mfma_f32_16x16x32_bf16 v[104:107], v[68:71], v[200:203], v[104:107]
	v_mfma_f32_16x16x32_bf16 v[84:87], v[80:83], v[200:203], v[84:87]
	v_mfma_f32_16x16x32_bf16 v[160:163], v[88:91], v[148:151], v[160:163]
	v_mfma_f32_16x16x32_bf16 v[128:131], v[100:103], v[148:151], v[128:131]
	v_mfma_f32_16x16x32_bf16 v[160:163], v[92:95], v[152:155], v[160:163]
	v_mfma_f32_16x16x32_bf16 v[152:155], v[108:111], v[152:155], v[128:131]
	v_mfma_f32_16x16x32_bf16 v[128:131], v[88:91], v[164:167], v[140:143]
	v_mfma_f32_16x16x32_bf16 v[140:143], v[92:95], v[172:175], v[128:131]
	v_mfma_f32_16x16x32_bf16 v[128:131], v[100:103], v[164:167], v[132:135]
	v_mfma_f32_16x16x32_bf16 v[120:123], v[88:91], v[176:179], v[120:123]
	v_mfma_f32_16x16x32_bf16 v[112:115], v[100:103], v[176:179], v[112:115]
	v_mfma_f32_16x16x32_bf16 v[96:99], v[88:91], v[196:199], v[96:99]
	v_mfma_f32_16x16x32_bf16 v[76:79], v[100:103], v[196:199], v[76:79]
	v_mfma_f32_16x16x32_bf16 v[132:135], v[108:111], v[172:175], v[128:131]
	v_mfma_f32_16x16x32_bf16 v[120:123], v[92:95], v[180:183], v[120:123]
	v_mfma_f32_16x16x32_bf16 v[112:115], v[108:111], v[180:183], v[112:115]
	v_mfma_f32_16x16x32_bf16 v[96:99], v[92:95], v[200:203], v[96:99]
	v_mfma_f32_16x16x32_bf16 v[76:79], v[108:111], v[200:203], v[76:79]
	s_setprio 0
	s_barrier
; #define PG8_STAGE(bufoff, gbase, voff) do { _Pragma("unroll") for (int _i = 0; _i < 2; ++_i) \
;         __builtin_amdgcn_global_load_lds((const unsigned*)((const char*)(gbase) + (voff)[_i]), (LAS unsigned*)(lds + (bufoff) + ldsw + _i * 8192), 16, 0, 0); } while (0)
; #define PG8_LDA(dst, b, h) do { _Pragma("unroll") for (int m = 0; m < 4; ++m) _Pragma("unroll") for (int k = 0; k < 2; ++k) dst[m][k] = *(const LAS bf16x8*)(lds + PG8_SA(b, h) + aoff + m * 2048 + k * 1024); } while (0)
; #define PG8_MMA(ai, bj, At, Bt) do { __builtin_amdgcn_s_setprio(1); _Pragma("unroll") for (int m = 0; m < 4; ++m) _Pragma("unroll") for (int n = 0; n < 2; ++n) _Pragma("unroll") for (int k = 0; k < 2; ++k) \
;         acc[ai][bj][m][n] = __builtin_amdgcn_mfma_f32_16x16x32_bf16(Bt[n][k], At[m][k], acc[ai][bj][m][n], 0, 0, 0); __builtin_amdgcn_s_setprio(0); } while (0)
; #define PG8_WAIT_V(n) asm volatile("s_waitcnt vmcnt(" #n ")" ::: "memory")
; #define PG8_WAIT_L(n) asm volatile("s_waitcnt lgkmcnt(" #n ")" ::: "memory")
; #define PG8_BAR __builtin_amdgcn_s_barrier()
; #define PG8_SCHED __builtin_amdgcn_sched_barrier(0)
; template <class Epi, class Sched>
; __device__ __forceinline__ void gemm_phase(LAS unsigned char* lds, const Gemm g, const Sched& S, const Epi& E) {
;     ...
;             PG8_LDA(At, 1, 1); PG8_STAGE(PG8_SB(1, 0), b3, voffB); PG8_STAGE(PG8_SB(1, 1), b3 + hstepB, voffB); PG8_STAGE(PG8_SA(1, 0), a3, voffA);
;             PG8_WAIT_V(8); PG8_WAIT_L(0); PG8_BAR; PG8_MMA(1, 0, At, B0); PG8_MMA(1, 1, At, B1); PG8_BAR; PG8_SCHED;
;         }
;         if (wr == 0) PG8_BAR;
	s_mov_b32 m0, s49
	v_lshl_add_u64 v[204:205], v[204:205], 0, s[58:59]
	ds_read_b128 v[128:131], v220 offset:49152
	ds_read_b128 v[148:151], v220 offset:50176
	ds_read_b128 v[164:167], v220 offset:51200
	ds_read_b128 v[172:175], v220 offset:52224
	ds_read_b128 v[176:179], v220 offset:53248
	ds_read_b128 v[180:183], v220 offset:54272
	ds_read_b128 v[196:199], v220 offset:55296
	ds_read_b128 v[200:203], v220 offset:56320
	global_load_lds_dwordx4 v[204:205], off
	v_lshl_add_u64 v[204:205], v[206:207], 0, s[58:59]
	s_mov_b32 m0, s45
	s_nop 0
	global_load_lds_dwordx4 v[204:205], off
	v_lshl_add_u64 v[204:205], s[80:81], 0, v[188:189]
	s_mov_b32 m0, s48
	s_nop 0
	global_load_lds_dwordx4 v[204:205], off
	v_lshl_add_u64 v[204:205], s[80:81], 0, v[184:185]
	s_mov_b32 m0, s35
	s_nop 0
	global_load_lds_dwordx4 v[204:205], off
	v_lshl_add_u64 v[204:205], v[208:209], 0, s[58:59]
	s_mov_b32 m0, s24
	s_nop 0
	global_load_lds_dwordx4 v[204:205], off
	v_lshl_add_u64 v[204:205], v[210:211], 0, s[58:59]
	s_mov_b32 m0, s25
	s_nop 0
	global_load_lds_dwordx4 v[204:205], off
	s_waitcnt vmcnt(8) lgkmcnt(0)
	s_barrier
	s_setprio 1
	v_mfma_f32_16x16x32_bf16 v[60:63], v[64:67], v[128:131], v[60:63]
	v_mfma_f32_16x16x32_bf16 v[52:55], v[72:75], v[128:131], v[52:55]
	v_mfma_f32_16x16x32_bf16 v[44:47], v[64:67], v[164:167], v[44:47]
	v_mfma_f32_16x16x32_bf16 v[36:39], v[72:75], v[164:167], v[36:39]
	v_mfma_f32_16x16x32_bf16 v[28:31], v[64:67], v[176:179], v[28:31]
	v_mfma_f32_16x16x32_bf16 v[20:23], v[72:75], v[176:179], v[20:23]
	v_mfma_f32_16x16x32_bf16 v[12:15], v[64:67], v[196:199], v[12:15]
	v_mfma_f32_16x16x32_bf16 v[4:7], v[72:75], v[196:199], v[4:7]
	v_mfma_f32_16x16x32_bf16 v[60:63], v[68:71], v[148:151], v[60:63]
	v_mfma_f32_16x16x32_bf16 v[52:55], v[80:83], v[148:151], v[52:55]
	v_mfma_f32_16x16x32_bf16 v[44:47], v[68:71], v[172:175], v[44:47]
	v_mfma_f32_16x16x32_bf16 v[36:39], v[80:83], v[172:175], v[36:39]
	v_mfma_f32_16x16x32_bf16 v[28:31], v[68:71], v[180:183], v[28:31]
	v_mfma_f32_16x16x32_bf16 v[20:23], v[80:83], v[180:183], v[20:23]
	v_mfma_f32_16x16x32_bf16 v[12:15], v[68:71], v[200:203], v[12:15]
	v_mfma_f32_16x16x32_bf16 v[4:7], v[80:83], v[200:203], v[4:7]
	v_mfma_f32_16x16x32_bf16 v[56:59], v[88:91], v[128:131], v[56:59]
	v_mfma_f32_16x16x32_bf16 v[48:51], v[100:103], v[128:131], v[48:51]
	v_mfma_f32_16x16x32_bf16 v[40:43], v[88:91], v[164:167], v[40:43]
	v_mfma_f32_16x16x32_bf16 v[32:35], v[100:103], v[164:167], v[32:35]
	v_mfma_f32_16x16x32_bf16 v[24:27], v[88:91], v[176:179], v[24:27]
	v_mfma_f32_16x16x32_bf16 v[16:19], v[100:103], v[176:179], v[16:19]
	v_mfma_f32_16x16x32_bf16 v[8:11], v[88:91], v[196:199], v[8:11]
	v_mfma_f32_16x16x32_bf16 v[0:3], v[100:103], v[196:199], v[0:3]
	v_mfma_f32_16x16x32_bf16 v[56:59], v[92:95], v[148:151], v[56:59]
	v_mfma_f32_16x16x32_bf16 v[48:51], v[108:111], v[148:151], v[48:51]
	v_mfma_f32_16x16x32_bf16 v[40:43], v[92:95], v[172:175], v[40:43]
	v_mfma_f32_16x16x32_bf16 v[32:35], v[108:111], v[172:175], v[32:35]
	v_mfma_f32_16x16x32_bf16 v[24:27], v[92:95], v[180:183], v[24:27]
	v_mfma_f32_16x16x32_bf16 v[16:19], v[108:111], v[180:183], v[16:19]
	v_mfma_f32_16x16x32_bf16 v[8:11], v[92:95], v[200:203], v[8:11]
	v_mfma_f32_16x16x32_bf16 v[0:3], v[108:111], v[200:203], v[0:3]
	s_setprio 0
	s_barrier
	s_andn2_b64 vcc, exec, s[0:1]
	s_mov_b64 s[80:81], -1
	s_mov_b64 s[0:1], 0
	s_mov_b64 s[82:83], 0x100
	s_cbranch_vccz .LBB0_553
	s_and_b64 vcc, exec, s[60:61]
	s_cbranch_vccz .LBB0_556
	s_barrier

; #define PG8_STAGE(bufoff, gbase, voff) do { _Pragma("unroll") for (int _i = 0; _i < 2; ++_i) \
;         __builtin_amdgcn_global_load_lds((const unsigned*)((const char*)(gbase) + (voff)[_i]), (LAS unsigned*)(lds + (bufoff) + ldsw + _i * 8192), 16, 0, 0); } while (0)
; #define PG8_LDA(dst, b, h) do { _Pragma("unroll") for (int m = 0; m < 4; ++m) _Pragma("unroll") for (int k = 0; k < 2; ++k) dst[m][k] = *(const LAS bf16x8*)(lds + PG8_SA(b, h) + aoff + m * 2048 + k * 1024); } while (0)
; #define PG8_LDB(dst, b, h) do { _Pragma("unroll") for (int n = 0; n < 2; ++n) _Pragma("unroll") for (int k = 0; k < 2; ++k) dst[n][k] = *(const LAS bf16x8*)(lds + PG8_SB(b, h) + boff + n * 2048 + k * 1024); } while (0)
; #define PG8_MMA(ai, bj, At, Bt) do { __builtin_amdgcn_s_setprio(1); _Pragma("unroll") for (int m = 0; m < 4; ++m) _Pragma("unroll") for (int n = 0; n < 2; ++n) _Pragma("unroll") for (int k = 0; k < 2; ++k) \
;         acc[ai][bj][m][n] = __builtin_amdgcn_mfma_f32_16x16x32_bf16(Bt[n][k], At[m][k], acc[ai][bj][m][n], 0, 0, 0); __builtin_amdgcn_s_setprio(0); } while (0)
; #define PG8_WAIT_V(n) asm volatile("s_waitcnt vmcnt(" #n ")" ::: "memory")
; #define PG8_WAIT_L(n) asm volatile("s_waitcnt lgkmcnt(" #n ")" ::: "memory")
; #define PG8_BAR __builtin_amdgcn_s_barrier()
; #define PG8_SCHED __builtin_amdgcn_sched_barrier(0)
; template <class Epi, class Sched>
; __device__ __forceinline__ void gemm_phase(LAS unsigned char* lds, const Gemm g, const Sched& S, const Epi& E) {
;     ...
;             const bool last = (t == nt - 2);
;             const char* a1 = cA + (size_t)(t + 1) * kstep;
;             const char* a2 = last ? nA : cA + (size_t)(t + 2) * kstep; const char* b2 = last ? nB : cB + (size_t)(t + 2) * kstep;
;             const char* a3 = a2 + kstep; const char* b3 = b2 + kstep;
;             PG8_LDB(B0, 0, 0); PG8_LDB(B1, 0, 1); PG8_SCHED; PG8_LDA(At, 0, 0); PG8_STAGE(PG8_SA(1, 1), a1 + hstepA, voffA);
;             PG8_WAIT_V(8); PG8_WAIT_L(0); PG8_BAR; PG8_MMA(0, 0, At, B0); PG8_MMA(0, 1, At, B1); PG8_BAR; PG8_SCHED;
;             PG8_LDA(At, 0, 1); PG8_STAGE(PG8_SB(0, 0), b2, voffB); PG8_STAGE(PG8_SB(0, 1), b2 + hstepB, voffB); PG8_STAGE(PG8_SA(0, 0), a2, voffA);
.LBB0_752:
	v_add_u32_e32 v1, s33, v166
	ds_read_b128 v[152:155], v1
	ds_read_b128 v[156:159], v1 offset:1024
	ds_read_b128 v[160:163], v1 offset:2048
	ds_read_b128 v[168:171], v1 offset:3072
	v_add_u32_e32 v1, s36, v166
	s_add_u32 s64, s60, s62
	ds_read_b128 v[172:175], v1
	ds_read_b128 v[176:179], v1 offset:1024
	ds_read_b128 v[180:183], v1 offset:2048
	ds_read_b128 v[184:187], v1 offset:3072
	s_addc_u32 s65, s61, s63
	s_add_u32 s64, s64, 0x100
	s_addc_u32 s65, s65, 0
	s_add_u32 s75, s72, s62
	s_addc_u32 s76, s73, s63
	s_cmpk_eq_i32 s62, 0x1700
	s_cselect_b32 s67, s1, s65
	s_cselect_b32 s66, s0, s64
	s_cselect_b32 s65, s59, s76
	s_cselect_b32 s64, s58, s75
	v_lshl_add_u64 v[2:3], v[148:149], 0, s[62:63]
	s_add_i32 m0, s13, 0xc000
	ds_read_b128 v[188:191], v167
	ds_read_b128 v[192:195], v167 offset:1024
	ds_read_b128 v[196:199], v167 offset:2048
	ds_read_b128 v[200:203], v167 offset:3072
	ds_read_b128 v[204:207], v167 offset:4096
	ds_read_b128 v[208:211], v167 offset:5120
	ds_read_b128 v[216:219], v167 offset:6144
	ds_read_b128 v[220:223], v167 offset:7168
	global_load_lds_dwordx4 v[2:3], off
	v_lshl_add_u64 v[2:3], v[150:151], 0, s[62:63]
	s_add_i32 m0, s13, 0xe000
	s_nop 0
	global_load_lds_dwordx4 v[2:3], off
	s_waitcnt vmcnt(8) lgkmcnt(0)
	s_barrier
	s_setprio 1
	v_mfma_f32_16x16x32_bf16 v[128:131], v[152:155], v[188:191], v[128:131]
	v_mfma_f32_16x16x32_bf16 v[124:127], v[160:163], v[188:191], v[124:127]
	v_mfma_f32_16x16x32_bf16 v[112:115], v[152:155], v[196:199], v[112:115]
	v_mfma_f32_16x16x32_bf16 v[108:111], v[160:163], v[196:199], v[108:111]
	v_mfma_f32_16x16x32_bf16 v[96:99], v[152:155], v[204:207], v[96:99]
	v_mfma_f32_16x16x32_bf16 v[92:95], v[160:163], v[204:207], v[92:95]
	v_mfma_f32_16x16x32_bf16 v[80:83], v[152:155], v[216:219], v[80:83]
	v_mfma_f32_16x16x32_bf16 v[76:79], v[160:163], v[216:219], v[76:79]
	v_mfma_f32_16x16x32_bf16 v[128:131], v[156:159], v[192:195], v[128:131]
	v_mfma_f32_16x16x32_bf16 v[124:127], v[168:171], v[192:195], v[124:127]
	v_mfma_f32_16x16x32_bf16 v[112:115], v[156:159], v[200:203], v[112:115]
	v_mfma_f32_16x16x32_bf16 v[108:111], v[168:171], v[200:203], v[108:111]
	v_mfma_f32_16x16x32_bf16 v[96:99], v[156:159], v[208:211], v[96:99]
	v_mfma_f32_16x16x32_bf16 v[92:95], v[168:171], v[208:211], v[92:95]
	v_mfma_f32_16x16x32_bf16 v[80:83], v[156:159], v[220:223], v[80:83]
	v_mfma_f32_16x16x32_bf16 v[76:79], v[168:171], v[220:223], v[76:79]
	v_mfma_f32_16x16x32_bf16 v[120:123], v[172:175], v[188:191], v[120:123]
	v_mfma_f32_16x16x32_bf16 v[116:119], v[180:183], v[188:191], v[116:119]
	v_mfma_f32_16x16x32_bf16 v[104:107], v[172:175], v[196:199], v[104:107]
	v_mfma_f32_16x16x32_bf16 v[100:103], v[180:183], v[196:199], v[100:103]
	v_mfma_f32_16x16x32_bf16 v[88:91], v[172:175], v[204:207], v[88:91]
	v_mfma_f32_16x16x32_bf16 v[84:87], v[180:183], v[204:207], v[84:87]
	v_mfma_f32_16x16x32_bf16 v[72:75], v[172:175], v[216:219], v[72:75]
	v_mfma_f32_16x16x32_bf16 v[68:71], v[180:183], v[216:219], v[68:71]
	v_mfma_f32_16x16x32_bf16 v[120:123], v[176:179], v[192:195], v[120:123]
	v_mfma_f32_16x16x32_bf16 v[116:119], v[184:187], v[192:195], v[116:119]
	v_mfma_f32_16x16x32_bf16 v[104:107], v[176:179], v[200:203], v[104:107]
	v_mfma_f32_16x16x32_bf16 v[100:103], v[184:187], v[200:203], v[100:103]
	v_mfma_f32_16x16x32_bf16 v[88:91], v[176:179], v[208:211], v[88:91]
	v_mfma_f32_16x16x32_bf16 v[84:87], v[184:187], v[208:211], v[84:87]
	v_mfma_f32_16x16x32_bf16 v[72:75], v[176:179], v[220:223], v[72:75]
	v_mfma_f32_16x16x32_bf16 v[68:71], v[184:187], v[220:223], v[68:71]
	s_setprio 0
	s_barrier
	s_add_i32 s75, s33, s12
	v_lshl_add_u64 v[224:225], s[64:65], 0, v[136:137]
	s_mov_b32 m0, s75
	ds_read_b128 v[188:191], v167 offset:16384
	ds_read_b128 v[192:195], v167 offset:17408
	ds_read_b128 v[196:199], v167 offset:18432
	ds_read_b128 v[200:203], v167 offset:19456
	ds_read_b128 v[204:207], v167 offset:20480
	ds_read_b128 v[208:211], v167 offset:21504
	ds_read_b128 v[216:219], v167 offset:22528
	ds_read_b128 v[220:223], v167 offset:23552
	global_load_lds_dwordx4 v[224:225], off
	s_add_i32 m0, s75, 0x2000
	s_add_u32 s76, s64, 0xc0000
	v_lshl_add_u64 v[226:227], s[64:65], 0, v[132:133]
	s_addc_u32 s77, s65, 0
	s_add_i32 s75, s36, s12
	global_load_lds_dwordx4 v[226:227], off
	v_lshl_add_u64 v[2:3], s[76:77], 0, v[136:137]
	s_mov_b32 m0, s75
	v_lshl_add_u64 v[228:229], s[66:67], 0, v[138:139]
	global_load_lds_dwordx4 v[2:3], off
	v_lshl_add_u64 v[2:3], s[76:77], 0, v[132:133]
	s_add_i32 m0, s75, 0x2000
	v_lshl_add_u64 v[230:231], s[66:67], 0, v[134:135]
	global_load_lds_dwordx4 v[2:3], off
	s_mov_b32 m0, s13
	s_nop 0
	global_load_lds_dwordx4 v[228:229], off
	s_mov_b32 m0, s14
	s_nop 0
	global_load_lds_dwordx4 v[230:231], off
	s_waitcnt vmcnt(8) lgkmcnt(0)
	s_barrier
; #define PG8_STAGE(bufoff, gbase, voff) do { _Pragma("unroll") for (int _i = 0; _i < 2; ++_i) \
;         __builtin_amdgcn_global_load_lds((const unsigned*)((const char*)(gbase) + (voff)[_i]), (LAS unsigned*)(lds + (bufoff) + ldsw + _i * 8192), 16, 0, 0); } while (0)
; #define PG8_LDA(dst, b, h) do { _Pragma("unroll") for (int m = 0; m < 4; ++m) _Pragma("unroll") for (int k = 0; k < 2; ++k) dst[m][k] = *(const LAS bf16x8*)(lds + PG8_SA(b, h) + aoff + m * 2048 + k * 1024); } while (0)
; #define PG8_LDB(dst, b, h) do { _Pragma("unroll") for (int n = 0; n < 2; ++n) _Pragma("unroll") for (int k = 0; k < 2; ++k) dst[n][k] = *(const LAS bf16x8*)(lds + PG8_SB(b, h) + boff + n * 2048 + k * 1024); } while (0)
; #define PG8_MMA(ai, bj, At, Bt) do { __builtin_amdgcn_s_setprio(1); _Pragma("unroll") for (int m = 0; m < 4; ++m) _Pragma("unroll") for (int n = 0; n < 2; ++n) _Pragma("unroll") for (int k = 0; k < 2; ++k) \
;         acc[ai][bj][m][n] = __builtin_amdgcn_mfma_f32_16x16x32_bf16(Bt[n][k], At[m][k], acc[ai][bj][m][n], 0, 0, 0); __builtin_amdgcn_s_setprio(0); } while (0)
; #define PG8_WAIT_V(n) asm volatile("s_waitcnt vmcnt(" #n ")" ::: "memory")
; #define PG8_WAIT_L(n) asm volatile("s_waitcnt lgkmcnt(" #n ")" ::: "memory")
; #define PG8_BAR __builtin_amdgcn_s_barrier()
; #define PG8_SCHED __builtin_amdgcn_sched_barrier(0)
; template <class Epi, class Sched>
; __device__ __forceinline__ void gemm_phase(LAS unsigned char* lds, const Gemm g, const Sched& S, const Epi& E) {
;     ...
;             PG8_WAIT_V(8); PG8_WAIT_L(0); PG8_BAR; PG8_MMA(1, 0, At, B0); PG8_MMA(1, 1, At, B1); PG8_BAR; PG8_SCHED;
;             PG8_LDB(B0, 1, 0); PG8_LDB(B1, 1, 1); PG8_SCHED; PG8_LDA(At, 1, 0); PG8_STAGE(PG8_SA(0, 1), a2 + hstepA, voffA);
;             PG8_WAIT_V(8); PG8_WAIT_L(0); PG8_BAR; PG8_MMA(0, 0, At, B0); PG8_MMA(0, 1, At, B1); PG8_BAR; PG8_SCHED;
	s_setprio 1
	v_mfma_f32_16x16x32_bf16 v[64:67], v[152:155], v[188:191], v[64:67]
	v_mfma_f32_16x16x32_bf16 v[60:63], v[160:163], v[188:191], v[60:63]
	v_mfma_f32_16x16x32_bf16 v[48:51], v[152:155], v[196:199], v[48:51]
	v_mfma_f32_16x16x32_bf16 v[44:47], v[160:163], v[196:199], v[44:47]
	v_mfma_f32_16x16x32_bf16 v[32:35], v[152:155], v[204:207], v[32:35]
	v_mfma_f32_16x16x32_bf16 v[28:31], v[160:163], v[204:207], v[28:31]
	v_mfma_f32_16x16x32_bf16 v[16:19], v[152:155], v[216:219], v[16:19]
	v_mfma_f32_16x16x32_bf16 v[12:15], v[160:163], v[216:219], v[12:15]
	v_mfma_f32_16x16x32_bf16 v[64:67], v[156:159], v[192:195], v[64:67]
	v_mfma_f32_16x16x32_bf16 v[60:63], v[168:171], v[192:195], v[60:63]
	v_mfma_f32_16x16x32_bf16 v[48:51], v[156:159], v[200:203], v[48:51]
	v_mfma_f32_16x16x32_bf16 v[44:47], v[168:171], v[200:203], v[44:47]
	v_mfma_f32_16x16x32_bf16 v[32:35], v[156:159], v[208:211], v[32:35]
	v_mfma_f32_16x16x32_bf16 v[28:31], v[168:171], v[208:211], v[28:31]
	v_mfma_f32_16x16x32_bf16 v[16:19], v[156:159], v[220:223], v[16:19]
	v_mfma_f32_16x16x32_bf16 v[12:15], v[168:171], v[220:223], v[12:15]
	v_mfma_f32_16x16x32_bf16 v[56:59], v[172:175], v[188:191], v[56:59]
	v_mfma_f32_16x16x32_bf16 v[52:55], v[180:183], v[188:191], v[52:55]
	v_mfma_f32_16x16x32_bf16 v[40:43], v[172:175], v[196:199], v[40:43]
	v_mfma_f32_16x16x32_bf16 v[36:39], v[180:183], v[196:199], v[36:39]
	v_mfma_f32_16x16x32_bf16 v[24:27], v[172:175], v[204:207], v[24:27]
	v_mfma_f32_16x16x32_bf16 v[20:23], v[180:183], v[204:207], v[20:23]
	v_mfma_f32_16x16x32_bf16 v[8:11], v[172:175], v[216:219], v[8:11]
	v_mfma_f32_16x16x32_bf16 v[2:5], v[180:183], v[216:219], v[4:7]
	v_mfma_f32_16x16x32_bf16 v[56:59], v[176:179], v[192:195], v[56:59]
	v_mfma_f32_16x16x32_bf16 v[52:55], v[184:187], v[192:195], v[52:55]
	v_mfma_f32_16x16x32_bf16 v[40:43], v[176:179], v[200:203], v[40:43]
	v_mfma_f32_16x16x32_bf16 v[36:39], v[184:187], v[200:203], v[36:39]
	v_mfma_f32_16x16x32_bf16 v[24:27], v[176:179], v[208:211], v[24:27]
	v_mfma_f32_16x16x32_bf16 v[20:23], v[184:187], v[208:211], v[20:23]
	v_mfma_f32_16x16x32_bf16 v[8:11], v[176:179], v[220:223], v[8:11]
	v_mfma_f32_16x16x32_bf16 v[2:5], v[184:187], v[220:223], v[2:5]
	s_setprio 0
	s_barrier
	v_add_u32_e32 v1, s37, v166
	ds_read_b128 v[152:155], v1
	ds_read_b128 v[156:159], v1 offset:1024
	ds_read_b128 v[160:163], v1 offset:2048
	ds_read_b128 v[168:171], v1 offset:3072
	v_add_u32_e32 v1, s26, v166
	ds_read_b128 v[172:175], v1
	ds_read_b128 v[176:179], v1 offset:1024
	ds_read_b128 v[180:183], v1 offset:2048
	ds_read_b128 v[184:187], v1 offset:3072
	s_add_u32 s66, s66, 0xc0000
	s_addc_u32 s67, s67, 0
	s_mov_b32 m0, s15
	v_lshl_add_u64 v[6:7], s[66:67], 0, v[138:139]
	ds_read_b128 v[188:191], v167 offset:32768
	ds_read_b128 v[192:195], v167 offset:33792
	ds_read_b128 v[196:199], v167 offset:34816
	ds_read_b128 v[200:203], v167 offset:35840
	ds_read_b128 v[204:207], v167 offset:36864
	ds_read_b128 v[208:211], v167 offset:37888
	ds_read_b128 v[216:219], v167 offset:38912
	ds_read_b128 v[220:223], v167 offset:39936
	global_load_lds_dwordx4 v[6:7], off
	v_lshl_add_u64 v[6:7], s[66:67], 0, v[134:135]
	s_mov_b32 m0, s19
	s_nop 0
	global_load_lds_dwordx4 v[6:7], off
	s_waitcnt vmcnt(8) lgkmcnt(0)
	s_barrier
	s_setprio 1
	v_mfma_f32_16x16x32_bf16 v[128:131], v[152:155], v[188:191], v[128:131]
	v_mfma_f32_16x16x32_bf16 v[124:127], v[160:163], v[188:191], v[124:127]
	v_mfma_f32_16x16x32_bf16 v[112:115], v[152:155], v[196:199], v[112:115]
	v_mfma_f32_16x16x32_bf16 v[108:111], v[160:163], v[196:199], v[108:111]
	v_mfma_f32_16x16x32_bf16 v[96:99], v[152:155], v[204:207], v[96:99]
	v_mfma_f32_16x16x32_bf16 v[92:95], v[160:163], v[204:207], v[92:95]
	v_mfma_f32_16x16x32_bf16 v[80:83], v[152:155], v[216:219], v[80:83]
	v_mfma_f32_16x16x32_bf16 v[76:79], v[160:163], v[216:219], v[76:79]
	v_mfma_f32_16x16x32_bf16 v[128:131], v[156:159], v[192:195], v[128:131]
	v_mfma_f32_16x16x32_bf16 v[124:127], v[168:171], v[192:195], v[124:127]
	v_mfma_f32_16x16x32_bf16 v[112:115], v[156:159], v[200:203], v[112:115]
	v_mfma_f32_16x16x32_bf16 v[108:111], v[168:171], v[200:203], v[108:111]
	v_mfma_f32_16x16x32_bf16 v[96:99], v[156:159], v[208:211], v[96:99]
	v_mfma_f32_16x16x32_bf16 v[92:95], v[168:171], v[208:211], v[92:95]
	v_mfma_f32_16x16x32_bf16 v[80:83], v[156:159], v[220:223], v[80:83]
	v_mfma_f32_16x16x32_bf16 v[76:79], v[168:171], v[220:223], v[76:79]
	v_mfma_f32_16x16x32_bf16 v[120:123], v[172:175], v[188:191], v[120:123]
	v_mfma_f32_16x16x32_bf16 v[116:119], v[180:183], v[188:191], v[116:119]
	v_mfma_f32_16x16x32_bf16 v[104:107], v[172:175], v[196:199], v[104:107]
	v_mfma_f32_16x16x32_bf16 v[100:103], v[180:183], v[196:199], v[100:103]
	v_mfma_f32_16x16x32_bf16 v[88:91], v[172:175], v[204:207], v[88:91]
	v_mfma_f32_16x16x32_bf16 v[84:87], v[180:183], v[204:207], v[84:87]
	v_mfma_f32_16x16x32_bf16 v[72:75], v[172:175], v[216:219], v[72:75]
	v_mfma_f32_16x16x32_bf16 v[68:71], v[180:183], v[216:219], v[68:71]
	v_mfma_f32_16x16x32_bf16 v[120:123], v[176:179], v[192:195], v[120:123]
	v_mfma_f32_16x16x32_bf16 v[116:119], v[184:187], v[192:195], v[116:119]
	v_mfma_f32_16x16x32_bf16 v[104:107], v[176:179], v[200:203], v[104:107]
	v_mfma_f32_16x16x32_bf16 v[100:103], v[184:187], v[200:203], v[100:103]
	v_mfma_f32_16x16x32_bf16 v[88:91], v[176:179], v[208:211], v[88:91]
	v_mfma_f32_16x16x32_bf16 v[84:87], v[184:187], v[208:211], v[84:87]
	v_mfma_f32_16x16x32_bf16 v[72:75], v[176:179], v[220:223], v[72:75]
	v_mfma_f32_16x16x32_bf16 v[68:71], v[184:187], v[220:223], v[68:71]
	s_setprio 0
	s_barrier
; #define PG8_STAGE(bufoff, gbase, voff) do { _Pragma("unroll") for (int _i = 0; _i < 2; ++_i) \
;         __builtin_amdgcn_global_load_lds((const unsigned*)((const char*)(gbase) + (voff)[_i]), (LAS unsigned*)(lds + (bufoff) + ldsw + _i * 8192), 16, 0, 0); } while (0)
; #define PG8_LDA(dst, b, h) do { _Pragma("unroll") for (int m = 0; m < 4; ++m) _Pragma("unroll") for (int k = 0; k < 2; ++k) dst[m][k] = *(const LAS bf16x8*)(lds + PG8_SA(b, h) + aoff + m * 2048 + k * 1024); } while (0)
; #define PG8_MMA(ai, bj, At, Bt) do { __builtin_amdgcn_s_setprio(1); _Pragma("unroll") for (int m = 0; m < 4; ++m) _Pragma("unroll") for (int n = 0; n < 2; ++n) _Pragma("unroll") for (int k = 0; k < 2; ++k) \
;         acc[ai][bj][m][n] = __builtin_amdgcn_mfma_f32_16x16x32_bf16(Bt[n][k], At[m][k], acc[ai][bj][m][n], 0, 0, 0); __builtin_amdgcn_s_setprio(0); } while (0)
; #define PG8_WAIT_V(n) asm volatile("s_waitcnt vmcnt(" #n ")" ::: "memory")
; #define PG8_WAIT_L(n) asm volatile("s_waitcnt lgkmcnt(" #n ")" ::: "memory")
; #define PG8_BAR __builtin_amdgcn_s_barrier()
; #define PG8_SCHED __builtin_amdgcn_sched_barrier(0)
; template <class Epi, class Sched>
; __device__ __forceinline__ void gemm_phase(LAS unsigned char* lds, const Gemm g, const Sched& S, const Epi& E) {
;     ...
;             PG8_LDA(At, 1, 1); PG8_STAGE(PG8_SB(1, 0), b3, voffB); PG8_STAGE(PG8_SB(1, 1), b3 + hstepB, voffB); PG8_STAGE(PG8_SA(1, 0), a3, voffA);
;             PG8_WAIT_V(8); PG8_WAIT_L(0); PG8_BAR; PG8_MMA(1, 0, At, B0); PG8_MMA(1, 1, At, B1); PG8_BAR; PG8_SCHED;
;         }
;         if (wr == 0) PG8_BAR;
	s_add_i32 s66, s37, s12
	v_lshl_add_u64 v[6:7], v[224:225], 0, s[42:43]
	s_mov_b32 m0, s66
	ds_read_b128 v[188:191], v167 offset:49152
	ds_read_b128 v[192:195], v167 offset:50176
	ds_read_b128 v[196:199], v167 offset:51200
	ds_read_b128 v[200:203], v167 offset:52224
	ds_read_b128 v[204:207], v167 offset:53248
	ds_read_b128 v[208:211], v167 offset:54272
	ds_read_b128 v[216:219], v167 offset:55296
	ds_read_b128 v[220:223], v167 offset:56320
	global_load_lds_dwordx4 v[6:7], off
	s_add_i32 m0, s66, 0x2000
	s_add_u32 s64, s64, 0xc0080
	v_lshl_add_u64 v[6:7], v[226:227], 0, s[42:43]
	s_addc_u32 s65, s65, 0
	s_add_i32 s66, s26, s12
	global_load_lds_dwordx4 v[6:7], off
	v_lshl_add_u64 v[6:7], s[64:65], 0, v[136:137]
	s_mov_b32 m0, s66
	s_nop 0
	global_load_lds_dwordx4 v[6:7], off
	v_lshl_add_u64 v[6:7], s[64:65], 0, v[132:133]
	s_add_i32 m0, s66, 0x2000
	s_nop 0
	global_load_lds_dwordx4 v[6:7], off
	v_lshl_add_u64 v[6:7], v[228:229], 0, s[42:43]
	s_mov_b32 m0, s23
	s_nop 0
	global_load_lds_dwordx4 v[6:7], off
	v_lshl_add_u64 v[6:7], v[230:231], 0, s[42:43]
	s_mov_b32 m0, s24
	s_nop 0
	global_load_lds_dwordx4 v[6:7], off
	s_waitcnt vmcnt(8) lgkmcnt(0)
	s_barrier
	s_setprio 1
	v_mfma_f32_16x16x32_bf16 v[64:67], v[152:155], v[188:191], v[64:67]
	v_mfma_f32_16x16x32_bf16 v[60:63], v[160:163], v[188:191], v[60:63]
	v_mfma_f32_16x16x32_bf16 v[48:51], v[152:155], v[196:199], v[48:51]
	v_mfma_f32_16x16x32_bf16 v[44:47], v[160:163], v[196:199], v[44:47]
	v_mfma_f32_16x16x32_bf16 v[32:35], v[152:155], v[204:207], v[32:35]
	v_mfma_f32_16x16x32_bf16 v[28:31], v[160:163], v[204:207], v[28:31]
	v_mfma_f32_16x16x32_bf16 v[16:19], v[152:155], v[216:219], v[16:19]
	v_mfma_f32_16x16x32_bf16 v[12:15], v[160:163], v[216:219], v[12:15]
	v_mfma_f32_16x16x32_bf16 v[64:67], v[156:159], v[192:195], v[64:67]
	v_mfma_f32_16x16x32_bf16 v[60:63], v[168:171], v[192:195], v[60:63]
	v_mfma_f32_16x16x32_bf16 v[48:51], v[156:159], v[200:203], v[48:51]
	v_mfma_f32_16x16x32_bf16 v[44:47], v[168:171], v[200:203], v[44:47]
	v_mfma_f32_16x16x32_bf16 v[32:35], v[156:159], v[208:211], v[32:35]
	v_mfma_f32_16x16x32_bf16 v[28:31], v[168:171], v[208:211], v[28:31]
	v_mfma_f32_16x16x32_bf16 v[16:19], v[156:159], v[220:223], v[16:19]
	v_mfma_f32_16x16x32_bf16 v[12:15], v[168:171], v[220:223], v[12:15]
	v_mfma_f32_16x16x32_bf16 v[56:59], v[172:175], v[188:191], v[56:59]
	v_mfma_f32_16x16x32_bf16 v[52:55], v[180:183], v[188:191], v[52:55]
	v_mfma_f32_16x16x32_bf16 v[40:43], v[172:175], v[196:199], v[40:43]
	v_mfma_f32_16x16x32_bf16 v[36:39], v[180:183], v[196:199], v[36:39]
	v_mfma_f32_16x16x32_bf16 v[24:27], v[172:175], v[204:207], v[24:27]
	v_mfma_f32_16x16x32_bf16 v[20:23], v[180:183], v[204:207], v[20:23]
	v_mfma_f32_16x16x32_bf16 v[6:9], v[172:175], v[216:219], v[8:11]
	v_mfma_f32_16x16x32_bf16 v[2:5], v[180:183], v[216:219], v[2:5]
	v_mfma_f32_16x16x32_bf16 v[56:59], v[176:179], v[192:195], v[56:59]
	v_mfma_f32_16x16x32_bf16 v[52:55], v[184:187], v[192:195], v[52:55]
	v_mfma_f32_16x16x32_bf16 v[40:43], v[176:179], v[200:203], v[40:43]
	v_mfma_f32_16x16x32_bf16 v[36:39], v[184:187], v[200:203], v[36:39]
	v_mfma_f32_16x16x32_bf16 v[24:27], v[176:179], v[208:211], v[24:27]
	v_mfma_f32_16x16x32_bf16 v[20:23], v[184:187], v[208:211], v[20:23]
	v_mfma_f32_16x16x32_bf16 v[8:11], v[176:179], v[220:223], v[6:9]
	v_mfma_f32_16x16x32_bf16 v[4:7], v[184:187], v[220:223], v[2:5]
	s_setprio 0
	s_barrier
	s_add_i32 s74, s74, 2
	s_add_u32 s62, s62, 0x100
	s_addc_u32 s63, s63, 0
	s_cmp_gt_u32 s74, 45
	s_cbranch_scc1 .LBB0_755

; #define PG8_STAGE(bufoff, gbase, voff) do { _Pragma("unroll") for (int _i = 0; _i < 2; ++_i) \
;         __builtin_amdgcn_global_load_lds((const unsigned*)((const char*)(gbase) + (voff)[_i]), (LAS unsigned*)(lds + (bufoff) + ldsw + _i * 8192), 16, 0, 0); } while (0)
; #define PG8_LDA(dst, b, h) do { _Pragma("unroll") for (int m = 0; m < 4; ++m) _Pragma("unroll") for (int k = 0; k < 2; ++k) dst[m][k] = *(const LAS bf16x8*)(lds + PG8_SA(b, h) + aoff + m * 2048 + k * 1024); } while (0)
; #define PG8_LDB(dst, b, h) do { _Pragma("unroll") for (int n = 0; n < 2; ++n) _Pragma("unroll") for (int k = 0; k < 2; ++k) dst[n][k] = *(const LAS bf16x8*)(lds + PG8_SB(b, h) + boff + n * 2048 + k * 1024); } while (0)
; #define PG8_MMA(ai, bj, At, Bt) do { __builtin_amdgcn_s_setprio(1); _Pragma("unroll") for (int m = 0; m < 4; ++m) _Pragma("unroll") for (int n = 0; n < 2; ++n) _Pragma("unroll") for (int k = 0; k < 2; ++k) \
;         acc[ai][bj][m][n] = __builtin_amdgcn_mfma_f32_16x16x32_bf16(Bt[n][k], At[m][k], acc[ai][bj][m][n], 0, 0, 0); __builtin_amdgcn_s_setprio(0); } while (0)
; #define PG8_WAIT_V(n) asm volatile("s_waitcnt vmcnt(" #n ")" ::: "memory")
; #define PG8_WAIT_L(n) asm volatile("s_waitcnt lgkmcnt(" #n ")" ::: "memory")
; #define PG8_BAR __builtin_amdgcn_s_barrier()
; #define PG8_SCHED __builtin_amdgcn_sched_barrier(0)
; template <class Epi, class Sched>
; __device__ __forceinline__ void gemm_phase(LAS unsigned char* lds, const Gemm g, const Sched& S, const Epi& E) {
;     ...
;             const bool last = (t == nt - 2);
;             const char* a1 = cA + (size_t)(t + 1) * kstep;
;             const char* a2 = last ? nA : cA + (size_t)(t + 2) * kstep; const char* b2 = last ? nB : cB + (size_t)(t + 2) * kstep;
;             const char* a3 = a2 + kstep; const char* b3 = b2 + kstep;
;             PG8_LDB(B0, 0, 0); PG8_LDB(B1, 0, 1); PG8_SCHED; PG8_LDA(At, 0, 0); PG8_STAGE(PG8_SA(1, 1), a1 + hstepA, voffA);
;             PG8_WAIT_V(8); PG8_WAIT_L(0); PG8_BAR; PG8_MMA(0, 0, At, B0); PG8_MMA(0, 1, At, B1); PG8_BAR; PG8_SCHED;
;             PG8_LDA(At, 0, 1); PG8_STAGE(PG8_SB(0, 0), b2, voffB); PG8_STAGE(PG8_SB(0, 1), b2 + hstepB, voffB); PG8_STAGE(PG8_SA(0, 0), a2, voffA);
.LBB0_829:
	ds_read_b128 v[128:131], v167
	ds_read_b128 v[132:135], v167 offset:1024
	ds_read_b128 v[170:173], v167 offset:2048
	ds_read_b128 v[176:179], v167 offset:3072
	ds_read_b128 v[180:183], v169
	ds_read_b128 v[184:187], v169 offset:1024
	ds_read_b128 v[188:191], v169 offset:2048
	ds_read_b128 v[192:195], v169 offset:3072
	s_add_u32 s39, s60, 0xfff80080
	s_addc_u32 s43, s61, -1
	s_cmp_eq_u32 s35, 28
	s_cselect_b32 s65, s12, s43
	s_cselect_b32 s64, s13, s39
	s_cselect_b32 s63, s29, s34
	s_cselect_b32 s62, s30, s31
	v_lshl_add_u64 v[152:153], s[60:61], 0, v[144:145]
	s_add_i32 m0, s18, 0xc000
	ds_read_b128 v[196:199], v175
	ds_read_b128 v[200:203], v175 offset:1024
	ds_read_b128 v[204:207], v175 offset:2048
	ds_read_b128 v[208:211], v175 offset:3072
	ds_read_b128 v[216:219], v175 offset:4096
	ds_read_b128 v[220:223], v175 offset:5120
	ds_read_b128 v[224:227], v175 offset:6144
	ds_read_b128 v[228:231], v175 offset:7168
	global_load_lds_dwordx4 v[152:153], off
	v_lshl_add_u64 v[152:153], s[60:61], 0, v[146:147]
	s_add_i32 m0, s18, 0xe000
	s_nop 0
	global_load_lds_dwordx4 v[152:153], off
	s_waitcnt vmcnt(8) lgkmcnt(0)
	s_barrier
	s_setprio 1
	v_mfma_f32_16x16x32_bf16 v[124:127], v[128:131], v[196:199], v[124:127]
	v_mfma_f32_16x16x32_bf16 v[120:123], v[170:173], v[196:199], v[120:123]
	v_mfma_f32_16x16x32_bf16 v[108:111], v[128:131], v[204:207], v[108:111]
	v_mfma_f32_16x16x32_bf16 v[104:107], v[170:173], v[204:207], v[104:107]
	v_mfma_f32_16x16x32_bf16 v[92:95], v[128:131], v[216:219], v[92:95]
	v_mfma_f32_16x16x32_bf16 v[88:91], v[170:173], v[216:219], v[88:91]
	v_mfma_f32_16x16x32_bf16 v[76:79], v[128:131], v[224:227], v[76:79]
	v_mfma_f32_16x16x32_bf16 v[72:75], v[170:173], v[224:227], v[72:75]
	v_mfma_f32_16x16x32_bf16 v[124:127], v[132:135], v[200:203], v[124:127]
	v_mfma_f32_16x16x32_bf16 v[120:123], v[176:179], v[200:203], v[120:123]
	v_mfma_f32_16x16x32_bf16 v[108:111], v[132:135], v[208:211], v[108:111]
	v_mfma_f32_16x16x32_bf16 v[104:107], v[176:179], v[208:211], v[104:107]
	v_mfma_f32_16x16x32_bf16 v[92:95], v[132:135], v[220:223], v[92:95]
	v_mfma_f32_16x16x32_bf16 v[88:91], v[176:179], v[220:223], v[88:91]
	v_mfma_f32_16x16x32_bf16 v[76:79], v[132:135], v[228:231], v[76:79]
	v_mfma_f32_16x16x32_bf16 v[72:75], v[176:179], v[228:231], v[72:75]
	v_mfma_f32_16x16x32_bf16 v[116:119], v[180:183], v[196:199], v[116:119]
	v_mfma_f32_16x16x32_bf16 v[112:115], v[188:191], v[196:199], v[112:115]
	v_mfma_f32_16x16x32_bf16 v[100:103], v[180:183], v[204:207], v[100:103]
	v_mfma_f32_16x16x32_bf16 v[96:99], v[188:191], v[204:207], v[96:99]
	v_mfma_f32_16x16x32_bf16 v[84:87], v[180:183], v[216:219], v[84:87]
	v_mfma_f32_16x16x32_bf16 v[80:83], v[188:191], v[216:219], v[80:83]
	v_mfma_f32_16x16x32_bf16 v[68:71], v[180:183], v[224:227], v[68:71]
	v_mfma_f32_16x16x32_bf16 v[64:67], v[188:191], v[224:227], v[64:67]
	v_mfma_f32_16x16x32_bf16 v[116:119], v[184:187], v[200:203], v[116:119]
	v_mfma_f32_16x16x32_bf16 v[112:115], v[192:195], v[200:203], v[112:115]
	v_mfma_f32_16x16x32_bf16 v[100:103], v[184:187], v[208:211], v[100:103]
	v_mfma_f32_16x16x32_bf16 v[96:99], v[192:195], v[208:211], v[96:99]
	v_mfma_f32_16x16x32_bf16 v[84:87], v[184:187], v[220:223], v[84:87]
	v_mfma_f32_16x16x32_bf16 v[80:83], v[192:195], v[220:223], v[80:83]
	v_mfma_f32_16x16x32_bf16 v[68:71], v[184:187], v[228:231], v[68:71]
	v_mfma_f32_16x16x32_bf16 v[64:67], v[192:195], v[228:231], v[64:67]
	s_setprio 0
	s_barrier
	s_add_i32 s39, s33, s15
	v_lshl_add_u64 v[152:153], s[62:63], 0, v[138:139]
	s_mov_b32 m0, s39
	ds_read_b128 v[196:199], v175 offset:16384
	ds_read_b128 v[200:203], v175 offset:17408
	ds_read_b128 v[204:207], v175 offset:18432
	ds_read_b128 v[208:211], v175 offset:19456
	ds_read_b128 v[216:219], v175 offset:20480
	ds_read_b128 v[220:223], v175 offset:21504
	ds_read_b128 v[224:227], v175 offset:22528
	ds_read_b128 v[228:231], v175 offset:23552
	global_load_lds_dwordx4 v[152:153], off
	s_add_i32 m0, s39, 0x2000
	s_add_u32 s48, s62, 0x80000
	v_lshl_add_u64 v[156:157], s[62:63], 0, v[142:143]
	s_addc_u32 s49, s63, 0
	s_add_i32 s39, s36, s15
	global_load_lds_dwordx4 v[156:157], off
	v_lshl_add_u64 v[160:161], s[48:49], 0, v[138:139]
	s_mov_b32 m0, s39
	v_lshl_add_u64 v[232:233], s[64:65], 0, v[140:141]
	global_load_lds_dwordx4 v[160:161], off
	v_lshl_add_u64 v[160:161], s[48:49], 0, v[142:143]
	s_add_i32 m0, s39, 0x2000
	s_nop 0
	global_load_lds_dwordx4 v[160:161], off
	v_lshl_add_u64 v[160:161], s[64:65], 0, v[136:137]
	s_mov_b32 m0, s18
	s_nop 0
	global_load_lds_dwordx4 v[160:161], off
	s_mov_b32 m0, s19
	s_nop 0
	global_load_lds_dwordx4 v[232:233], off
	s_waitcnt vmcnt(8) lgkmcnt(0)
	s_barrier
; #define PG8_STAGE(bufoff, gbase, voff) do { _Pragma("unroll") for (int _i = 0; _i < 2; ++_i) \
;         __builtin_amdgcn_global_load_lds((const unsigned*)((const char*)(gbase) + (voff)[_i]), (LAS unsigned*)(lds + (bufoff) + ldsw + _i * 8192), 16, 0, 0); } while (0)
; #define PG8_LDA(dst, b, h) do { _Pragma("unroll") for (int m = 0; m < 4; ++m) _Pragma("unroll") for (int k = 0; k < 2; ++k) dst[m][k] = *(const LAS bf16x8*)(lds + PG8_SA(b, h) + aoff + m * 2048 + k * 1024); } while (0)
; #define PG8_LDB(dst, b, h) do { _Pragma("unroll") for (int n = 0; n < 2; ++n) _Pragma("unroll") for (int k = 0; k < 2; ++k) dst[n][k] = *(const LAS bf16x8*)(lds + PG8_SB(b, h) + boff + n * 2048 + k * 1024); } while (0)
; #define PG8_MMA(ai, bj, At, Bt) do { __builtin_amdgcn_s_setprio(1); _Pragma("unroll") for (int m = 0; m < 4; ++m) _Pragma("unroll") for (int n = 0; n < 2; ++n) _Pragma("unroll") for (int k = 0; k < 2; ++k) \
;         acc[ai][bj][m][n] = __builtin_amdgcn_mfma_f32_16x16x32_bf16(Bt[n][k], At[m][k], acc[ai][bj][m][n], 0, 0, 0); __builtin_amdgcn_s_setprio(0); } while (0)
; #define PG8_WAIT_V(n) asm volatile("s_waitcnt vmcnt(" #n ")" ::: "memory")
; #define PG8_WAIT_L(n) asm volatile("s_waitcnt lgkmcnt(" #n ")" ::: "memory")
; #define PG8_BAR __builtin_amdgcn_s_barrier()
; #define PG8_SCHED __builtin_amdgcn_sched_barrier(0)
; template <class Epi, class Sched>
; __device__ __forceinline__ void gemm_phase(LAS unsigned char* lds, const Gemm g, const Sched& S, const Epi& E) {
;     ...
;             PG8_WAIT_V(8); PG8_WAIT_L(0); PG8_BAR; PG8_MMA(1, 0, At, B0); PG8_MMA(1, 1, At, B1); PG8_BAR; PG8_SCHED;
;             PG8_LDB(B0, 1, 0); PG8_LDB(B1, 1, 1); PG8_SCHED; PG8_LDA(At, 1, 0); PG8_STAGE(PG8_SA(0, 1), a2 + hstepA, voffA);
;             PG8_WAIT_V(8); PG8_WAIT_L(0); PG8_BAR; PG8_MMA(0, 0, At, B0); PG8_MMA(0, 1, At, B1); PG8_BAR; PG8_SCHED;
	s_setprio 1
	v_mfma_f32_16x16x32_bf16 v[60:63], v[128:131], v[196:199], v[60:63]
	v_mfma_f32_16x16x32_bf16 v[56:59], v[170:173], v[196:199], v[56:59]
	v_mfma_f32_16x16x32_bf16 v[44:47], v[128:131], v[204:207], v[44:47]
	v_mfma_f32_16x16x32_bf16 v[40:43], v[170:173], v[204:207], v[40:43]
	v_mfma_f32_16x16x32_bf16 v[28:31], v[128:131], v[216:219], v[28:31]
	v_mfma_f32_16x16x32_bf16 v[24:27], v[170:173], v[216:219], v[24:27]
	v_mfma_f32_16x16x32_bf16 v[12:15], v[128:131], v[224:227], v[12:15]
	v_mfma_f32_16x16x32_bf16 v[8:11], v[170:173], v[224:227], v[8:11]
	v_mfma_f32_16x16x32_bf16 v[60:63], v[132:135], v[200:203], v[60:63]
	v_mfma_f32_16x16x32_bf16 v[56:59], v[176:179], v[200:203], v[56:59]
	v_mfma_f32_16x16x32_bf16 v[44:47], v[132:135], v[208:211], v[44:47]
	v_mfma_f32_16x16x32_bf16 v[40:43], v[176:179], v[208:211], v[40:43]
	v_mfma_f32_16x16x32_bf16 v[28:31], v[132:135], v[220:223], v[28:31]
	v_mfma_f32_16x16x32_bf16 v[24:27], v[176:179], v[220:223], v[24:27]
	v_mfma_f32_16x16x32_bf16 v[12:15], v[132:135], v[228:231], v[12:15]
	v_mfma_f32_16x16x32_bf16 v[8:11], v[176:179], v[228:231], v[8:11]
	v_mfma_f32_16x16x32_bf16 v[52:55], v[180:183], v[196:199], v[52:55]
	v_mfma_f32_16x16x32_bf16 v[48:51], v[188:191], v[196:199], v[48:51]
	v_mfma_f32_16x16x32_bf16 v[36:39], v[180:183], v[204:207], v[36:39]
	v_mfma_f32_16x16x32_bf16 v[32:35], v[188:191], v[204:207], v[32:35]
	v_mfma_f32_16x16x32_bf16 v[20:23], v[180:183], v[216:219], v[20:23]
	v_mfma_f32_16x16x32_bf16 v[16:19], v[188:191], v[216:219], v[16:19]
	v_mfma_f32_16x16x32_bf16 v[4:7], v[180:183], v[224:227], v[4:7]
	v_mfma_f32_16x16x32_bf16 v[0:3], v[188:191], v[224:227], v[0:3]
	v_mfma_f32_16x16x32_bf16 v[52:55], v[184:187], v[200:203], v[52:55]
	v_mfma_f32_16x16x32_bf16 v[48:51], v[192:195], v[200:203], v[48:51]
	v_mfma_f32_16x16x32_bf16 v[36:39], v[184:187], v[208:211], v[36:39]
	v_mfma_f32_16x16x32_bf16 v[32:35], v[192:195], v[208:211], v[32:35]
	v_mfma_f32_16x16x32_bf16 v[20:23], v[184:187], v[220:223], v[20:23]
	v_mfma_f32_16x16x32_bf16 v[16:19], v[192:195], v[220:223], v[16:19]
	v_mfma_f32_16x16x32_bf16 v[4:7], v[184:187], v[228:231], v[4:7]
	v_mfma_f32_16x16x32_bf16 v[0:3], v[192:195], v[228:231], v[0:3]
	s_setprio 0
	s_barrier
	v_add_u32_e32 v154, s37, v165
	ds_read_b128 v[128:131], v154
	ds_read_b128 v[132:135], v154 offset:1024
	ds_read_b128 v[170:173], v154 offset:2048
	ds_read_b128 v[176:179], v154 offset:3072
	v_add_u32_e32 v154, s26, v165
	ds_read_b128 v[180:183], v154
	ds_read_b128 v[184:187], v154 offset:1024
	ds_read_b128 v[188:191], v154 offset:2048
	ds_read_b128 v[192:195], v154 offset:3072
	s_add_u32 s48, s64, 0x80000
	s_addc_u32 s49, s65, 0
	s_mov_b32 m0, s21
	v_lshl_add_u64 v[234:235], s[48:49], 0, v[136:137]
	ds_read_b128 v[196:199], v175 offset:32768
	ds_read_b128 v[200:203], v175 offset:33792
	ds_read_b128 v[204:207], v175 offset:34816
	ds_read_b128 v[208:211], v175 offset:35840
	ds_read_b128 v[216:219], v175 offset:36864
	ds_read_b128 v[220:223], v175 offset:37888
	ds_read_b128 v[224:227], v175 offset:38912
	ds_read_b128 v[228:231], v175 offset:39936
	global_load_lds_dwordx4 v[234:235], off
	v_lshl_add_u64 v[234:235], s[48:49], 0, v[140:141]
	s_mov_b32 m0, s22
	s_nop 0
	global_load_lds_dwordx4 v[234:235], off
	s_waitcnt vmcnt(8) lgkmcnt(0)
	s_barrier
	s_setprio 1
	v_mfma_f32_16x16x32_bf16 v[124:127], v[128:131], v[196:199], v[124:127]
	v_mfma_f32_16x16x32_bf16 v[120:123], v[170:173], v[196:199], v[120:123]
	v_mfma_f32_16x16x32_bf16 v[108:111], v[128:131], v[204:207], v[108:111]
	v_mfma_f32_16x16x32_bf16 v[104:107], v[170:173], v[204:207], v[104:107]
	v_mfma_f32_16x16x32_bf16 v[92:95], v[128:131], v[216:219], v[92:95]
	v_mfma_f32_16x16x32_bf16 v[88:91], v[170:173], v[216:219], v[88:91]
	v_mfma_f32_16x16x32_bf16 v[76:79], v[128:131], v[224:227], v[76:79]
	v_mfma_f32_16x16x32_bf16 v[72:75], v[170:173], v[224:227], v[72:75]
	v_mfma_f32_16x16x32_bf16 v[124:127], v[132:135], v[200:203], v[124:127]
	v_mfma_f32_16x16x32_bf16 v[120:123], v[176:179], v[200:203], v[120:123]
	v_mfma_f32_16x16x32_bf16 v[108:111], v[132:135], v[208:211], v[108:111]
	v_mfma_f32_16x16x32_bf16 v[104:107], v[176:179], v[208:211], v[104:107]
	v_mfma_f32_16x16x32_bf16 v[92:95], v[132:135], v[220:223], v[92:95]
	v_mfma_f32_16x16x32_bf16 v[88:91], v[176:179], v[220:223], v[88:91]
	v_mfma_f32_16x16x32_bf16 v[76:79], v[132:135], v[228:231], v[76:79]
	v_mfma_f32_16x16x32_bf16 v[72:75], v[176:179], v[228:231], v[72:75]
	v_mfma_f32_16x16x32_bf16 v[116:119], v[180:183], v[196:199], v[116:119]
	v_mfma_f32_16x16x32_bf16 v[112:115], v[188:191], v[196:199], v[112:115]
	v_mfma_f32_16x16x32_bf16 v[100:103], v[180:183], v[204:207], v[100:103]
	v_mfma_f32_16x16x32_bf16 v[96:99], v[188:191], v[204:207], v[96:99]
	v_mfma_f32_16x16x32_bf16 v[84:87], v[180:183], v[216:219], v[84:87]
	v_mfma_f32_16x16x32_bf16 v[80:83], v[188:191], v[216:219], v[80:83]
	v_mfma_f32_16x16x32_bf16 v[68:71], v[180:183], v[224:227], v[68:71]
	v_mfma_f32_16x16x32_bf16 v[64:67], v[188:191], v[224:227], v[64:67]
	v_mfma_f32_16x16x32_bf16 v[116:119], v[184:187], v[200:203], v[116:119]
	v_mfma_f32_16x16x32_bf16 v[112:115], v[192:195], v[200:203], v[112:115]
	v_mfma_f32_16x16x32_bf16 v[100:103], v[184:187], v[208:211], v[100:103]
	v_mfma_f32_16x16x32_bf16 v[96:99], v[192:195], v[208:211], v[96:99]
	v_mfma_f32_16x16x32_bf16 v[84:87], v[184:187], v[220:223], v[84:87]
	v_mfma_f32_16x16x32_bf16 v[80:83], v[192:195], v[220:223], v[80:83]
	v_mfma_f32_16x16x32_bf16 v[68:71], v[184:187], v[228:231], v[68:71]
	v_mfma_f32_16x16x32_bf16 v[64:67], v[192:195], v[228:231], v[64:67]
	s_setprio 0
	s_barrier
; #define PG8_STAGE(bufoff, gbase, voff) do { _Pragma("unroll") for (int _i = 0; _i < 2; ++_i) \
;         __builtin_amdgcn_global_load_lds((const unsigned*)((const char*)(gbase) + (voff)[_i]), (LAS unsigned*)(lds + (bufoff) + ldsw + _i * 8192), 16, 0, 0); } while (0)
; #define PG8_LDA(dst, b, h) do { _Pragma("unroll") for (int m = 0; m < 4; ++m) _Pragma("unroll") for (int k = 0; k < 2; ++k) dst[m][k] = *(const LAS bf16x8*)(lds + PG8_SA(b, h) + aoff + m * 2048 + k * 1024); } while (0)
; #define PG8_MMA(ai, bj, At, Bt) do { __builtin_amdgcn_s_setprio(1); _Pragma("unroll") for (int m = 0; m < 4; ++m) _Pragma("unroll") for (int n = 0; n < 2; ++n) _Pragma("unroll") for (int k = 0; k < 2; ++k) \
;         acc[ai][bj][m][n] = __builtin_amdgcn_mfma_f32_16x16x32_bf16(Bt[n][k], At[m][k], acc[ai][bj][m][n], 0, 0, 0); __builtin_amdgcn_s_setprio(0); } while (0)
; #define PG8_WAIT_V(n) asm volatile("s_waitcnt vmcnt(" #n ")" ::: "memory")
; #define PG8_WAIT_L(n) asm volatile("s_waitcnt lgkmcnt(" #n ")" ::: "memory")
; #define PG8_BAR __builtin_amdgcn_s_barrier()
; #define PG8_SCHED __builtin_amdgcn_sched_barrier(0)
; template <class Epi, class Sched>
; __device__ __forceinline__ void gemm_phase(LAS unsigned char* lds, const Gemm g, const Sched& S, const Epi& E) {
;     ...
;             PG8_LDA(At, 1, 1); PG8_STAGE(PG8_SB(1, 0), b3, voffB); PG8_STAGE(PG8_SB(1, 1), b3 + hstepB, voffB); PG8_STAGE(PG8_SA(1, 0), a3, voffA);
;             PG8_WAIT_V(8); PG8_WAIT_L(0); PG8_BAR; PG8_MMA(1, 0, At, B0); PG8_MMA(1, 1, At, B1); PG8_BAR; PG8_SCHED;
;         }
;         if (wr == 0) PG8_BAR;
	s_add_i32 s39, s37, s15
	v_lshl_add_u64 v[152:153], v[152:153], 0, s[8:9]
	s_mov_b32 m0, s39
	ds_read_b128 v[196:199], v175 offset:49152
	ds_read_b128 v[200:203], v175 offset:50176
	ds_read_b128 v[204:207], v175 offset:51200
	ds_read_b128 v[208:211], v175 offset:52224
	ds_read_b128 v[216:219], v175 offset:53248
	ds_read_b128 v[220:223], v175 offset:54272
	ds_read_b128 v[224:227], v175 offset:55296
	ds_read_b128 v[228:231], v175 offset:56320
	global_load_lds_dwordx4 v[152:153], off
	s_add_i32 m0, s39, 0x2000
	s_add_u32 s48, s62, 0x80080
	v_lshl_add_u64 v[152:153], v[156:157], 0, s[8:9]
	s_addc_u32 s49, s63, 0
	s_add_i32 s39, s26, s15
	global_load_lds_dwordx4 v[152:153], off
	v_lshl_add_u64 v[152:153], s[48:49], 0, v[138:139]
	s_mov_b32 m0, s39
	s_nop 0
	global_load_lds_dwordx4 v[152:153], off
	v_lshl_add_u64 v[152:153], s[48:49], 0, v[142:143]
	s_add_i32 m0, s39, 0x2000
	s_nop 0
	global_load_lds_dwordx4 v[152:153], off
	v_lshl_add_u64 v[152:153], v[160:161], 0, s[8:9]
	s_mov_b32 m0, s25
	s_nop 0
	global_load_lds_dwordx4 v[152:153], off
	v_lshl_add_u64 v[152:153], v[232:233], 0, s[8:9]
	s_mov_b32 m0, s27
	s_nop 0
	global_load_lds_dwordx4 v[152:153], off
	s_waitcnt vmcnt(8) lgkmcnt(0)
	s_barrier
	s_setprio 1
	v_mfma_f32_16x16x32_bf16 v[60:63], v[128:131], v[196:199], v[60:63]
	v_mfma_f32_16x16x32_bf16 v[56:59], v[170:173], v[196:199], v[56:59]
	v_mfma_f32_16x16x32_bf16 v[44:47], v[128:131], v[204:207], v[44:47]
	v_mfma_f32_16x16x32_bf16 v[40:43], v[170:173], v[204:207], v[40:43]
	v_mfma_f32_16x16x32_bf16 v[28:31], v[128:131], v[216:219], v[28:31]
	v_mfma_f32_16x16x32_bf16 v[24:27], v[170:173], v[216:219], v[24:27]
	v_mfma_f32_16x16x32_bf16 v[12:15], v[128:131], v[224:227], v[12:15]
	v_mfma_f32_16x16x32_bf16 v[8:11], v[170:173], v[224:227], v[8:11]
	v_mfma_f32_16x16x32_bf16 v[60:63], v[132:135], v[200:203], v[60:63]
	v_mfma_f32_16x16x32_bf16 v[56:59], v[176:179], v[200:203], v[56:59]
	v_mfma_f32_16x16x32_bf16 v[44:47], v[132:135], v[208:211], v[44:47]
	v_mfma_f32_16x16x32_bf16 v[40:43], v[176:179], v[208:211], v[40:43]
	v_mfma_f32_16x16x32_bf16 v[28:31], v[132:135], v[220:223], v[28:31]
	v_mfma_f32_16x16x32_bf16 v[24:27], v[176:179], v[220:223], v[24:27]
	v_mfma_f32_16x16x32_bf16 v[12:15], v[132:135], v[228:231], v[12:15]
	v_mfma_f32_16x16x32_bf16 v[8:11], v[176:179], v[228:231], v[8:11]
	v_mfma_f32_16x16x32_bf16 v[52:55], v[180:183], v[196:199], v[52:55]
	v_mfma_f32_16x16x32_bf16 v[48:51], v[188:191], v[196:199], v[48:51]
	v_mfma_f32_16x16x32_bf16 v[36:39], v[180:183], v[204:207], v[36:39]
	v_mfma_f32_16x16x32_bf16 v[32:35], v[188:191], v[204:207], v[32:35]
	v_mfma_f32_16x16x32_bf16 v[20:23], v[180:183], v[216:219], v[20:23]
	v_mfma_f32_16x16x32_bf16 v[16:19], v[188:191], v[216:219], v[16:19]
	v_mfma_f32_16x16x32_bf16 v[4:7], v[180:183], v[224:227], v[4:7]
	v_mfma_f32_16x16x32_bf16 v[0:3], v[188:191], v[224:227], v[0:3]
	v_mfma_f32_16x16x32_bf16 v[52:55], v[184:187], v[200:203], v[52:55]
	v_mfma_f32_16x16x32_bf16 v[48:51], v[192:195], v[200:203], v[48:51]
	v_mfma_f32_16x16x32_bf16 v[36:39], v[184:187], v[208:211], v[36:39]
	v_mfma_f32_16x16x32_bf16 v[32:35], v[192:195], v[208:211], v[32:35]
	v_mfma_f32_16x16x32_bf16 v[20:23], v[184:187], v[220:223], v[20:23]
	v_mfma_f32_16x16x32_bf16 v[16:19], v[192:195], v[220:223], v[16:19]
	v_mfma_f32_16x16x32_bf16 v[4:7], v[184:187], v[228:231], v[4:7]
	v_mfma_f32_16x16x32_bf16 v[0:3], v[192:195], v[228:231], v[0:3]
	s_setprio 0
	s_barrier
	s_add_i32 s35, s35, 2
	s_add_u32 s60, s60, 0x100
	s_addc_u32 s61, s61, 0
	s_add_u32 s31, s31, 0x100
	s_addc_u32 s34, s34, 0
	s_cmp_gt_u32 s35, 29
	s_cbranch_scc0 .LBB0_829
	s_and_b64 vcc, exec, s[10:11]
	s_cbranch_vccz .LBB0_832
	s_barrier

; #define PG8_STAGE(bufoff, gbase, voff) do { _Pragma("unroll") for (int _i = 0; _i < 2; ++_i) \
;         __builtin_amdgcn_global_load_lds((const unsigned*)((const char*)(gbase) + (voff)[_i]), (LAS unsigned*)(lds + (bufoff) + ldsw + _i * 8192), 16, 0, 0); } while (0)
; #define PG8_LDA(dst, b, h) do { _Pragma("unroll") for (int m = 0; m < 4; ++m) _Pragma("unroll") for (int k = 0; k < 2; ++k) dst[m][k] = *(const LAS bf16x8*)(lds + PG8_SA(b, h) + aoff + m * 2048 + k * 1024); } while (0)
; #define PG8_LDB(dst, b, h) do { _Pragma("unroll") for (int n = 0; n < 2; ++n) _Pragma("unroll") for (int k = 0; k < 2; ++k) dst[n][k] = *(const LAS bf16x8*)(lds + PG8_SB(b, h) + boff + n * 2048 + k * 1024); } while (0)
; #define PG8_MMA(ai, bj, At, Bt) do { __builtin_amdgcn_s_setprio(1); _Pragma("unroll") for (int m = 0; m < 4; ++m) _Pragma("unroll") for (int n = 0; n < 2; ++n) _Pragma("unroll") for (int k = 0; k < 2; ++k) \
;         acc[ai][bj][m][n] = __builtin_amdgcn_mfma_f32_16x16x32_bf16(Bt[n][k], At[m][k], acc[ai][bj][m][n], 0, 0, 0); __builtin_amdgcn_s_setprio(0); } while (0)
; #define PG8_WAIT_V(n) asm volatile("s_waitcnt vmcnt(" #n ")" ::: "memory")
; #define PG8_WAIT_L(n) asm volatile("s_waitcnt lgkmcnt(" #n ")" ::: "memory")
; #define PG8_BAR __builtin_amdgcn_s_barrier()
; #define PG8_SCHED __builtin_amdgcn_sched_barrier(0)
; template <class Epi, class Sched>
; __device__ __forceinline__ void gemm_phase(LAS unsigned char* lds, const Gemm g, const Sched& S, const Epi& E) {
;     ...
;             const bool last = (t == nt - 2);
;             const char* a1 = cA + (size_t)(t + 1) * kstep;
;             const char* a2 = last ? nA : cA + (size_t)(t + 2) * kstep; const char* b2 = last ? nB : cB + (size_t)(t + 2) * kstep;
;             const char* a3 = a2 + kstep; const char* b3 = b2 + kstep;
;             PG8_LDB(B0, 0, 0); PG8_LDB(B1, 0, 1); PG8_SCHED; PG8_LDA(At, 0, 0); PG8_STAGE(PG8_SA(1, 1), a1 + hstepA, voffA);
;             PG8_WAIT_V(8); PG8_WAIT_L(0); PG8_BAR; PG8_MMA(0, 0, At, B0); PG8_MMA(0, 1, At, B1); PG8_BAR; PG8_SCHED;
;             PG8_LDA(At, 0, 1); PG8_STAGE(PG8_SB(0, 0), b2, voffB); PG8_STAGE(PG8_SB(0, 1), b2 + hstepB, voffB); PG8_STAGE(PG8_SA(0, 0), a2, voffA);
.LBB0_923:
	ds_read_b128 v[64:67], v209
	ds_read_b128 v[68:71], v209 offset:1024
	ds_read_b128 v[72:75], v209 offset:2048
	ds_read_b128 v[76:79], v209 offset:3072
	ds_read_b128 v[84:87], v210
	ds_read_b128 v[88:91], v210 offset:1024
	ds_read_b128 v[92:95], v210 offset:2048
	ds_read_b128 v[96:99], v210 offset:3072
	s_add_u32 s4, s0, 0xfff80080
	s_addc_u32 s5, s1, -1
	s_cmp_eq_u32 s62, 28
	s_cselect_b32 s7, s12, s5
	s_cselect_b32 s6, s13, s4
	s_cselect_b32 s5, s53, s61
	s_cselect_b32 s4, s55, s60
	v_lshl_add_u64 v[218:219], s[0:1], 0, v[170:171]
	s_add_i32 m0, s15, 0xc000
	ds_read_b128 v[174:177], v211
	ds_read_b128 v[178:181], v211 offset:1024
	ds_read_b128 v[182:185], v211 offset:2048
	ds_read_b128 v[186:189], v211 offset:3072
	ds_read_b128 v[190:193], v211 offset:4096
	ds_read_b128 v[194:197], v211 offset:5120
	ds_read_b128 v[198:201], v211 offset:6144
	ds_read_b128 v[202:205], v211 offset:7168
	global_load_lds_dwordx4 v[218:219], off
	v_lshl_add_u64 v[218:219], s[0:1], 0, v[172:173]
	s_add_i32 m0, s15, 0xe000
	s_nop 0
	global_load_lds_dwordx4 v[218:219], off
	s_waitcnt vmcnt(8) lgkmcnt(0)
	s_barrier
	s_setprio 1
	v_mfma_f32_16x16x32_bf16 v[156:159], v[64:67], v[174:177], v[156:159]
	v_mfma_f32_16x16x32_bf16 v[148:151], v[72:75], v[174:177], v[148:151]
	v_mfma_f32_16x16x32_bf16 v[140:143], v[64:67], v[182:185], v[140:143]
	v_mfma_f32_16x16x32_bf16 v[136:139], v[72:75], v[182:185], v[136:139]
	v_mfma_f32_16x16x32_bf16 v[124:127], v[64:67], v[190:193], v[124:127]
	v_mfma_f32_16x16x32_bf16 v[120:123], v[72:75], v[190:193], v[120:123]
	v_mfma_f32_16x16x32_bf16 v[108:111], v[64:67], v[198:201], v[108:111]
	v_mfma_f32_16x16x32_bf16 v[104:107], v[72:75], v[198:201], v[104:107]
	v_mfma_f32_16x16x32_bf16 v[156:159], v[68:71], v[178:181], v[156:159]
	v_mfma_f32_16x16x32_bf16 v[148:151], v[76:79], v[178:181], v[148:151]
	v_mfma_f32_16x16x32_bf16 v[140:143], v[68:71], v[186:189], v[140:143]
	v_mfma_f32_16x16x32_bf16 v[136:139], v[76:79], v[186:189], v[136:139]
	v_mfma_f32_16x16x32_bf16 v[124:127], v[68:71], v[194:197], v[124:127]
	v_mfma_f32_16x16x32_bf16 v[120:123], v[76:79], v[194:197], v[120:123]
	v_mfma_f32_16x16x32_bf16 v[108:111], v[68:71], v[202:205], v[108:111]
	v_mfma_f32_16x16x32_bf16 v[104:107], v[76:79], v[202:205], v[104:107]
	v_mfma_f32_16x16x32_bf16 v[152:155], v[84:87], v[174:177], v[152:155]
	v_mfma_f32_16x16x32_bf16 v[144:147], v[92:95], v[174:177], v[144:147]
	v_mfma_f32_16x16x32_bf16 v[132:135], v[84:87], v[182:185], v[132:135]
	v_mfma_f32_16x16x32_bf16 v[128:131], v[92:95], v[182:185], v[128:131]
	v_mfma_f32_16x16x32_bf16 v[116:119], v[84:87], v[190:193], v[116:119]
	v_mfma_f32_16x16x32_bf16 v[112:115], v[92:95], v[190:193], v[112:115]
	v_mfma_f32_16x16x32_bf16 v[80:83], v[84:87], v[198:201], v[80:83]
	v_mfma_f32_16x16x32_bf16 v[100:103], v[92:95], v[198:201], v[100:103]
	v_mfma_f32_16x16x32_bf16 v[152:155], v[88:91], v[178:181], v[152:155]
	v_mfma_f32_16x16x32_bf16 v[144:147], v[96:99], v[178:181], v[144:147]
	v_mfma_f32_16x16x32_bf16 v[132:135], v[88:91], v[186:189], v[132:135]
	v_mfma_f32_16x16x32_bf16 v[128:131], v[96:99], v[186:189], v[128:131]
	v_mfma_f32_16x16x32_bf16 v[116:119], v[88:91], v[194:197], v[116:119]
	v_mfma_f32_16x16x32_bf16 v[112:115], v[96:99], v[194:197], v[112:115]
	v_mfma_f32_16x16x32_bf16 v[80:83], v[88:91], v[202:205], v[80:83]
	v_mfma_f32_16x16x32_bf16 v[100:103], v[96:99], v[202:205], v[100:103]
	s_setprio 0
	s_barrier
	s_add_i32 s63, s33, s14
	v_lshl_add_u64 v[218:219], s[4:5], 0, v[162:163]
	s_mov_b32 m0, s63
	ds_read_b128 v[174:177], v211 offset:16384
	ds_read_b128 v[178:181], v211 offset:17408
	ds_read_b128 v[182:185], v211 offset:18432
	ds_read_b128 v[186:189], v211 offset:19456
	ds_read_b128 v[190:193], v211 offset:20480
	ds_read_b128 v[194:197], v211 offset:21504
	ds_read_b128 v[198:201], v211 offset:22528
	ds_read_b128 v[202:205], v211 offset:23552
	global_load_lds_dwordx4 v[218:219], off
	s_add_i32 m0, s63, 0x2000
	s_add_u32 s70, s4, 0x80000
	v_lshl_add_u64 v[220:221], s[4:5], 0, v[166:167]
	s_addc_u32 s71, s5, 0
	s_add_i32 s63, s36, s14
	global_load_lds_dwordx4 v[220:221], off
	v_lshl_add_u64 v[222:223], s[70:71], 0, v[162:163]
	s_mov_b32 m0, s63
	v_lshl_add_u64 v[224:225], s[6:7], 0, v[164:165]
	global_load_lds_dwordx4 v[222:223], off
	v_lshl_add_u64 v[222:223], s[70:71], 0, v[166:167]
	s_add_i32 m0, s63, 0x2000
	s_nop 0
	global_load_lds_dwordx4 v[222:223], off
	v_lshl_add_u64 v[222:223], s[6:7], 0, v[160:161]
	s_mov_b32 m0, s15
	s_nop 0
	global_load_lds_dwordx4 v[222:223], off
	s_mov_b32 m0, s21
	s_nop 0
	global_load_lds_dwordx4 v[224:225], off
	s_waitcnt vmcnt(8) lgkmcnt(0)
	s_barrier
; #define PG8_STAGE(bufoff, gbase, voff) do { _Pragma("unroll") for (int _i = 0; _i < 2; ++_i) \
;         __builtin_amdgcn_global_load_lds((const unsigned*)((const char*)(gbase) + (voff)[_i]), (LAS unsigned*)(lds + (bufoff) + ldsw + _i * 8192), 16, 0, 0); } while (0)
; #define PG8_LDA(dst, b, h) do { _Pragma("unroll") for (int m = 0; m < 4; ++m) _Pragma("unroll") for (int k = 0; k < 2; ++k) dst[m][k] = *(const LAS bf16x8*)(lds + PG8_SA(b, h) + aoff + m * 2048 + k * 1024); } while (0)
; #define PG8_LDB(dst, b, h) do { _Pragma("unroll") for (int n = 0; n < 2; ++n) _Pragma("unroll") for (int k = 0; k < 2; ++k) dst[n][k] = *(const LAS bf16x8*)(lds + PG8_SB(b, h) + boff + n * 2048 + k * 1024); } while (0)
; #define PG8_MMA(ai, bj, At, Bt) do { __builtin_amdgcn_s_setprio(1); _Pragma("unroll") for (int m = 0; m < 4; ++m) _Pragma("unroll") for (int n = 0; n < 2; ++n) _Pragma("unroll") for (int k = 0; k < 2; ++k) \
;         acc[ai][bj][m][n] = __builtin_amdgcn_mfma_f32_16x16x32_bf16(Bt[n][k], At[m][k], acc[ai][bj][m][n], 0, 0, 0); __builtin_amdgcn_s_setprio(0); } while (0)
; #define PG8_WAIT_V(n) asm volatile("s_waitcnt vmcnt(" #n ")" ::: "memory")
; #define PG8_WAIT_L(n) asm volatile("s_waitcnt lgkmcnt(" #n ")" ::: "memory")
; #define PG8_BAR __builtin_amdgcn_s_barrier()
; #define PG8_SCHED __builtin_amdgcn_sched_barrier(0)
; template <class Epi, class Sched>
; __device__ __forceinline__ void gemm_phase(LAS unsigned char* lds, const Gemm g, const Sched& S, const Epi& E) {
;     ...
;             PG8_WAIT_V(8); PG8_WAIT_L(0); PG8_BAR; PG8_MMA(1, 0, At, B0); PG8_MMA(1, 1, At, B1); PG8_BAR; PG8_SCHED;
;             PG8_LDB(B0, 1, 0); PG8_LDB(B1, 1, 1); PG8_SCHED; PG8_LDA(At, 1, 0); PG8_STAGE(PG8_SA(0, 1), a2 + hstepA, voffA);
;             PG8_WAIT_V(8); PG8_WAIT_L(0); PG8_BAR; PG8_MMA(0, 0, At, B0); PG8_MMA(0, 1, At, B1); PG8_BAR; PG8_SCHED;
	s_setprio 1
	v_mfma_f32_16x16x32_bf16 v[60:63], v[64:67], v[174:177], v[60:63]
	v_mfma_f32_16x16x32_bf16 v[56:59], v[72:75], v[174:177], v[56:59]
	v_mfma_f32_16x16x32_bf16 v[44:47], v[64:67], v[182:185], v[44:47]
	v_mfma_f32_16x16x32_bf16 v[40:43], v[72:75], v[182:185], v[40:43]
	v_mfma_f32_16x16x32_bf16 v[28:31], v[64:67], v[190:193], v[28:31]
	v_mfma_f32_16x16x32_bf16 v[24:27], v[72:75], v[190:193], v[24:27]
	v_mfma_f32_16x16x32_bf16 v[12:15], v[64:67], v[198:201], v[12:15]
	v_mfma_f32_16x16x32_bf16 v[8:11], v[72:75], v[198:201], v[8:11]
	v_mfma_f32_16x16x32_bf16 v[60:63], v[68:71], v[178:181], v[60:63]
	v_mfma_f32_16x16x32_bf16 v[56:59], v[76:79], v[178:181], v[56:59]
	v_mfma_f32_16x16x32_bf16 v[44:47], v[68:71], v[186:189], v[44:47]
	v_mfma_f32_16x16x32_bf16 v[40:43], v[76:79], v[186:189], v[40:43]
	v_mfma_f32_16x16x32_bf16 v[28:31], v[68:71], v[194:197], v[28:31]
	v_mfma_f32_16x16x32_bf16 v[24:27], v[76:79], v[194:197], v[24:27]
	v_mfma_f32_16x16x32_bf16 v[12:15], v[68:71], v[202:205], v[12:15]
	v_mfma_f32_16x16x32_bf16 v[8:11], v[76:79], v[202:205], v[8:11]
	v_mfma_f32_16x16x32_bf16 v[52:55], v[84:87], v[174:177], v[52:55]
	v_mfma_f32_16x16x32_bf16 v[48:51], v[92:95], v[174:177], v[48:51]
	v_mfma_f32_16x16x32_bf16 v[36:39], v[84:87], v[182:185], v[36:39]
	v_mfma_f32_16x16x32_bf16 v[32:35], v[92:95], v[182:185], v[32:35]
	v_mfma_f32_16x16x32_bf16 v[20:23], v[84:87], v[190:193], v[20:23]
	v_mfma_f32_16x16x32_bf16 v[16:19], v[92:95], v[190:193], v[16:19]
	v_mfma_f32_16x16x32_bf16 v[0:3], v[84:87], v[198:201], v[0:3]
	v_mfma_f32_16x16x32_bf16 v[4:7], v[92:95], v[198:201], v[4:7]
	v_mfma_f32_16x16x32_bf16 v[52:55], v[88:91], v[178:181], v[52:55]
	v_mfma_f32_16x16x32_bf16 v[48:51], v[96:99], v[178:181], v[48:51]
	v_mfma_f32_16x16x32_bf16 v[36:39], v[88:91], v[186:189], v[36:39]
	v_mfma_f32_16x16x32_bf16 v[32:35], v[96:99], v[186:189], v[32:35]
	v_mfma_f32_16x16x32_bf16 v[20:23], v[88:91], v[194:197], v[20:23]
	v_mfma_f32_16x16x32_bf16 v[16:19], v[96:99], v[194:197], v[16:19]
	v_mfma_f32_16x16x32_bf16 v[0:3], v[88:91], v[202:205], v[0:3]
	v_mfma_f32_16x16x32_bf16 v[4:7], v[96:99], v[202:205], v[4:7]
	s_setprio 0
	s_barrier
	v_add_u32_e32 v76, s37, v208
	v_add_u32_e32 v96, s26, v208
	ds_read_b128 v[64:67], v76
	ds_read_b128 v[68:71], v76 offset:1024
	ds_read_b128 v[72:75], v76 offset:2048
	ds_read_b128 v[76:79], v76 offset:3072
	ds_read_b128 v[84:87], v96
	ds_read_b128 v[88:91], v96 offset:1024
	ds_read_b128 v[92:95], v96 offset:2048
	ds_read_b128 v[96:99], v96 offset:3072
	s_add_u32 s6, s6, 0x80000
	s_addc_u32 s7, s7, 0
	s_mov_b32 m0, s22
	v_lshl_add_u64 v[226:227], s[6:7], 0, v[160:161]
	ds_read_b128 v[174:177], v211 offset:32768
	ds_read_b128 v[178:181], v211 offset:33792
	ds_read_b128 v[182:185], v211 offset:34816
	ds_read_b128 v[186:189], v211 offset:35840
	ds_read_b128 v[190:193], v211 offset:36864
	ds_read_b128 v[194:197], v211 offset:37888
	ds_read_b128 v[198:201], v211 offset:38912
	ds_read_b128 v[202:205], v211 offset:39936
	global_load_lds_dwordx4 v[226:227], off
	v_lshl_add_u64 v[226:227], s[6:7], 0, v[164:165]
	s_mov_b32 m0, s23
	s_nop 0
	global_load_lds_dwordx4 v[226:227], off
	s_waitcnt vmcnt(8) lgkmcnt(0)
	s_barrier
	s_setprio 1
	v_mfma_f32_16x16x32_bf16 v[156:159], v[64:67], v[174:177], v[156:159]
	v_mfma_f32_16x16x32_bf16 v[148:151], v[72:75], v[174:177], v[148:151]
	v_mfma_f32_16x16x32_bf16 v[140:143], v[64:67], v[182:185], v[140:143]
	v_mfma_f32_16x16x32_bf16 v[136:139], v[72:75], v[182:185], v[136:139]
	v_mfma_f32_16x16x32_bf16 v[124:127], v[64:67], v[190:193], v[124:127]
	v_mfma_f32_16x16x32_bf16 v[120:123], v[72:75], v[190:193], v[120:123]
	v_mfma_f32_16x16x32_bf16 v[108:111], v[64:67], v[198:201], v[108:111]
	v_mfma_f32_16x16x32_bf16 v[104:107], v[72:75], v[198:201], v[104:107]
	v_mfma_f32_16x16x32_bf16 v[156:159], v[68:71], v[178:181], v[156:159]
	v_mfma_f32_16x16x32_bf16 v[148:151], v[76:79], v[178:181], v[148:151]
	v_mfma_f32_16x16x32_bf16 v[140:143], v[68:71], v[186:189], v[140:143]
	v_mfma_f32_16x16x32_bf16 v[136:139], v[76:79], v[186:189], v[136:139]
	v_mfma_f32_16x16x32_bf16 v[124:127], v[68:71], v[194:197], v[124:127]
	v_mfma_f32_16x16x32_bf16 v[120:123], v[76:79], v[194:197], v[120:123]
	v_mfma_f32_16x16x32_bf16 v[108:111], v[68:71], v[202:205], v[108:111]
	v_mfma_f32_16x16x32_bf16 v[104:107], v[76:79], v[202:205], v[104:107]
	v_mfma_f32_16x16x32_bf16 v[152:155], v[84:87], v[174:177], v[152:155]
	v_mfma_f32_16x16x32_bf16 v[144:147], v[92:95], v[174:177], v[144:147]
	v_mfma_f32_16x16x32_bf16 v[132:135], v[84:87], v[182:185], v[132:135]
	v_mfma_f32_16x16x32_bf16 v[128:131], v[92:95], v[182:185], v[128:131]
	v_mfma_f32_16x16x32_bf16 v[116:119], v[84:87], v[190:193], v[116:119]
	v_mfma_f32_16x16x32_bf16 v[112:115], v[92:95], v[190:193], v[112:115]
	v_mfma_f32_16x16x32_bf16 v[80:83], v[84:87], v[198:201], v[80:83]
	v_mfma_f32_16x16x32_bf16 v[100:103], v[92:95], v[198:201], v[100:103]
	v_mfma_f32_16x16x32_bf16 v[152:155], v[88:91], v[178:181], v[152:155]
	v_mfma_f32_16x16x32_bf16 v[144:147], v[96:99], v[178:181], v[144:147]
	v_mfma_f32_16x16x32_bf16 v[132:135], v[88:91], v[186:189], v[132:135]
	v_mfma_f32_16x16x32_bf16 v[128:131], v[96:99], v[186:189], v[128:131]
	v_mfma_f32_16x16x32_bf16 v[116:119], v[88:91], v[194:197], v[116:119]
	v_mfma_f32_16x16x32_bf16 v[112:115], v[96:99], v[194:197], v[112:115]
	v_mfma_f32_16x16x32_bf16 v[80:83], v[88:91], v[202:205], v[80:83]
	v_mfma_f32_16x16x32_bf16 v[100:103], v[96:99], v[202:205], v[100:103]
	s_setprio 0
	s_barrier
; #define PG8_STAGE(bufoff, gbase, voff) do { _Pragma("unroll") for (int _i = 0; _i < 2; ++_i) \
;         __builtin_amdgcn_global_load_lds((const unsigned*)((const char*)(gbase) + (voff)[_i]), (LAS unsigned*)(lds + (bufoff) + ldsw + _i * 8192), 16, 0, 0); } while (0)
; #define PG8_LDA(dst, b, h) do { _Pragma("unroll") for (int m = 0; m < 4; ++m) _Pragma("unroll") for (int k = 0; k < 2; ++k) dst[m][k] = *(const LAS bf16x8*)(lds + PG8_SA(b, h) + aoff + m * 2048 + k * 1024); } while (0)
; #define PG8_MMA(ai, bj, At, Bt) do { __builtin_amdgcn_s_setprio(1); _Pragma("unroll") for (int m = 0; m < 4; ++m) _Pragma("unroll") for (int n = 0; n < 2; ++n) _Pragma("unroll") for (int k = 0; k < 2; ++k) \
;         acc[ai][bj][m][n] = __builtin_amdgcn_mfma_f32_16x16x32_bf16(Bt[n][k], At[m][k], acc[ai][bj][m][n], 0, 0, 0); __builtin_amdgcn_s_setprio(0); } while (0)
; #define PG8_WAIT_V(n) asm volatile("s_waitcnt vmcnt(" #n ")" ::: "memory")
; #define PG8_WAIT_L(n) asm volatile("s_waitcnt lgkmcnt(" #n ")" ::: "memory")
; #define PG8_BAR __builtin_amdgcn_s_barrier()
; #define PG8_SCHED __builtin_amdgcn_sched_barrier(0)
; template <class Epi, class Sched>
; __device__ __forceinline__ void gemm_phase(LAS unsigned char* lds, const Gemm g, const Sched& S, const Epi& E) {
;     ...
;             PG8_LDA(At, 1, 1); PG8_STAGE(PG8_SB(1, 0), b3, voffB); PG8_STAGE(PG8_SB(1, 1), b3 + hstepB, voffB); PG8_STAGE(PG8_SA(1, 0), a3, voffA);
;             PG8_WAIT_V(8); PG8_WAIT_L(0); PG8_BAR; PG8_MMA(1, 0, At, B0); PG8_MMA(1, 1, At, B1); PG8_BAR; PG8_SCHED;
;         }
;         if (wr == 0) PG8_BAR;
	s_add_i32 s6, s37, s14
	v_lshl_add_u64 v[218:219], v[218:219], 0, s[48:49]
	s_mov_b32 m0, s6
	ds_read_b128 v[174:177], v211 offset:49152
	ds_read_b128 v[178:181], v211 offset:50176
	ds_read_b128 v[182:185], v211 offset:51200
	ds_read_b128 v[186:189], v211 offset:52224
	ds_read_b128 v[190:193], v211 offset:53248
	ds_read_b128 v[194:197], v211 offset:54272
	ds_read_b128 v[198:201], v211 offset:55296
	ds_read_b128 v[202:205], v211 offset:56320
	global_load_lds_dwordx4 v[218:219], off
	s_add_i32 m0, s6, 0x2000
	s_add_u32 s4, s4, 0x80080
	v_lshl_add_u64 v[218:219], v[220:221], 0, s[48:49]
	s_addc_u32 s5, s5, 0
	s_add_i32 s6, s26, s14
	global_load_lds_dwordx4 v[218:219], off
	v_lshl_add_u64 v[218:219], s[4:5], 0, v[162:163]
	s_mov_b32 m0, s6
	s_nop 0
	global_load_lds_dwordx4 v[218:219], off
	v_lshl_add_u64 v[218:219], s[4:5], 0, v[166:167]
	s_add_i32 m0, s6, 0x2000
	s_nop 0
	global_load_lds_dwordx4 v[218:219], off
	v_lshl_add_u64 v[218:219], v[222:223], 0, s[48:49]
	s_mov_b32 m0, s45
	s_nop 0
	global_load_lds_dwordx4 v[218:219], off
	v_lshl_add_u64 v[218:219], v[224:225], 0, s[48:49]
	s_mov_b32 m0, s64
	s_nop 0
	global_load_lds_dwordx4 v[218:219], off
	s_waitcnt vmcnt(8) lgkmcnt(0)
	s_barrier
	s_setprio 1
	v_mfma_f32_16x16x32_bf16 v[60:63], v[64:67], v[174:177], v[60:63]
	v_mfma_f32_16x16x32_bf16 v[56:59], v[72:75], v[174:177], v[56:59]
	v_mfma_f32_16x16x32_bf16 v[44:47], v[64:67], v[182:185], v[44:47]
	v_mfma_f32_16x16x32_bf16 v[40:43], v[72:75], v[182:185], v[40:43]
	v_mfma_f32_16x16x32_bf16 v[28:31], v[64:67], v[190:193], v[28:31]
	v_mfma_f32_16x16x32_bf16 v[24:27], v[72:75], v[190:193], v[24:27]
	v_mfma_f32_16x16x32_bf16 v[12:15], v[64:67], v[198:201], v[12:15]
	v_mfma_f32_16x16x32_bf16 v[8:11], v[72:75], v[198:201], v[8:11]
	v_mfma_f32_16x16x32_bf16 v[60:63], v[68:71], v[178:181], v[60:63]
	v_mfma_f32_16x16x32_bf16 v[56:59], v[76:79], v[178:181], v[56:59]
	v_mfma_f32_16x16x32_bf16 v[44:47], v[68:71], v[186:189], v[44:47]
	v_mfma_f32_16x16x32_bf16 v[40:43], v[76:79], v[186:189], v[40:43]
	v_mfma_f32_16x16x32_bf16 v[28:31], v[68:71], v[194:197], v[28:31]
	v_mfma_f32_16x16x32_bf16 v[24:27], v[76:79], v[194:197], v[24:27]
	v_mfma_f32_16x16x32_bf16 v[12:15], v[68:71], v[202:205], v[12:15]
	v_mfma_f32_16x16x32_bf16 v[8:11], v[76:79], v[202:205], v[8:11]
	v_mfma_f32_16x16x32_bf16 v[52:55], v[84:87], v[174:177], v[52:55]
	v_mfma_f32_16x16x32_bf16 v[48:51], v[92:95], v[174:177], v[48:51]
	v_mfma_f32_16x16x32_bf16 v[36:39], v[84:87], v[182:185], v[36:39]
	v_mfma_f32_16x16x32_bf16 v[32:35], v[92:95], v[182:185], v[32:35]
	v_mfma_f32_16x16x32_bf16 v[20:23], v[84:87], v[190:193], v[20:23]
	v_mfma_f32_16x16x32_bf16 v[16:19], v[92:95], v[190:193], v[16:19]
	v_mfma_f32_16x16x32_bf16 v[0:3], v[84:87], v[198:201], v[0:3]
	v_mfma_f32_16x16x32_bf16 v[4:7], v[92:95], v[198:201], v[4:7]
	v_mfma_f32_16x16x32_bf16 v[52:55], v[88:91], v[178:181], v[52:55]
	v_mfma_f32_16x16x32_bf16 v[48:51], v[96:99], v[178:181], v[48:51]
	v_mfma_f32_16x16x32_bf16 v[36:39], v[88:91], v[186:189], v[36:39]
	v_mfma_f32_16x16x32_bf16 v[32:35], v[96:99], v[186:189], v[32:35]
	v_mfma_f32_16x16x32_bf16 v[20:23], v[88:91], v[194:197], v[20:23]
	v_mfma_f32_16x16x32_bf16 v[16:19], v[96:99], v[194:197], v[16:19]
	v_mfma_f32_16x16x32_bf16 v[0:3], v[88:91], v[202:205], v[0:3]
	v_mfma_f32_16x16x32_bf16 v[4:7], v[96:99], v[202:205], v[4:7]
	s_setprio 0
	s_barrier
	s_add_i32 s62, s62, 2
	s_add_u32 s0, s0, 0x100
	s_addc_u32 s1, s1, 0
	s_add_u32 s60, s60, 0x100
	s_addc_u32 s61, s61, 0
	s_cmp_gt_u32 s62, 29
	s_cbranch_scc0 .LBB0_923
	s_and_b64 vcc, exec, s[50:51]
	s_cbranch_vccz .LBB0_926
	s_barrier

; #define PG8_STAGE(bufoff, gbase, voff) do { _Pragma("unroll") for (int _i = 0; _i < 2; ++_i) \
;         __builtin_amdgcn_global_load_lds((const unsigned*)((const char*)(gbase) + (voff)[_i]), (LAS unsigned*)(lds + (bufoff) + ldsw + _i * 8192), 16, 0, 0); } while (0)
; #define PG8_LDA(dst, b, h) do { _Pragma("unroll") for (int m = 0; m < 4; ++m) _Pragma("unroll") for (int k = 0; k < 2; ++k) dst[m][k] = *(const LAS bf16x8*)(lds + PG8_SA(b, h) + aoff + m * 2048 + k * 1024); } while (0)
; #define PG8_LDB(dst, b, h) do { _Pragma("unroll") for (int n = 0; n < 2; ++n) _Pragma("unroll") for (int k = 0; k < 2; ++k) dst[n][k] = *(const LAS bf16x8*)(lds + PG8_SB(b, h) + boff + n * 2048 + k * 1024); } while (0)
; #define PG8_MMA(ai, bj, At, Bt) do { __builtin_amdgcn_s_setprio(1); _Pragma("unroll") for (int m = 0; m < 4; ++m) _Pragma("unroll") for (int n = 0; n < 2; ++n) _Pragma("unroll") for (int k = 0; k < 2; ++k) \
;         acc[ai][bj][m][n] = __builtin_amdgcn_mfma_f32_16x16x32_bf16(Bt[n][k], At[m][k], acc[ai][bj][m][n], 0, 0, 0); __builtin_amdgcn_s_setprio(0); } while (0)
; #define PG8_WAIT_V(n) asm volatile("s_waitcnt vmcnt(" #n ")" ::: "memory")
; #define PG8_WAIT_L(n) asm volatile("s_waitcnt lgkmcnt(" #n ")" ::: "memory")
; #define PG8_BAR __builtin_amdgcn_s_barrier()
; #define PG8_SCHED __builtin_amdgcn_sched_barrier(0)
; template <class Epi, class Sched>
; __device__ __forceinline__ void gemm_phase(LAS unsigned char* lds, const Gemm g, const Sched& S, const Epi& E) {
;     ...
;             const bool last = (t == nt - 2);
;             const char* a1 = cA + (size_t)(t + 1) * kstep;
;             const char* a2 = last ? nA : cA + (size_t)(t + 2) * kstep; const char* b2 = last ? nB : cB + (size_t)(t + 2) * kstep;
;             const char* a3 = a2 + kstep; const char* b3 = b2 + kstep;
;             PG8_LDB(B0, 0, 0); PG8_LDB(B1, 0, 1); PG8_SCHED; PG8_LDA(At, 0, 0); PG8_STAGE(PG8_SA(1, 1), a1 + hstepA, voffA);
;             PG8_WAIT_V(8); PG8_WAIT_L(0); PG8_BAR; PG8_MMA(0, 0, At, B0); PG8_MMA(0, 1, At, B1); PG8_BAR; PG8_SCHED;
;             PG8_LDA(At, 0, 1); PG8_STAGE(PG8_SB(0, 0), b2, voffB); PG8_STAGE(PG8_SB(0, 1), b2 + hstepB, voffB); PG8_STAGE(PG8_SA(0, 0), a2, voffA);
.LBB0_1077:
	ds_read_b128 v[128:131], v193
	ds_read_b128 v[132:135], v193 offset:1024
	ds_read_b128 v[148:151], v193 offset:2048
	ds_read_b128 v[152:155], v193 offset:3072
	ds_read_b128 v[156:159], v194
	ds_read_b128 v[160:163], v194 offset:1024
	ds_read_b128 v[164:167], v194 offset:2048
	ds_read_b128 v[168:171], v194 offset:3072
	s_add_u32 s30, s24, 0x100
	s_addc_u32 s31, s25, 0
	s_cmpk_eq_i32 s1, 0x5c
	s_cselect_b32 s39, s23, s31
	s_cselect_b32 s38, s22, s30
	s_cselect_b32 s35, s7, s5
	s_cselect_b32 s34, s6, s4
	v_lshl_add_u64 v[214:215], s[24:25], 0, v[144:145]
	s_add_i32 m0, s28, 0xc000
	ds_read_b128 v[172:175], v195
	ds_read_b128 v[176:179], v195 offset:1024
	ds_read_b128 v[180:183], v195 offset:2048
	ds_read_b128 v[184:187], v195 offset:3072
	ds_read_b128 v[198:201], v195 offset:4096
	ds_read_b128 v[202:205], v195 offset:5120
	ds_read_b128 v[206:209], v195 offset:6144
	ds_read_b128 v[210:213], v195 offset:7168
	global_load_lds_dwordx4 v[214:215], off
	v_lshl_add_u64 v[214:215], s[24:25], 0, v[146:147]
	s_add_i32 m0, s28, 0xe000
	s_nop 0
	global_load_lds_dwordx4 v[214:215], off
	s_waitcnt vmcnt(8) lgkmcnt(0)
	s_barrier
	s_setprio 1
	v_mfma_f32_16x16x32_bf16 v[124:127], v[128:131], v[172:175], v[124:127]
	v_mfma_f32_16x16x32_bf16 v[120:123], v[148:151], v[172:175], v[120:123]
	v_mfma_f32_16x16x32_bf16 v[108:111], v[128:131], v[180:183], v[108:111]
	v_mfma_f32_16x16x32_bf16 v[104:107], v[148:151], v[180:183], v[104:107]
	v_mfma_f32_16x16x32_bf16 v[92:95], v[128:131], v[198:201], v[92:95]
	v_mfma_f32_16x16x32_bf16 v[88:91], v[148:151], v[198:201], v[88:91]
	v_mfma_f32_16x16x32_bf16 v[76:79], v[128:131], v[206:209], v[76:79]
	v_mfma_f32_16x16x32_bf16 v[72:75], v[148:151], v[206:209], v[72:75]
	v_mfma_f32_16x16x32_bf16 v[124:127], v[132:135], v[176:179], v[124:127]
	v_mfma_f32_16x16x32_bf16 v[120:123], v[152:155], v[176:179], v[120:123]
	v_mfma_f32_16x16x32_bf16 v[108:111], v[132:135], v[184:187], v[108:111]
	v_mfma_f32_16x16x32_bf16 v[104:107], v[152:155], v[184:187], v[104:107]
	v_mfma_f32_16x16x32_bf16 v[92:95], v[132:135], v[202:205], v[92:95]
	v_mfma_f32_16x16x32_bf16 v[88:91], v[152:155], v[202:205], v[88:91]
	v_mfma_f32_16x16x32_bf16 v[76:79], v[132:135], v[210:213], v[76:79]
	v_mfma_f32_16x16x32_bf16 v[72:75], v[152:155], v[210:213], v[72:75]
	v_mfma_f32_16x16x32_bf16 v[116:119], v[156:159], v[172:175], v[116:119]
	v_mfma_f32_16x16x32_bf16 v[112:115], v[164:167], v[172:175], v[112:115]
	v_mfma_f32_16x16x32_bf16 v[100:103], v[156:159], v[180:183], v[100:103]
	v_mfma_f32_16x16x32_bf16 v[96:99], v[164:167], v[180:183], v[96:99]
	v_mfma_f32_16x16x32_bf16 v[84:87], v[156:159], v[198:201], v[84:87]
	v_mfma_f32_16x16x32_bf16 v[80:83], v[164:167], v[198:201], v[80:83]
	v_mfma_f32_16x16x32_bf16 v[68:71], v[156:159], v[206:209], v[68:71]
	v_mfma_f32_16x16x32_bf16 v[64:67], v[164:167], v[206:209], v[64:67]
	v_mfma_f32_16x16x32_bf16 v[116:119], v[160:163], v[176:179], v[116:119]
	v_mfma_f32_16x16x32_bf16 v[112:115], v[168:171], v[176:179], v[112:115]
	v_mfma_f32_16x16x32_bf16 v[100:103], v[160:163], v[184:187], v[100:103]
	v_mfma_f32_16x16x32_bf16 v[96:99], v[168:171], v[184:187], v[96:99]
	v_mfma_f32_16x16x32_bf16 v[84:87], v[160:163], v[202:205], v[84:87]
	v_mfma_f32_16x16x32_bf16 v[80:83], v[168:171], v[202:205], v[80:83]
	v_mfma_f32_16x16x32_bf16 v[68:71], v[160:163], v[210:213], v[68:71]
	v_mfma_f32_16x16x32_bf16 v[64:67], v[168:171], v[210:213], v[64:67]
	s_setprio 0
	s_barrier
	s_add_i32 s12, s33, s27
	v_lshl_add_u64 v[214:215], s[34:35], 0, v[138:139]
	s_mov_b32 m0, s12
	ds_read_b128 v[172:175], v195 offset:16384
	ds_read_b128 v[176:179], v195 offset:17408
	ds_read_b128 v[180:183], v195 offset:18432
	ds_read_b128 v[184:187], v195 offset:19456
	ds_read_b128 v[198:201], v195 offset:20480
	ds_read_b128 v[202:205], v195 offset:21504
	ds_read_b128 v[206:209], v195 offset:22528
	ds_read_b128 v[210:213], v195 offset:23552
	global_load_lds_dwordx4 v[214:215], off
	s_add_i32 m0, s12, 0x2000
	s_add_u32 s12, s34, 0x180000
	v_lshl_add_u64 v[216:217], s[34:35], 0, v[142:143]
	s_addc_u32 s13, s35, 0
	s_add_i32 s24, s36, s27
	global_load_lds_dwordx4 v[216:217], off
	v_lshl_add_u64 v[218:219], s[12:13], 0, v[138:139]
	s_mov_b32 m0, s24
	v_lshl_add_u64 v[220:221], s[38:39], 0, v[140:141]
	global_load_lds_dwordx4 v[218:219], off
	v_lshl_add_u64 v[218:219], s[12:13], 0, v[142:143]
	s_add_i32 m0, s24, 0x2000
	s_nop 0
	global_load_lds_dwordx4 v[218:219], off
	v_lshl_add_u64 v[218:219], s[38:39], 0, v[136:137]
	s_mov_b32 m0, s28
	s_nop 0
	global_load_lds_dwordx4 v[218:219], off
	s_mov_b32 m0, s40
	s_nop 0
	global_load_lds_dwordx4 v[220:221], off
	s_waitcnt vmcnt(8) lgkmcnt(0)
	s_barrier
; #define PG8_STAGE(bufoff, gbase, voff) do { _Pragma("unroll") for (int _i = 0; _i < 2; ++_i) \
;         __builtin_amdgcn_global_load_lds((const unsigned*)((const char*)(gbase) + (voff)[_i]), (LAS unsigned*)(lds + (bufoff) + ldsw + _i * 8192), 16, 0, 0); } while (0)
; #define PG8_LDA(dst, b, h) do { _Pragma("unroll") for (int m = 0; m < 4; ++m) _Pragma("unroll") for (int k = 0; k < 2; ++k) dst[m][k] = *(const LAS bf16x8*)(lds + PG8_SA(b, h) + aoff + m * 2048 + k * 1024); } while (0)
; #define PG8_LDB(dst, b, h) do { _Pragma("unroll") for (int n = 0; n < 2; ++n) _Pragma("unroll") for (int k = 0; k < 2; ++k) dst[n][k] = *(const LAS bf16x8*)(lds + PG8_SB(b, h) + boff + n * 2048 + k * 1024); } while (0)
; #define PG8_MMA(ai, bj, At, Bt) do { __builtin_amdgcn_s_setprio(1); _Pragma("unroll") for (int m = 0; m < 4; ++m) _Pragma("unroll") for (int n = 0; n < 2; ++n) _Pragma("unroll") for (int k = 0; k < 2; ++k) \
;         acc[ai][bj][m][n] = __builtin_amdgcn_mfma_f32_16x16x32_bf16(Bt[n][k], At[m][k], acc[ai][bj][m][n], 0, 0, 0); __builtin_amdgcn_s_setprio(0); } while (0)
; #define PG8_WAIT_V(n) asm volatile("s_waitcnt vmcnt(" #n ")" ::: "memory")
; #define PG8_WAIT_L(n) asm volatile("s_waitcnt lgkmcnt(" #n ")" ::: "memory")
; #define PG8_BAR __builtin_amdgcn_s_barrier()
; #define PG8_SCHED __builtin_amdgcn_sched_barrier(0)
; template <class Epi, class Sched>
; __device__ __forceinline__ void gemm_phase(LAS unsigned char* lds, const Gemm g, const Sched& S, const Epi& E) {
;     ...
;             PG8_WAIT_V(8); PG8_WAIT_L(0); PG8_BAR; PG8_MMA(1, 0, At, B0); PG8_MMA(1, 1, At, B1); PG8_BAR; PG8_SCHED;
;             PG8_LDB(B0, 1, 0); PG8_LDB(B1, 1, 1); PG8_SCHED; PG8_LDA(At, 1, 0); PG8_STAGE(PG8_SA(0, 1), a2 + hstepA, voffA);
;             PG8_WAIT_V(8); PG8_WAIT_L(0); PG8_BAR; PG8_MMA(0, 0, At, B0); PG8_MMA(0, 1, At, B1); PG8_BAR; PG8_SCHED;
	s_setprio 1
	v_mfma_f32_16x16x32_bf16 v[60:63], v[128:131], v[172:175], v[60:63]
	v_mfma_f32_16x16x32_bf16 v[56:59], v[148:151], v[172:175], v[56:59]
	v_mfma_f32_16x16x32_bf16 v[44:47], v[128:131], v[180:183], v[44:47]
	v_mfma_f32_16x16x32_bf16 v[40:43], v[148:151], v[180:183], v[40:43]
	v_mfma_f32_16x16x32_bf16 v[28:31], v[128:131], v[198:201], v[28:31]
	v_mfma_f32_16x16x32_bf16 v[24:27], v[148:151], v[198:201], v[24:27]
	v_mfma_f32_16x16x32_bf16 v[12:15], v[128:131], v[206:209], v[12:15]
	v_mfma_f32_16x16x32_bf16 v[8:11], v[148:151], v[206:209], v[8:11]
	v_mfma_f32_16x16x32_bf16 v[60:63], v[132:135], v[176:179], v[60:63]
	v_mfma_f32_16x16x32_bf16 v[56:59], v[152:155], v[176:179], v[56:59]
	v_mfma_f32_16x16x32_bf16 v[44:47], v[132:135], v[184:187], v[44:47]
	v_mfma_f32_16x16x32_bf16 v[40:43], v[152:155], v[184:187], v[40:43]
	v_mfma_f32_16x16x32_bf16 v[28:31], v[132:135], v[202:205], v[28:31]
	v_mfma_f32_16x16x32_bf16 v[24:27], v[152:155], v[202:205], v[24:27]
	v_mfma_f32_16x16x32_bf16 v[12:15], v[132:135], v[210:213], v[12:15]
	v_mfma_f32_16x16x32_bf16 v[8:11], v[152:155], v[210:213], v[8:11]
	v_mfma_f32_16x16x32_bf16 v[52:55], v[156:159], v[172:175], v[52:55]
	v_mfma_f32_16x16x32_bf16 v[48:51], v[164:167], v[172:175], v[48:51]
	v_mfma_f32_16x16x32_bf16 v[36:39], v[156:159], v[180:183], v[36:39]
	v_mfma_f32_16x16x32_bf16 v[32:35], v[164:167], v[180:183], v[32:35]
	v_mfma_f32_16x16x32_bf16 v[20:23], v[156:159], v[198:201], v[20:23]
	v_mfma_f32_16x16x32_bf16 v[16:19], v[164:167], v[198:201], v[16:19]
	v_mfma_f32_16x16x32_bf16 v[4:7], v[156:159], v[206:209], v[4:7]
	v_mfma_f32_16x16x32_bf16 v[0:3], v[164:167], v[206:209], v[0:3]
	v_mfma_f32_16x16x32_bf16 v[52:55], v[160:163], v[176:179], v[52:55]
	v_mfma_f32_16x16x32_bf16 v[48:51], v[168:171], v[176:179], v[48:51]
	v_mfma_f32_16x16x32_bf16 v[36:39], v[160:163], v[184:187], v[36:39]
	v_mfma_f32_16x16x32_bf16 v[32:35], v[168:171], v[184:187], v[32:35]
	v_mfma_f32_16x16x32_bf16 v[20:23], v[160:163], v[202:205], v[20:23]
	v_mfma_f32_16x16x32_bf16 v[16:19], v[168:171], v[202:205], v[16:19]
	v_mfma_f32_16x16x32_bf16 v[4:7], v[160:163], v[210:213], v[4:7]
	v_mfma_f32_16x16x32_bf16 v[0:3], v[168:171], v[210:213], v[0:3]
	s_setprio 0
	s_barrier
	v_add_u32_e32 v152, s37, v190
	v_add_u32_e32 v168, s26, v190
	ds_read_b128 v[128:131], v152
	ds_read_b128 v[132:135], v152 offset:1024
	ds_read_b128 v[148:151], v152 offset:2048
	ds_read_b128 v[152:155], v152 offset:3072
	ds_read_b128 v[156:159], v168
	ds_read_b128 v[160:163], v168 offset:1024
	ds_read_b128 v[164:167], v168 offset:2048
	ds_read_b128 v[168:171], v168 offset:3072
	s_add_u32 s12, s38, 0x180000
	s_addc_u32 s13, s39, 0
	s_mov_b32 m0, s41
	v_lshl_add_u64 v[222:223], s[12:13], 0, v[136:137]
	ds_read_b128 v[172:175], v195 offset:32768
	ds_read_b128 v[176:179], v195 offset:33792
	ds_read_b128 v[180:183], v195 offset:34816
	ds_read_b128 v[184:187], v195 offset:35840
	ds_read_b128 v[198:201], v195 offset:36864
	ds_read_b128 v[202:205], v195 offset:37888
	ds_read_b128 v[206:209], v195 offset:38912
	ds_read_b128 v[210:213], v195 offset:39936
	global_load_lds_dwordx4 v[222:223], off
	v_lshl_add_u64 v[222:223], s[12:13], 0, v[140:141]
	s_mov_b32 m0, s42
	s_nop 0
	global_load_lds_dwordx4 v[222:223], off
	s_waitcnt vmcnt(8) lgkmcnt(0)
	s_barrier
	s_setprio 1
	v_mfma_f32_16x16x32_bf16 v[124:127], v[128:131], v[172:175], v[124:127]
	v_mfma_f32_16x16x32_bf16 v[120:123], v[148:151], v[172:175], v[120:123]
	v_mfma_f32_16x16x32_bf16 v[108:111], v[128:131], v[180:183], v[108:111]
	v_mfma_f32_16x16x32_bf16 v[104:107], v[148:151], v[180:183], v[104:107]
	v_mfma_f32_16x16x32_bf16 v[92:95], v[128:131], v[198:201], v[92:95]
	v_mfma_f32_16x16x32_bf16 v[88:91], v[148:151], v[198:201], v[88:91]
	v_mfma_f32_16x16x32_bf16 v[76:79], v[128:131], v[206:209], v[76:79]
	v_mfma_f32_16x16x32_bf16 v[72:75], v[148:151], v[206:209], v[72:75]
	v_mfma_f32_16x16x32_bf16 v[124:127], v[132:135], v[176:179], v[124:127]
	v_mfma_f32_16x16x32_bf16 v[120:123], v[152:155], v[176:179], v[120:123]
	v_mfma_f32_16x16x32_bf16 v[108:111], v[132:135], v[184:187], v[108:111]
	v_mfma_f32_16x16x32_bf16 v[104:107], v[152:155], v[184:187], v[104:107]
	v_mfma_f32_16x16x32_bf16 v[92:95], v[132:135], v[202:205], v[92:95]
	v_mfma_f32_16x16x32_bf16 v[88:91], v[152:155], v[202:205], v[88:91]
	v_mfma_f32_16x16x32_bf16 v[76:79], v[132:135], v[210:213], v[76:79]
	v_mfma_f32_16x16x32_bf16 v[72:75], v[152:155], v[210:213], v[72:75]
	v_mfma_f32_16x16x32_bf16 v[116:119], v[156:159], v[172:175], v[116:119]
	v_mfma_f32_16x16x32_bf16 v[112:115], v[164:167], v[172:175], v[112:115]
	v_mfma_f32_16x16x32_bf16 v[100:103], v[156:159], v[180:183], v[100:103]
	v_mfma_f32_16x16x32_bf16 v[96:99], v[164:167], v[180:183], v[96:99]
	v_mfma_f32_16x16x32_bf16 v[84:87], v[156:159], v[198:201], v[84:87]
	v_mfma_f32_16x16x32_bf16 v[80:83], v[164:167], v[198:201], v[80:83]
	v_mfma_f32_16x16x32_bf16 v[68:71], v[156:159], v[206:209], v[68:71]
	v_mfma_f32_16x16x32_bf16 v[64:67], v[164:167], v[206:209], v[64:67]
	v_mfma_f32_16x16x32_bf16 v[116:119], v[160:163], v[176:179], v[116:119]
	v_mfma_f32_16x16x32_bf16 v[112:115], v[168:171], v[176:179], v[112:115]
	v_mfma_f32_16x16x32_bf16 v[100:103], v[160:163], v[184:187], v[100:103]
	v_mfma_f32_16x16x32_bf16 v[96:99], v[168:171], v[184:187], v[96:99]
	v_mfma_f32_16x16x32_bf16 v[84:87], v[160:163], v[202:205], v[84:87]
	v_mfma_f32_16x16x32_bf16 v[80:83], v[168:171], v[202:205], v[80:83]
	v_mfma_f32_16x16x32_bf16 v[68:71], v[160:163], v[210:213], v[68:71]
	v_mfma_f32_16x16x32_bf16 v[64:67], v[168:171], v[210:213], v[64:67]
	s_setprio 0
	s_barrier
; #define PG8_STAGE(bufoff, gbase, voff) do { _Pragma("unroll") for (int _i = 0; _i < 2; ++_i) \
;         __builtin_amdgcn_global_load_lds((const unsigned*)((const char*)(gbase) + (voff)[_i]), (LAS unsigned*)(lds + (bufoff) + ldsw + _i * 8192), 16, 0, 0); } while (0)
; #define PG8_LDA(dst, b, h) do { _Pragma("unroll") for (int m = 0; m < 4; ++m) _Pragma("unroll") for (int k = 0; k < 2; ++k) dst[m][k] = *(const LAS bf16x8*)(lds + PG8_SA(b, h) + aoff + m * 2048 + k * 1024); } while (0)
; #define PG8_MMA(ai, bj, At, Bt) do { __builtin_amdgcn_s_setprio(1); _Pragma("unroll") for (int m = 0; m < 4; ++m) _Pragma("unroll") for (int n = 0; n < 2; ++n) _Pragma("unroll") for (int k = 0; k < 2; ++k) \
;         acc[ai][bj][m][n] = __builtin_amdgcn_mfma_f32_16x16x32_bf16(Bt[n][k], At[m][k], acc[ai][bj][m][n], 0, 0, 0); __builtin_amdgcn_s_setprio(0); } while (0)
; #define PG8_WAIT_V(n) asm volatile("s_waitcnt vmcnt(" #n ")" ::: "memory")
; #define PG8_WAIT_L(n) asm volatile("s_waitcnt lgkmcnt(" #n ")" ::: "memory")
; #define PG8_BAR __builtin_amdgcn_s_barrier()
; #define PG8_SCHED __builtin_amdgcn_sched_barrier(0)
; template <class Epi, class Sched>
; __device__ __forceinline__ void gemm_phase(LAS unsigned char* lds, const Gemm g, const Sched& S, const Epi& E) {
;     ...
;             PG8_LDA(At, 1, 1); PG8_STAGE(PG8_SB(1, 0), b3, voffB); PG8_STAGE(PG8_SB(1, 1), b3 + hstepB, voffB); PG8_STAGE(PG8_SA(1, 0), a3, voffA);
;             PG8_WAIT_V(8); PG8_WAIT_L(0); PG8_BAR; PG8_MMA(1, 0, At, B0); PG8_MMA(1, 1, At, B1); PG8_BAR; PG8_SCHED;
;         }
;         if (wr == 0) PG8_BAR;
	s_add_i32 s12, s37, s27
	v_lshl_add_u64 v[214:215], v[214:215], 0, s[16:17]
	s_mov_b32 m0, s12
	ds_read_b128 v[172:175], v195 offset:49152
	ds_read_b128 v[176:179], v195 offset:50176
	ds_read_b128 v[180:183], v195 offset:51200
	ds_read_b128 v[184:187], v195 offset:52224
	ds_read_b128 v[198:201], v195 offset:53248
	ds_read_b128 v[202:205], v195 offset:54272
	ds_read_b128 v[206:209], v195 offset:55296
	ds_read_b128 v[210:213], v195 offset:56320
	global_load_lds_dwordx4 v[214:215], off
	s_add_i32 m0, s12, 0x2000
	s_add_u32 s12, s34, 0x180080
	v_lshl_add_u64 v[214:215], v[216:217], 0, s[16:17]
	s_addc_u32 s13, s35, 0
	s_add_i32 s24, s26, s27
	global_load_lds_dwordx4 v[214:215], off
	v_lshl_add_u64 v[214:215], s[12:13], 0, v[138:139]
	s_mov_b32 m0, s24
	s_nop 0
	global_load_lds_dwordx4 v[214:215], off
	v_lshl_add_u64 v[214:215], s[12:13], 0, v[142:143]
	s_add_i32 m0, s24, 0x2000
	s_nop 0
	global_load_lds_dwordx4 v[214:215], off
	v_lshl_add_u64 v[214:215], v[218:219], 0, s[16:17]
	s_mov_b32 m0, s46
	s_nop 0
	global_load_lds_dwordx4 v[214:215], off
	v_lshl_add_u64 v[214:215], v[220:221], 0, s[16:17]
	s_mov_b32 m0, s47
	s_nop 0
	global_load_lds_dwordx4 v[214:215], off
	s_waitcnt vmcnt(8) lgkmcnt(0)
	s_barrier
	s_setprio 1
	v_mfma_f32_16x16x32_bf16 v[60:63], v[128:131], v[172:175], v[60:63]
	v_mfma_f32_16x16x32_bf16 v[56:59], v[148:151], v[172:175], v[56:59]
	v_mfma_f32_16x16x32_bf16 v[44:47], v[128:131], v[180:183], v[44:47]
	v_mfma_f32_16x16x32_bf16 v[40:43], v[148:151], v[180:183], v[40:43]
	v_mfma_f32_16x16x32_bf16 v[28:31], v[128:131], v[198:201], v[28:31]
	v_mfma_f32_16x16x32_bf16 v[24:27], v[148:151], v[198:201], v[24:27]
	v_mfma_f32_16x16x32_bf16 v[12:15], v[128:131], v[206:209], v[12:15]
	v_mfma_f32_16x16x32_bf16 v[8:11], v[148:151], v[206:209], v[8:11]
	v_mfma_f32_16x16x32_bf16 v[60:63], v[132:135], v[176:179], v[60:63]
	v_mfma_f32_16x16x32_bf16 v[56:59], v[152:155], v[176:179], v[56:59]
	v_mfma_f32_16x16x32_bf16 v[44:47], v[132:135], v[184:187], v[44:47]
	v_mfma_f32_16x16x32_bf16 v[40:43], v[152:155], v[184:187], v[40:43]
	v_mfma_f32_16x16x32_bf16 v[28:31], v[132:135], v[202:205], v[28:31]
	v_mfma_f32_16x16x32_bf16 v[24:27], v[152:155], v[202:205], v[24:27]
	v_mfma_f32_16x16x32_bf16 v[12:15], v[132:135], v[210:213], v[12:15]
	v_mfma_f32_16x16x32_bf16 v[8:11], v[152:155], v[210:213], v[8:11]
	v_mfma_f32_16x16x32_bf16 v[52:55], v[156:159], v[172:175], v[52:55]
	v_mfma_f32_16x16x32_bf16 v[48:51], v[164:167], v[172:175], v[48:51]
	v_mfma_f32_16x16x32_bf16 v[36:39], v[156:159], v[180:183], v[36:39]
	v_mfma_f32_16x16x32_bf16 v[32:35], v[164:167], v[180:183], v[32:35]
	v_mfma_f32_16x16x32_bf16 v[20:23], v[156:159], v[198:201], v[20:23]
	v_mfma_f32_16x16x32_bf16 v[16:19], v[164:167], v[198:201], v[16:19]
	v_mfma_f32_16x16x32_bf16 v[4:7], v[156:159], v[206:209], v[4:7]
	v_mfma_f32_16x16x32_bf16 v[0:3], v[164:167], v[206:209], v[0:3]
	v_mfma_f32_16x16x32_bf16 v[52:55], v[160:163], v[176:179], v[52:55]
	v_mfma_f32_16x16x32_bf16 v[48:51], v[168:171], v[176:179], v[48:51]
	v_mfma_f32_16x16x32_bf16 v[36:39], v[160:163], v[184:187], v[36:39]
	v_mfma_f32_16x16x32_bf16 v[32:35], v[168:171], v[184:187], v[32:35]
	v_mfma_f32_16x16x32_bf16 v[20:23], v[160:163], v[202:205], v[20:23]
	v_mfma_f32_16x16x32_bf16 v[16:19], v[168:171], v[202:205], v[16:19]
	v_mfma_f32_16x16x32_bf16 v[4:7], v[160:163], v[210:213], v[4:7]
	v_mfma_f32_16x16x32_bf16 v[0:3], v[168:171], v[210:213], v[0:3]
	s_setprio 0
	s_barrier
	s_add_i32 s1, s1, 2
	s_add_u32 s4, s4, 0x100
	s_addc_u32 s5, s5, 0
	s_cmpk_gt_u32 s1, 0x5d
	s_mov_b64 s[24:25], s[30:31]
	s_cbranch_scc0 .LBB0_1077
	s_and_b64 vcc, exec, s[18:19]
	s_cbranch_vccz .LBB0_1080
	s_barrier
